# GEMM main loops: loop-head scalar pointer-select block sunk to the next load segment
# baseline (speedup 1.0000x reference)
.LBB0_139:
	v_add_u32_e32 v253, 0x10000, v146
	ds_read_b128 v[140:143], v253
	ds_read_b128 v[150:153], v253 offset:1024
	ds_read_b128 v[154:157], v253 offset:2048
	ds_read_b128 v[158:161], v253 offset:3072
	s_mov_b32 m0, s12
	ds_read_b128 v[162:165], v145
	ds_read_b128 v[166:169], v145 offset:1024
	ds_read_b128 v[170:173], v145 offset:2048
	ds_read_b128 v[174:177], v145 offset:3072
	ds_read_b128 v[178:181], v145 offset:4096
	ds_read_b128 v[182:185], v145 offset:5120
	ds_read_b128 v[186:189], v145 offset:6144
	ds_read_b128 v[190:193], v145 offset:7168
	global_load_lds_dwordx4 v136, s[6:7]
	s_mov_b32 m0, s78
	s_nop 0
	global_load_lds_dwordx4 v138, s[6:7]
	s_waitcnt lgkmcnt(8)
	s_setprio 1
	s_barrier
	s_waitcnt lgkmcnt(0)
	v_mfma_f32_16x16x32_bf16 v[126:129], v[140:143], v[162:165], v[126:129]
	v_mfma_f32_16x16x32_bf16 v[122:125], v[154:157], v[162:165], v[122:125]
	v_mfma_f32_16x16x32_bf16 v[118:121], v[140:143], v[170:173], v[118:121]
	v_mfma_f32_16x16x32_bf16 v[110:113], v[154:157], v[170:173], v[110:113]
	v_mfma_f32_16x16x32_bf16 v[102:105], v[140:143], v[178:181], v[102:105]
	v_mfma_f32_16x16x32_bf16 v[94:97], v[154:157], v[178:181], v[94:97]
	v_mfma_f32_16x16x32_bf16 v[86:89], v[140:143], v[186:189], v[86:89]
	v_mfma_f32_16x16x32_bf16 v[78:81], v[154:157], v[186:189], v[78:81]
	v_mfma_f32_16x16x32_bf16 v[126:129], v[150:153], v[166:169], v[126:129]
	v_mfma_f32_16x16x32_bf16 v[122:125], v[158:161], v[166:169], v[122:125]
	v_mfma_f32_16x16x32_bf16 v[118:121], v[150:153], v[174:177], v[118:121]
	v_mfma_f32_16x16x32_bf16 v[110:113], v[158:161], v[174:177], v[110:113]
	v_mfma_f32_16x16x32_bf16 v[102:105], v[150:153], v[182:185], v[102:105]
	v_mfma_f32_16x16x32_bf16 v[94:97], v[158:161], v[182:185], v[94:97]
	v_mfma_f32_16x16x32_bf16 v[86:89], v[150:153], v[190:193], v[86:89]
	v_mfma_f32_16x16x32_bf16 v[78:81], v[158:161], v[190:193], v[78:81]
	s_barrier
	s_setprio 0
	s_add_u32 s10, s6, 0xfff80080
	s_addc_u32 s11, s7, -1
	s_cmp_eq_u32 s41, 28
	s_cselect_b32 s11, s63, s11
	s_cselect_b32 s10, s62, s10
	s_cselect_b32 s53, s61, s29
	s_cselect_b32 s52, s60, s28
	s_mov_b32 m0, s83
	ds_read_b128 v[206:209], v253 offset:16384
	ds_read_b128 v[210:213], v253 offset:17408
	v_lshl_add_u64 v[222:223], s[52:53], 0, v[194:195]
	ds_read_b128 v[214:217], v253 offset:18432
	ds_read_b128 v[218:221], v253 offset:19456
	global_load_lds_dwordx4 v[222:223], off
	v_lshl_add_u64 v[224:225], s[52:53], 0, v[134:135]
	s_mov_b32 m0, s54
	s_nop 0
	global_load_lds_dwordx4 v[224:225], off
	s_setprio 1
	s_barrier
	s_waitcnt lgkmcnt(0)
	v_mfma_f32_16x16x32_bf16 v[114:117], v[206:209], v[162:165], v[114:117]
	v_mfma_f32_16x16x32_bf16 v[106:109], v[214:217], v[162:165], v[106:109]
	v_mfma_f32_16x16x32_bf16 v[98:101], v[206:209], v[170:173], v[98:101]
	v_mfma_f32_16x16x32_bf16 v[90:93], v[214:217], v[170:173], v[90:93]
	v_mfma_f32_16x16x32_bf16 v[82:85], v[206:209], v[178:181], v[82:85]
	v_mfma_f32_16x16x32_bf16 v[74:77], v[214:217], v[178:181], v[74:77]
	v_mfma_f32_16x16x32_bf16 v[70:73], v[206:209], v[186:189], v[70:73]
	v_mfma_f32_16x16x32_bf16 v[66:69], v[214:217], v[186:189], v[66:69]
	v_mfma_f32_16x16x32_bf16 v[114:117], v[210:213], v[166:169], v[114:117]
	v_mfma_f32_16x16x32_bf16 v[106:109], v[218:221], v[166:169], v[106:109]
	v_mfma_f32_16x16x32_bf16 v[98:101], v[210:213], v[174:177], v[98:101]
	v_mfma_f32_16x16x32_bf16 v[90:93], v[218:221], v[174:177], v[90:93]
	v_mfma_f32_16x16x32_bf16 v[82:85], v[210:213], v[182:185], v[82:85]
	v_mfma_f32_16x16x32_bf16 v[74:77], v[218:221], v[182:185], v[74:77]
	s_mov_b32 m0, s55
	v_mfma_f32_16x16x32_bf16 v[70:73], v[210:213], v[190:193], v[70:73]
	v_lshl_add_u64 v[226:227], s[10:11], 0, v[130:131]
	v_mfma_f32_16x16x32_bf16 v[66:69], v[218:221], v[190:193], v[66:69]
	s_barrier
	s_setprio 0
	ds_read_b128 v[162:165], v145 offset:16384
	ds_read_b128 v[166:169], v145 offset:17408
	ds_read_b128 v[170:173], v145 offset:18432
	ds_read_b128 v[174:177], v145 offset:19456
	ds_read_b128 v[178:181], v145 offset:20480
	ds_read_b128 v[182:185], v145 offset:21504
	ds_read_b128 v[186:189], v145 offset:22528
	ds_read_b128 v[190:193], v145 offset:23552
	global_load_lds_dwordx4 v[226:227], off
	v_lshl_add_u64 v[228:229], s[10:11], 0, v[132:133]
	s_mov_b32 m0, s34
	s_nop 0
	global_load_lds_dwordx4 v[228:229], off
	s_setprio 1
	s_barrier
	s_waitcnt lgkmcnt(0)
	v_mfma_f32_16x16x32_bf16 v[62:65], v[140:143], v[162:165], v[62:65]
	v_mfma_f32_16x16x32_bf16 v[58:61], v[154:157], v[162:165], v[58:61]
	v_mfma_f32_16x16x32_bf16 v[54:57], v[140:143], v[170:173], v[54:57]
	v_mfma_f32_16x16x32_bf16 v[46:49], v[154:157], v[170:173], v[46:49]
	v_mfma_f32_16x16x32_bf16 v[38:41], v[140:143], v[178:181], v[38:41]
	v_mfma_f32_16x16x32_bf16 v[30:33], v[154:157], v[178:181], v[30:33]
	v_mfma_f32_16x16x32_bf16 v[22:25], v[140:143], v[186:189], v[22:25]
	v_mfma_f32_16x16x32_bf16 v[14:17], v[154:157], v[186:189], v[14:17]
	v_mfma_f32_16x16x32_bf16 v[62:65], v[150:153], v[166:169], v[62:65]
	v_mfma_f32_16x16x32_bf16 v[58:61], v[158:161], v[166:169], v[58:61]
	v_mfma_f32_16x16x32_bf16 v[54:57], v[150:153], v[174:177], v[54:57]
	v_mfma_f32_16x16x32_bf16 v[46:49], v[158:161], v[174:177], v[46:49]
	v_mfma_f32_16x16x32_bf16 v[38:41], v[150:153], v[182:185], v[38:41]
	v_mfma_f32_16x16x32_bf16 v[30:33], v[158:161], v[182:185], v[30:33]
	v_mfma_f32_16x16x32_bf16 v[22:25], v[150:153], v[190:193], v[22:25]
	v_mfma_f32_16x16x32_bf16 v[14:17], v[158:161], v[190:193], v[14:17]
	s_barrier
	s_setprio 0
	s_add_u32 s58, s52, 0x80000
	s_addc_u32 s59, s53, 0
	s_mov_b32 m0, s4
	s_nop 0
	global_load_lds_dwordx4 v194, s[58:59]
	s_mov_b32 m0, s5
	s_nop 0
	global_load_lds_dwordx4 v134, s[58:59]
	s_waitcnt vmcnt(6)
	s_setprio 1
	s_barrier
	v_mfma_f32_16x16x32_bf16 v[50:53], v[206:209], v[162:165], v[50:53]
	v_mfma_f32_16x16x32_bf16 v[42:45], v[214:217], v[162:165], v[42:45]
	v_mfma_f32_16x16x32_bf16 v[34:37], v[206:209], v[170:173], v[34:37]
	v_mfma_f32_16x16x32_bf16 v[26:29], v[214:217], v[170:173], v[26:29]
	v_mfma_f32_16x16x32_bf16 v[18:21], v[206:209], v[178:181], v[18:21]
	v_mfma_f32_16x16x32_bf16 v[10:13], v[214:217], v[178:181], v[10:13]
	v_mfma_f32_16x16x32_bf16 v[6:9], v[206:209], v[186:189], v[6:9]
	v_mfma_f32_16x16x32_bf16 v[2:5], v[214:217], v[186:189], v[2:5]
	v_mfma_f32_16x16x32_bf16 v[50:53], v[210:213], v[166:169], v[50:53]
	v_mfma_f32_16x16x32_bf16 v[42:45], v[218:221], v[166:169], v[42:45]
	v_mfma_f32_16x16x32_bf16 v[34:37], v[210:213], v[174:177], v[34:37]
	v_mfma_f32_16x16x32_bf16 v[26:29], v[218:221], v[174:177], v[26:29]
	v_mfma_f32_16x16x32_bf16 v[18:21], v[210:213], v[182:185], v[18:21]
	v_mfma_f32_16x16x32_bf16 v[10:13], v[218:221], v[182:185], v[10:13]
	v_mfma_f32_16x16x32_bf16 v[6:9], v[210:213], v[190:193], v[6:9]
	v_mfma_f32_16x16x32_bf16 v[2:5], v[218:221], v[190:193], v[2:5]
	s_barrier
	s_setprio 0
	ds_read_b128 v[140:143], v253 offset:32768
	ds_read_b128 v[150:153], v253 offset:33792
	ds_read_b128 v[154:157], v253 offset:34816
	ds_read_b128 v[158:161], v253 offset:35840
	s_add_u32 s10, s10, 0x80000
	s_addc_u32 s11, s11, 0
	s_mov_b32 m0, s56
	ds_read_b128 v[162:165], v145 offset:32768
	ds_read_b128 v[166:169], v145 offset:33792
	ds_read_b128 v[170:173], v145 offset:34816
	ds_read_b128 v[174:177], v145 offset:35840
	ds_read_b128 v[178:181], v145 offset:36864
	ds_read_b128 v[182:185], v145 offset:37888
	ds_read_b128 v[186:189], v145 offset:38912
	ds_read_b128 v[190:193], v145 offset:39936
	global_load_lds_dwordx4 v130, s[10:11]
	s_mov_b32 m0, s57
	s_nop 0
	global_load_lds_dwordx4 v132, s[10:11]
	s_waitcnt lgkmcnt(8)
	s_setprio 1
	s_barrier
	s_waitcnt lgkmcnt(0)
	v_mfma_f32_16x16x32_bf16 v[126:129], v[140:143], v[162:165], v[126:129]
	v_mfma_f32_16x16x32_bf16 v[122:125], v[154:157], v[162:165], v[122:125]
	v_mfma_f32_16x16x32_bf16 v[118:121], v[140:143], v[170:173], v[118:121]
	v_mfma_f32_16x16x32_bf16 v[110:113], v[154:157], v[170:173], v[110:113]
	v_mfma_f32_16x16x32_bf16 v[102:105], v[140:143], v[178:181], v[102:105]
	v_mfma_f32_16x16x32_bf16 v[94:97], v[154:157], v[178:181], v[94:97]
	v_mfma_f32_16x16x32_bf16 v[86:89], v[140:143], v[186:189], v[86:89]
	v_mfma_f32_16x16x32_bf16 v[78:81], v[154:157], v[186:189], v[78:81]
	v_mfma_f32_16x16x32_bf16 v[126:129], v[150:153], v[166:169], v[126:129]
	v_mfma_f32_16x16x32_bf16 v[122:125], v[158:161], v[166:169], v[122:125]
	v_mfma_f32_16x16x32_bf16 v[118:121], v[150:153], v[174:177], v[118:121]
	v_mfma_f32_16x16x32_bf16 v[110:113], v[158:161], v[174:177], v[110:113]
	v_mfma_f32_16x16x32_bf16 v[102:105], v[150:153], v[182:185], v[102:105]
	v_mfma_f32_16x16x32_bf16 v[94:97], v[158:161], v[182:185], v[94:97]
	v_mfma_f32_16x16x32_bf16 v[86:89], v[150:153], v[190:193], v[86:89]
	v_mfma_f32_16x16x32_bf16 v[78:81], v[158:161], v[190:193], v[78:81]
	s_barrier
	s_setprio 0
	s_mov_b32 m0, s70
	ds_read_b128 v[206:209], v253 offset:49152
	ds_read_b128 v[210:213], v253 offset:50176
	v_lshl_add_u64 v[222:223], v[222:223], 0, s[76:77]
	ds_read_b128 v[214:217], v253 offset:51200
	ds_read_b128 v[218:221], v253 offset:52224
	global_load_lds_dwordx4 v[222:223], off
	v_lshl_add_u64 v[222:223], v[224:225], 0, s[76:77]
	s_mov_b32 m0, s71
	s_nop 0
	global_load_lds_dwordx4 v[222:223], off
	s_setprio 1
	s_barrier
	s_waitcnt lgkmcnt(0)
	v_mfma_f32_16x16x32_bf16 v[114:117], v[206:209], v[162:165], v[114:117]
	v_mfma_f32_16x16x32_bf16 v[106:109], v[214:217], v[162:165], v[106:109]
	v_mfma_f32_16x16x32_bf16 v[98:101], v[206:209], v[170:173], v[98:101]
	v_mfma_f32_16x16x32_bf16 v[90:93], v[214:217], v[170:173], v[90:93]
	v_mfma_f32_16x16x32_bf16 v[82:85], v[206:209], v[178:181], v[82:85]
	v_mfma_f32_16x16x32_bf16 v[74:77], v[214:217], v[178:181], v[74:77]
	v_mfma_f32_16x16x32_bf16 v[70:73], v[206:209], v[186:189], v[70:73]
	v_mfma_f32_16x16x32_bf16 v[66:69], v[214:217], v[186:189], v[66:69]
	v_mfma_f32_16x16x32_bf16 v[114:117], v[210:213], v[166:169], v[114:117]
	v_mfma_f32_16x16x32_bf16 v[106:109], v[218:221], v[166:169], v[106:109]
	v_mfma_f32_16x16x32_bf16 v[98:101], v[210:213], v[174:177], v[98:101]
	v_mfma_f32_16x16x32_bf16 v[90:93], v[218:221], v[174:177], v[90:93]
	v_mfma_f32_16x16x32_bf16 v[82:85], v[210:213], v[182:185], v[82:85]
	v_mfma_f32_16x16x32_bf16 v[74:77], v[218:221], v[182:185], v[74:77]
	s_mov_b32 m0, s33
	v_mfma_f32_16x16x32_bf16 v[70:73], v[210:213], v[190:193], v[70:73]
	v_lshl_add_u64 v[222:223], v[226:227], 0, s[76:77]
	v_mfma_f32_16x16x32_bf16 v[66:69], v[218:221], v[190:193], v[66:69]
	s_barrier
	s_setprio 0
	ds_read_b128 v[162:165], v145 offset:49152
	ds_read_b128 v[166:169], v145 offset:50176
	ds_read_b128 v[170:173], v145 offset:51200
	ds_read_b128 v[174:177], v145 offset:52224
	ds_read_b128 v[178:181], v145 offset:53248
	ds_read_b128 v[182:185], v145 offset:54272
	ds_read_b128 v[186:189], v145 offset:55296
	ds_read_b128 v[190:193], v145 offset:56320
	global_load_lds_dwordx4 v[222:223], off
	v_lshl_add_u64 v[222:223], v[228:229], 0, s[76:77]
	s_mov_b32 m0, s35
	s_nop 0
	global_load_lds_dwordx4 v[222:223], off
	s_setprio 1
	s_barrier
	s_waitcnt lgkmcnt(0)
	v_mfma_f32_16x16x32_bf16 v[62:65], v[140:143], v[162:165], v[62:65]
	v_mfma_f32_16x16x32_bf16 v[58:61], v[154:157], v[162:165], v[58:61]
	v_mfma_f32_16x16x32_bf16 v[54:57], v[140:143], v[170:173], v[54:57]
	v_mfma_f32_16x16x32_bf16 v[46:49], v[154:157], v[170:173], v[46:49]
	v_mfma_f32_16x16x32_bf16 v[38:41], v[140:143], v[178:181], v[38:41]
	v_mfma_f32_16x16x32_bf16 v[30:33], v[154:157], v[178:181], v[30:33]
	v_mfma_f32_16x16x32_bf16 v[22:25], v[140:143], v[186:189], v[22:25]
	v_mfma_f32_16x16x32_bf16 v[14:17], v[154:157], v[186:189], v[14:17]
	v_mfma_f32_16x16x32_bf16 v[62:65], v[150:153], v[166:169], v[62:65]
	v_mfma_f32_16x16x32_bf16 v[58:61], v[158:161], v[166:169], v[58:61]
	v_mfma_f32_16x16x32_bf16 v[54:57], v[150:153], v[174:177], v[54:57]
	v_mfma_f32_16x16x32_bf16 v[46:49], v[158:161], v[174:177], v[46:49]
	v_mfma_f32_16x16x32_bf16 v[38:41], v[150:153], v[182:185], v[38:41]
	v_mfma_f32_16x16x32_bf16 v[30:33], v[158:161], v[182:185], v[30:33]
	v_mfma_f32_16x16x32_bf16 v[22:25], v[150:153], v[190:193], v[22:25]
	v_mfma_f32_16x16x32_bf16 v[14:17], v[158:161], v[190:193], v[14:17]
	s_barrier
	s_setprio 0
	s_add_u32 s10, s52, 0x80080
	s_addc_u32 s11, s53, 0
	s_mov_b32 m0, s67
	s_nop 0
	global_load_lds_dwordx4 v194, s[10:11]
	s_mov_b32 m0, s17
	s_nop 0
	global_load_lds_dwordx4 v134, s[10:11]
	s_waitcnt vmcnt(6)
	s_setprio 1
	s_barrier
	v_mfma_f32_16x16x32_bf16 v[50:53], v[206:209], v[162:165], v[50:53]
	v_mfma_f32_16x16x32_bf16 v[42:45], v[214:217], v[162:165], v[42:45]
	v_mfma_f32_16x16x32_bf16 v[34:37], v[206:209], v[170:173], v[34:37]
	v_mfma_f32_16x16x32_bf16 v[26:29], v[214:217], v[170:173], v[26:29]
	v_mfma_f32_16x16x32_bf16 v[18:21], v[206:209], v[178:181], v[18:21]
	v_mfma_f32_16x16x32_bf16 v[10:13], v[214:217], v[178:181], v[10:13]
	v_mfma_f32_16x16x32_bf16 v[6:9], v[206:209], v[186:189], v[6:9]
	v_mfma_f32_16x16x32_bf16 v[2:5], v[214:217], v[186:189], v[2:5]
	v_mfma_f32_16x16x32_bf16 v[50:53], v[210:213], v[166:169], v[50:53]
	v_mfma_f32_16x16x32_bf16 v[42:45], v[218:221], v[166:169], v[42:45]
	v_mfma_f32_16x16x32_bf16 v[34:37], v[210:213], v[174:177], v[34:37]
	v_mfma_f32_16x16x32_bf16 v[26:29], v[218:221], v[174:177], v[26:29]
	v_mfma_f32_16x16x32_bf16 v[18:21], v[210:213], v[182:185], v[18:21]
	v_mfma_f32_16x16x32_bf16 v[10:13], v[218:221], v[182:185], v[10:13]
	v_mfma_f32_16x16x32_bf16 v[6:9], v[210:213], v[190:193], v[6:9]
	v_mfma_f32_16x16x32_bf16 v[2:5], v[218:221], v[190:193], v[2:5]
	s_setprio 0
	s_add_i32 s41, s41, 2
	s_add_u32 s6, s6, 0x100
	s_addc_u32 s7, s7, 0
	s_add_u32 s28, s28, 0x100
	s_addc_u32 s29, s29, 0
	s_cmp_gt_u32 s41, 29
	s_barrier
	s_cbranch_scc0 .LBB0_139
	s_cmp_gt_i32 s79, 3
	s_mov_b64 s[6:7], -1
	s_cbranch_scc0 .LBB0_146
	s_lshl_b32 s10, s82, 8
	v_lshl_or_b32 v140, s80, 8, v149
	s_cmp_lg_u32 s79, 4
	v_ashrrev_i32_e32 v141, 31, v140
	s_cbranch_scc0 .LBB0_143
	v_readlane_b32 s6, v252, 55
	v_readlane_b32 s7, v252, 56
	v_add_u32_e32 v150, s10, v147
	s_nop 0
	v_mov_b64_e32 v[142:143], s[6:7]
	s_mov_b32 s6, 0x9000
	v_mad_i64_i32 v[142:143], s[6:7], v150, s6, v[142:143]
	v_lshl_add_u64 v[142:143], v[140:141], 1, v[142:143]
	v_cvt_pk_bf16_f32 v150, v126, v127
	v_cvt_pk_bf16_f32 v151, v128, v129
	v_cvt_pk_bf16_f32 v152, v122, v123
	v_cvt_pk_bf16_f32 v153, v124, v125
	global_store_dwordx4 v[142:143], v[150:153], off
	v_add_co_u32_e32 v154, vcc, s44, v142
	s_nop 0
	v_cvt_pk_bf16_f32 v150, v114, v115
	v_cvt_pk_bf16_f32 v151, v116, v117
	v_cvt_pk_bf16_f32 v152, v106, v107
	v_cvt_pk_bf16_f32 v153, v108, v109
	global_store_dwordx4 v[142:143], v[150:153], off offset:256
	v_addc_co_u32_e32 v155, vcc, 0, v143, vcc
	s_nop 0
	v_cvt_pk_bf16_f32 v150, v118, v119
	v_cvt_pk_bf16_f32 v151, v120, v121
	v_cvt_pk_bf16_f32 v152, v110, v111
	v_cvt_pk_bf16_f32 v153, v112, v113
	global_store_dwordx4 v[154:155], v[150:153], off
	s_mov_b64 s[6:7], 0
	s_nop 0
	v_cvt_pk_bf16_f32 v150, v98, v99
	v_cvt_pk_bf16_f32 v151, v100, v101
	v_cvt_pk_bf16_f32 v152, v90, v91
	v_cvt_pk_bf16_f32 v153, v92, v93
	global_store_dwordx4 v[154:155], v[150:153], off offset:256
	v_add_co_u32_e32 v154, vcc, s45, v142
	s_nop 0
	v_cvt_pk_bf16_f32 v150, v102, v103
	v_cvt_pk_bf16_f32 v151, v104, v105
	v_cvt_pk_bf16_f32 v152, v94, v95
	v_cvt_pk_bf16_f32 v153, v96, v97
	s_nop 0
	v_addc_co_u32_e32 v155, vcc, 0, v143, vcc
	global_store_dwordx4 v[154:155], v[150:153], off
	s_nop 1
	v_cvt_pk_bf16_f32 v150, v82, v83
	v_cvt_pk_bf16_f32 v151, v84, v85
	v_cvt_pk_bf16_f32 v152, v74, v75
	v_cvt_pk_bf16_f32 v153, v76, v77
	global_store_dwordx4 v[154:155], v[150:153], off offset:256
	v_add_co_u32_e32 v154, vcc, s90, v142
	s_nop 0
	v_cvt_pk_bf16_f32 v150, v86, v87
	v_cvt_pk_bf16_f32 v151, v88, v89
	v_cvt_pk_bf16_f32 v152, v78, v79
	v_cvt_pk_bf16_f32 v153, v80, v81
	s_nop 0
	v_addc_co_u32_e32 v155, vcc, 0, v143, vcc
	global_store_dwordx4 v[154:155], v[150:153], off
	s_nop 1
	v_cvt_pk_bf16_f32 v150, v70, v71
	v_cvt_pk_bf16_f32 v151, v72, v73
	v_cvt_pk_bf16_f32 v152, v66, v67
	v_cvt_pk_bf16_f32 v153, v68, v69
	global_store_dwordx4 v[154:155], v[150:153], off offset:256
	v_add_co_u32_e32 v154, vcc, s20, v142
	s_nop 0
	v_cvt_pk_bf16_f32 v150, v62, v63
	v_cvt_pk_bf16_f32 v151, v64, v65
	v_cvt_pk_bf16_f32 v152, v58, v59
	v_cvt_pk_bf16_f32 v153, v60, v61
	s_nop 0
	v_addc_co_u32_e32 v155, vcc, 0, v143, vcc
	global_store_dwordx4 v[154:155], v[150:153], off
	s_nop 1
	v_cvt_pk_bf16_f32 v150, v50, v51
	v_cvt_pk_bf16_f32 v151, v52, v53
	v_cvt_pk_bf16_f32 v152, v42, v43
	v_cvt_pk_bf16_f32 v153, v44, v45
	global_store_dwordx4 v[154:155], v[150:153], off offset:256
	v_add_co_u32_e32 v154, vcc, s21, v142
	s_nop 0
	v_cvt_pk_bf16_f32 v150, v54, v55
	v_cvt_pk_bf16_f32 v151, v56, v57
	v_cvt_pk_bf16_f32 v152, v46, v47
	v_cvt_pk_bf16_f32 v153, v48, v49
	s_nop 0
	v_addc_co_u32_e32 v155, vcc, 0, v143, vcc
	global_store_dwordx4 v[154:155], v[150:153], off
	s_nop 1
	v_cvt_pk_bf16_f32 v150, v34, v35
	v_cvt_pk_bf16_f32 v151, v36, v37
	v_cvt_pk_bf16_f32 v152, v26, v27
	v_cvt_pk_bf16_f32 v153, v28, v29
	global_store_dwordx4 v[154:155], v[150:153], off offset:256
	v_add_co_u32_e32 v154, vcc, s22, v142
	s_nop 0
	v_cvt_pk_bf16_f32 v150, v38, v39
	v_cvt_pk_bf16_f32 v151, v40, v41
	v_cvt_pk_bf16_f32 v152, v30, v31
	v_cvt_pk_bf16_f32 v153, v32, v33
	s_nop 0
	v_addc_co_u32_e32 v155, vcc, 0, v143, vcc
	global_store_dwordx4 v[154:155], v[150:153], off
	v_add_co_u32_e32 v142, vcc, s23, v142
	s_nop 0
	v_cvt_pk_bf16_f32 v150, v18, v19
	v_cvt_pk_bf16_f32 v151, v20, v21
	v_cvt_pk_bf16_f32 v152, v10, v11
	v_cvt_pk_bf16_f32 v153, v12, v13
	global_store_dwordx4 v[154:155], v[150:153], off offset:256
	v_addc_co_u32_e32 v143, vcc, 0, v143, vcc
	s_nop 0
	v_cvt_pk_bf16_f32 v150, v22, v23
	v_cvt_pk_bf16_f32 v151, v24, v25
	v_cvt_pk_bf16_f32 v152, v14, v15
	v_cvt_pk_bf16_f32 v153, v16, v17
	global_store_dwordx4 v[142:143], v[150:153], off
	s_nop 1
	v_cvt_pk_bf16_f32 v150, v6, v7
	v_cvt_pk_bf16_f32 v151, v8, v9
	v_cvt_pk_bf16_f32 v152, v2, v3
	v_cvt_pk_bf16_f32 v153, v4, v5
	global_store_dwordx4 v[142:143], v[150:153], off offset:256

.LBB0_255:
	v_add_u32_e32 v253, 0x10000, v182
	ds_read_b128 v[130:133], v253
	ds_read_b128 v[134:137], v253 offset:1024
	ds_read_b128 v[138:141], v253 offset:2048
	ds_read_b128 v[142:145], v253 offset:3072
	s_add_i32 m0, s5, 0xc000
	ds_read_b128 v[146:149], v181
	ds_read_b128 v[150:153], v181 offset:1024
	ds_read_b128 v[154:157], v181 offset:2048
	ds_read_b128 v[170:173], v181 offset:3072
	ds_read_b128 v[174:177], v181 offset:4096
	ds_read_b128 v[184:187], v181 offset:5120
	ds_read_b128 v[188:191], v181 offset:6144
	ds_read_b128 v[206:209], v181 offset:7168
	global_load_lds_dwordx4 v166, s[6:7]
	s_add_i32 m0, s5, 0xe000
	s_nop 0
	global_load_lds_dwordx4 v168, s[6:7]
	s_waitcnt lgkmcnt(8)
	s_setprio 1
	s_barrier
	s_waitcnt lgkmcnt(0)
	v_mfma_f32_16x16x32_bf16 v[126:129], v[130:133], v[146:149], v[126:129]
	v_mfma_f32_16x16x32_bf16 v[122:125], v[138:141], v[146:149], v[122:125]
	v_mfma_f32_16x16x32_bf16 v[110:113], v[130:133], v[154:157], v[110:113]
	v_mfma_f32_16x16x32_bf16 v[106:109], v[138:141], v[154:157], v[106:109]
	v_mfma_f32_16x16x32_bf16 v[94:97], v[130:133], v[174:177], v[94:97]
	v_mfma_f32_16x16x32_bf16 v[90:93], v[138:141], v[174:177], v[90:93]
	v_mfma_f32_16x16x32_bf16 v[78:81], v[130:133], v[188:191], v[78:81]
	v_mfma_f32_16x16x32_bf16 v[74:77], v[138:141], v[188:191], v[74:77]
	v_mfma_f32_16x16x32_bf16 v[126:129], v[134:137], v[150:153], v[126:129]
	v_mfma_f32_16x16x32_bf16 v[122:125], v[142:145], v[150:153], v[122:125]
	v_mfma_f32_16x16x32_bf16 v[110:113], v[134:137], v[170:173], v[110:113]
	v_mfma_f32_16x16x32_bf16 v[106:109], v[142:145], v[170:173], v[106:109]
	v_mfma_f32_16x16x32_bf16 v[94:97], v[134:137], v[184:187], v[94:97]
	v_mfma_f32_16x16x32_bf16 v[90:93], v[142:145], v[184:187], v[90:93]
	v_mfma_f32_16x16x32_bf16 v[78:81], v[134:137], v[206:209], v[78:81]
	v_mfma_f32_16x16x32_bf16 v[74:77], v[142:145], v[206:209], v[74:77]
	s_barrier
	s_setprio 0
	s_add_u32 s8, s6, 0xfff00080
	s_addc_u32 s9, s7, -1
	s_cmp_eq_u32 s79, 60
	s_cselect_b32 s11, s53, s9
	s_cselect_b32 s10, s52, s8
	s_cselect_b32 s9, s61, s78
	s_cselect_b32 s8, s60, s1
	ds_read_b128 v[210:213], v253 offset:16384
	ds_read_b128 v[214:217], v253 offset:17408
	s_mov_b32 m0, s12
	ds_read_b128 v[218:221], v253 offset:18432
	ds_read_b128 v[222:225], v253 offset:19456
	v_lshl_add_u64 v[178:179], s[8:9], 0, v[162:163]
	global_load_lds_dwordx4 v[178:179], off
	v_lshl_add_u64 v[192:193], s[8:9], 0, v[158:159]
	s_mov_b32 m0, s17
	s_nop 0
	global_load_lds_dwordx4 v[192:193], off
	s_setprio 1
	s_barrier
	s_waitcnt lgkmcnt(0)
	v_mfma_f32_16x16x32_bf16 v[118:121], v[210:213], v[146:149], v[118:121]
	v_mfma_f32_16x16x32_bf16 v[114:117], v[218:221], v[146:149], v[114:117]
	v_mfma_f32_16x16x32_bf16 v[102:105], v[210:213], v[154:157], v[102:105]
	v_mfma_f32_16x16x32_bf16 v[98:101], v[218:221], v[154:157], v[98:101]
	v_mfma_f32_16x16x32_bf16 v[86:89], v[210:213], v[174:177], v[86:89]
	v_mfma_f32_16x16x32_bf16 v[82:85], v[218:221], v[174:177], v[82:85]
	v_mfma_f32_16x16x32_bf16 v[70:73], v[210:213], v[188:191], v[70:73]
	v_mfma_f32_16x16x32_bf16 v[66:69], v[218:221], v[188:191], v[66:69]
	v_mfma_f32_16x16x32_bf16 v[118:121], v[214:217], v[150:153], v[118:121]
	v_mfma_f32_16x16x32_bf16 v[114:117], v[222:225], v[150:153], v[114:117]
	v_mfma_f32_16x16x32_bf16 v[102:105], v[214:217], v[170:173], v[102:105]
	v_mfma_f32_16x16x32_bf16 v[98:101], v[222:225], v[170:173], v[98:101]
	v_mfma_f32_16x16x32_bf16 v[86:89], v[214:217], v[184:187], v[86:89]
	v_mfma_f32_16x16x32_bf16 v[82:85], v[222:225], v[184:187], v[82:85]
	s_mov_b32 m0, s5
	v_mfma_f32_16x16x32_bf16 v[70:73], v[214:217], v[206:209], v[70:73]
	v_lshl_add_u64 v[226:227], s[10:11], 0, v[164:165]
	v_mfma_f32_16x16x32_bf16 v[66:69], v[222:225], v[206:209], v[66:69]
	s_barrier
	s_setprio 0
	ds_read_b128 v[146:149], v181 offset:16384
	ds_read_b128 v[150:153], v181 offset:17408
	ds_read_b128 v[154:157], v181 offset:18432
	ds_read_b128 v[170:173], v181 offset:19456
	ds_read_b128 v[174:177], v181 offset:20480
	ds_read_b128 v[184:187], v181 offset:21504
	ds_read_b128 v[188:191], v181 offset:22528
	ds_read_b128 v[206:209], v181 offset:23552
	global_load_lds_dwordx4 v[226:227], off
	v_lshl_add_u64 v[228:229], s[10:11], 0, v[160:161]
	s_mov_b32 m0, s26
	s_nop 0
	global_load_lds_dwordx4 v[228:229], off
	s_setprio 1
	s_barrier
	s_waitcnt lgkmcnt(0)
	v_mfma_f32_16x16x32_bf16 v[62:65], v[130:133], v[146:149], v[62:65]
	v_mfma_f32_16x16x32_bf16 v[58:61], v[138:141], v[146:149], v[58:61]
	v_mfma_f32_16x16x32_bf16 v[46:49], v[130:133], v[154:157], v[46:49]
	v_mfma_f32_16x16x32_bf16 v[42:45], v[138:141], v[154:157], v[42:45]
	v_mfma_f32_16x16x32_bf16 v[30:33], v[130:133], v[174:177], v[30:33]
	v_mfma_f32_16x16x32_bf16 v[26:29], v[138:141], v[174:177], v[26:29]
	v_mfma_f32_16x16x32_bf16 v[14:17], v[130:133], v[188:191], v[14:17]
	v_mfma_f32_16x16x32_bf16 v[10:13], v[138:141], v[188:191], v[10:13]
	v_mfma_f32_16x16x32_bf16 v[62:65], v[134:137], v[150:153], v[62:65]
	v_mfma_f32_16x16x32_bf16 v[58:61], v[142:145], v[150:153], v[58:61]
	v_mfma_f32_16x16x32_bf16 v[46:49], v[134:137], v[170:173], v[46:49]
	v_mfma_f32_16x16x32_bf16 v[42:45], v[142:145], v[170:173], v[42:45]
	v_mfma_f32_16x16x32_bf16 v[30:33], v[134:137], v[184:187], v[30:33]
	v_mfma_f32_16x16x32_bf16 v[26:29], v[142:145], v[184:187], v[26:29]
	v_mfma_f32_16x16x32_bf16 v[14:17], v[134:137], v[206:209], v[14:17]
	v_mfma_f32_16x16x32_bf16 v[10:13], v[142:145], v[206:209], v[10:13]
	s_barrier
	s_setprio 0
	s_add_u32 s80, s8, 0x100000
	s_addc_u32 s81, s9, 0
	s_mov_b32 m0, s34
	s_nop 0
	global_load_lds_dwordx4 v162, s[80:81]
	s_mov_b32 m0, s35
	s_nop 0
	global_load_lds_dwordx4 v158, s[80:81]
	s_waitcnt vmcnt(6)
	s_setprio 1
	s_barrier
	v_mfma_f32_16x16x32_bf16 v[54:57], v[210:213], v[146:149], v[54:57]
	v_mfma_f32_16x16x32_bf16 v[50:53], v[218:221], v[146:149], v[50:53]
	v_mfma_f32_16x16x32_bf16 v[38:41], v[210:213], v[154:157], v[38:41]
	v_mfma_f32_16x16x32_bf16 v[34:37], v[218:221], v[154:157], v[34:37]
	v_mfma_f32_16x16x32_bf16 v[22:25], v[210:213], v[174:177], v[22:25]
	v_mfma_f32_16x16x32_bf16 v[18:21], v[218:221], v[174:177], v[18:21]
	v_mfma_f32_16x16x32_bf16 v[6:9], v[210:213], v[188:191], v[6:9]
	v_mfma_f32_16x16x32_bf16 v[2:5], v[218:221], v[188:191], v[2:5]
	v_mfma_f32_16x16x32_bf16 v[54:57], v[214:217], v[150:153], v[54:57]
	v_mfma_f32_16x16x32_bf16 v[50:53], v[222:225], v[150:153], v[50:53]
	v_mfma_f32_16x16x32_bf16 v[38:41], v[214:217], v[170:173], v[38:41]
	v_mfma_f32_16x16x32_bf16 v[34:37], v[222:225], v[170:173], v[34:37]
	v_mfma_f32_16x16x32_bf16 v[22:25], v[214:217], v[184:187], v[22:25]
	v_mfma_f32_16x16x32_bf16 v[18:21], v[222:225], v[184:187], v[18:21]
	v_mfma_f32_16x16x32_bf16 v[6:9], v[214:217], v[206:209], v[6:9]
	v_mfma_f32_16x16x32_bf16 v[2:5], v[222:225], v[206:209], v[2:5]
	s_barrier
	s_setprio 0
	ds_read_b128 v[130:133], v253 offset:32768
	ds_read_b128 v[134:137], v253 offset:33792
	ds_read_b128 v[138:141], v253 offset:34816
	ds_read_b128 v[142:145], v253 offset:35840
	s_add_u32 s10, s10, 0x100000
	s_addc_u32 s11, s11, 0
	s_mov_b32 m0, s42
	ds_read_b128 v[146:149], v181 offset:32768
	ds_read_b128 v[150:153], v181 offset:33792
	ds_read_b128 v[154:157], v181 offset:34816
	ds_read_b128 v[170:173], v181 offset:35840
	ds_read_b128 v[174:177], v181 offset:36864
	ds_read_b128 v[184:187], v181 offset:37888
	ds_read_b128 v[188:191], v181 offset:38912
	ds_read_b128 v[206:209], v181 offset:39936
	global_load_lds_dwordx4 v164, s[10:11]
	s_mov_b32 m0, s54
	s_nop 0
	global_load_lds_dwordx4 v160, s[10:11]
	s_waitcnt lgkmcnt(8)
	s_setprio 1
	s_barrier
	s_waitcnt lgkmcnt(0)
	v_mfma_f32_16x16x32_bf16 v[126:129], v[130:133], v[146:149], v[126:129]
	v_mfma_f32_16x16x32_bf16 v[122:125], v[138:141], v[146:149], v[122:125]
	v_mfma_f32_16x16x32_bf16 v[110:113], v[130:133], v[154:157], v[110:113]
	v_mfma_f32_16x16x32_bf16 v[106:109], v[138:141], v[154:157], v[106:109]
	v_mfma_f32_16x16x32_bf16 v[94:97], v[130:133], v[174:177], v[94:97]
	v_mfma_f32_16x16x32_bf16 v[90:93], v[138:141], v[174:177], v[90:93]
	v_mfma_f32_16x16x32_bf16 v[78:81], v[130:133], v[188:191], v[78:81]
	v_mfma_f32_16x16x32_bf16 v[74:77], v[138:141], v[188:191], v[74:77]
	v_mfma_f32_16x16x32_bf16 v[126:129], v[134:137], v[150:153], v[126:129]
	v_mfma_f32_16x16x32_bf16 v[122:125], v[142:145], v[150:153], v[122:125]
	v_mfma_f32_16x16x32_bf16 v[110:113], v[134:137], v[170:173], v[110:113]
	v_mfma_f32_16x16x32_bf16 v[106:109], v[142:145], v[170:173], v[106:109]
	v_mfma_f32_16x16x32_bf16 v[94:97], v[134:137], v[184:187], v[94:97]
	v_mfma_f32_16x16x32_bf16 v[90:93], v[142:145], v[184:187], v[90:93]
	v_mfma_f32_16x16x32_bf16 v[78:81], v[134:137], v[206:209], v[78:81]
	v_mfma_f32_16x16x32_bf16 v[74:77], v[142:145], v[206:209], v[74:77]
	s_barrier
	s_setprio 0
	s_mov_b32 m0, s55
	ds_read_b128 v[210:213], v253 offset:49152
	ds_read_b128 v[214:217], v253 offset:50176
	v_lshl_add_u64 v[178:179], v[178:179], 0, s[76:77]
	ds_read_b128 v[218:221], v253 offset:51200
	ds_read_b128 v[222:225], v253 offset:52224
	global_load_lds_dwordx4 v[178:179], off
	v_lshl_add_u64 v[178:179], v[192:193], 0, s[76:77]
	s_mov_b32 m0, s56
	s_nop 0
	global_load_lds_dwordx4 v[178:179], off
	s_setprio 1
	s_barrier
	s_waitcnt lgkmcnt(0)
	v_mfma_f32_16x16x32_bf16 v[118:121], v[210:213], v[146:149], v[118:121]
	v_mfma_f32_16x16x32_bf16 v[114:117], v[218:221], v[146:149], v[114:117]
	v_mfma_f32_16x16x32_bf16 v[102:105], v[210:213], v[154:157], v[102:105]
	v_mfma_f32_16x16x32_bf16 v[98:101], v[218:221], v[154:157], v[98:101]
	v_mfma_f32_16x16x32_bf16 v[86:89], v[210:213], v[174:177], v[86:89]
	v_mfma_f32_16x16x32_bf16 v[82:85], v[218:221], v[174:177], v[82:85]
	v_mfma_f32_16x16x32_bf16 v[70:73], v[210:213], v[188:191], v[70:73]
	v_mfma_f32_16x16x32_bf16 v[66:69], v[218:221], v[188:191], v[66:69]
	v_mfma_f32_16x16x32_bf16 v[118:121], v[214:217], v[150:153], v[118:121]
	v_mfma_f32_16x16x32_bf16 v[114:117], v[222:225], v[150:153], v[114:117]
	v_mfma_f32_16x16x32_bf16 v[102:105], v[214:217], v[170:173], v[102:105]
	v_mfma_f32_16x16x32_bf16 v[98:101], v[222:225], v[170:173], v[98:101]
	v_mfma_f32_16x16x32_bf16 v[86:89], v[214:217], v[184:187], v[86:89]
	v_mfma_f32_16x16x32_bf16 v[82:85], v[222:225], v[184:187], v[82:85]
	s_mov_b32 m0, s57
	v_mfma_f32_16x16x32_bf16 v[70:73], v[214:217], v[206:209], v[70:73]
	v_lshl_add_u64 v[178:179], v[226:227], 0, s[76:77]
	v_mfma_f32_16x16x32_bf16 v[66:69], v[222:225], v[206:209], v[66:69]
	s_barrier
	s_setprio 0
	ds_read_b128 v[146:149], v181 offset:49152
	ds_read_b128 v[150:153], v181 offset:50176
	ds_read_b128 v[154:157], v181 offset:51200
	ds_read_b128 v[170:173], v181 offset:52224
	ds_read_b128 v[174:177], v181 offset:53248
	ds_read_b128 v[184:187], v181 offset:54272
	ds_read_b128 v[188:191], v181 offset:55296
	ds_read_b128 v[206:209], v181 offset:56320
	global_load_lds_dwordx4 v[178:179], off
	v_lshl_add_u64 v[178:179], v[228:229], 0, s[76:77]
	s_mov_b32 m0, s58
	s_nop 0
	global_load_lds_dwordx4 v[178:179], off
	s_setprio 1
	s_barrier
	s_waitcnt lgkmcnt(0)
	v_mfma_f32_16x16x32_bf16 v[62:65], v[130:133], v[146:149], v[62:65]
	v_mfma_f32_16x16x32_bf16 v[58:61], v[138:141], v[146:149], v[58:61]
	v_mfma_f32_16x16x32_bf16 v[46:49], v[130:133], v[154:157], v[46:49]
	v_mfma_f32_16x16x32_bf16 v[42:45], v[138:141], v[154:157], v[42:45]
	v_mfma_f32_16x16x32_bf16 v[30:33], v[130:133], v[174:177], v[30:33]
	v_mfma_f32_16x16x32_bf16 v[26:29], v[138:141], v[174:177], v[26:29]
	v_mfma_f32_16x16x32_bf16 v[14:17], v[130:133], v[188:191], v[14:17]
	v_mfma_f32_16x16x32_bf16 v[10:13], v[138:141], v[188:191], v[10:13]
	v_mfma_f32_16x16x32_bf16 v[62:65], v[134:137], v[150:153], v[62:65]
	v_mfma_f32_16x16x32_bf16 v[58:61], v[142:145], v[150:153], v[58:61]
	v_mfma_f32_16x16x32_bf16 v[46:49], v[134:137], v[170:173], v[46:49]
	v_mfma_f32_16x16x32_bf16 v[42:45], v[142:145], v[170:173], v[42:45]
	v_mfma_f32_16x16x32_bf16 v[30:33], v[134:137], v[184:187], v[30:33]
	v_mfma_f32_16x16x32_bf16 v[26:29], v[142:145], v[184:187], v[26:29]
	v_mfma_f32_16x16x32_bf16 v[14:17], v[134:137], v[206:209], v[14:17]
	v_mfma_f32_16x16x32_bf16 v[10:13], v[142:145], v[206:209], v[10:13]
	s_barrier
	s_setprio 0
	s_add_u32 s8, s8, 0x100080
	s_addc_u32 s9, s9, 0
	s_mov_b32 m0, s59
	s_nop 0
	global_load_lds_dwordx4 v162, s[8:9]
	s_mov_b32 m0, s67
	s_nop 0
	global_load_lds_dwordx4 v158, s[8:9]
	s_waitcnt vmcnt(6)
	s_setprio 1
	s_barrier
	v_mfma_f32_16x16x32_bf16 v[54:57], v[210:213], v[146:149], v[54:57]
	v_mfma_f32_16x16x32_bf16 v[50:53], v[218:221], v[146:149], v[50:53]
	v_mfma_f32_16x16x32_bf16 v[38:41], v[210:213], v[154:157], v[38:41]
	v_mfma_f32_16x16x32_bf16 v[34:37], v[218:221], v[154:157], v[34:37]
	v_mfma_f32_16x16x32_bf16 v[22:25], v[210:213], v[174:177], v[22:25]
	v_mfma_f32_16x16x32_bf16 v[18:21], v[218:221], v[174:177], v[18:21]
	v_mfma_f32_16x16x32_bf16 v[6:9], v[210:213], v[188:191], v[6:9]
	v_mfma_f32_16x16x32_bf16 v[2:5], v[218:221], v[188:191], v[2:5]
	v_mfma_f32_16x16x32_bf16 v[54:57], v[214:217], v[150:153], v[54:57]
	v_mfma_f32_16x16x32_bf16 v[50:53], v[222:225], v[150:153], v[50:53]
	v_mfma_f32_16x16x32_bf16 v[38:41], v[214:217], v[170:173], v[38:41]
	v_mfma_f32_16x16x32_bf16 v[34:37], v[222:225], v[170:173], v[34:37]
	v_mfma_f32_16x16x32_bf16 v[22:25], v[214:217], v[184:187], v[22:25]
	v_mfma_f32_16x16x32_bf16 v[18:21], v[222:225], v[184:187], v[18:21]
	v_mfma_f32_16x16x32_bf16 v[6:9], v[214:217], v[206:209], v[6:9]
	v_mfma_f32_16x16x32_bf16 v[2:5], v[222:225], v[206:209], v[2:5]
	s_setprio 0
	s_add_i32 s79, s79, 2
	s_add_u32 s6, s6, 0x100
	s_addc_u32 s7, s7, 0
	s_add_u32 s1, s1, 0x100
	s_addc_u32 s78, s78, 0
	s_cmp_gt_u32 s79, 61
	s_barrier
	s_cbranch_scc0 .LBB0_255
	s_lshl_b32 s1, s28, 9
	s_and_b32 s1, s1, 0xfffff800
	s_lshl_b32 s6, s29, 8
	s_add_i32 s1, s1, s6
	v_add_u32_e32 v172, s1, v180
	s_lshl_b32 s1, s28, 8
	s_and_b32 s1, s1, 0x300
	v_or_b32_e32 v132, s1, v183
	v_mov_b64_e32 v[170:171], s[50:51]
	v_mad_i64_i32 v[130:131], s[6:7], v172, s37, v[170:171]
	v_lshlrev_b32_e32 v194, 1, v132
	v_lshl_add_u64 v[130:131], v[130:131], 0, v[194:195]
	v_lshl_add_u64 v[132:133], v[130:131], 0, s[84:85]
	v_add_co_u32_e32 v130, vcc, s16, v130
	v_or_b32_e32 v178, 16, v172
	s_nop 0
	v_addc_co_u32_e32 v131, vcc, 0, v131, vcc
	global_load_dwordx4 v[184:187], v[130:131], off offset:2048
	global_load_dwordx4 v[154:157], v[132:133], off offset:256
	v_mad_i64_i32 v[130:131], s[6:7], v178, s37, v[170:171]
	v_lshl_add_u64 v[130:131], v[130:131], 0, v[194:195]
	v_lshl_add_u64 v[132:133], v[130:131], 0, s[84:85]
	v_add_co_u32_e32 v130, vcc, s16, v130
	v_or_b32_e32 v176, 32, v172
	s_nop 0
	v_addc_co_u32_e32 v131, vcc, 0, v131, vcc
	global_load_dwordx4 v[150:153], v[130:131], off offset:2048
	global_load_dwordx4 v[146:149], v[132:133], off offset:256
	v_mad_i64_i32 v[130:131], s[6:7], v176, s37, v[170:171]
	v_lshl_add_u64 v[130:131], v[130:131], 0, v[194:195]
	v_lshl_add_u64 v[132:133], v[130:131], 0, s[84:85]
	v_add_co_u32_e32 v130, vcc, s16, v130
	v_or_b32_e32 v174, 48, v172
	s_nop 0
	v_addc_co_u32_e32 v131, vcc, 0, v131, vcc
	global_load_dwordx4 v[142:145], v[130:131], off offset:2048
	global_load_dwordx4 v[138:141], v[132:133], off offset:256
	v_mad_i64_i32 v[130:131], s[6:7], v174, s37, v[170:171]
	v_lshl_add_u64 v[130:131], v[130:131], 0, v[194:195]
	v_lshl_add_u64 v[132:133], v[130:131], 0, s[84:85]
	v_add_co_u32_e32 v130, vcc, s16, v130
	v_pk_mul_f32 v[126:127], v[126:127], s[72:73] op_sel_hi:[1,0]
	s_nop 0
	v_addc_co_u32_e32 v131, vcc, 0, v131, vcc
	global_load_dwordx4 v[134:137], v[130:131], off offset:2048
	s_nop 0
	global_load_dwordx4 v[130:133], v[132:133], off offset:256
	v_pk_mul_f32 v[190:191], v[124:125], s[72:73] op_sel_hi:[1,0]
	v_pk_mul_f32 v[128:129], v[128:129], s[72:73] op_sel_hi:[1,0]
	v_pk_mul_f32 v[122:123], v[122:123], s[72:73] op_sel_hi:[1,0]
	v_ashrrev_i32_e32 v173, 31, v172
	v_lshlrev_b64 v[188:189], 11, v[172:173]
	v_pk_mul_f32 v[118:119], v[118:119], s[72:73] op_sel_hi:[1,0]
	v_pk_mul_f32 v[120:121], v[120:121], s[72:73] op_sel_hi:[1,0]
	v_pk_mul_f32 v[110:111], v[110:111], s[72:73] op_sel_hi:[1,0]
	v_pk_mul_f32 v[112:113], v[112:113], s[72:73] op_sel_hi:[1,0]
	v_ashrrev_i32_e32 v179, 31, v178
	v_pk_mul_f32 v[102:103], v[102:103], s[72:73] op_sel_hi:[1,0]
	v_pk_mul_f32 v[104:105], v[104:105], s[72:73] op_sel_hi:[1,0]
	v_pk_mul_f32 v[94:95], v[94:95], s[72:73] op_sel_hi:[1,0]
	v_pk_mul_f32 v[96:97], v[96:97], s[72:73] op_sel_hi:[1,0]
	v_ashrrev_i32_e32 v177, 31, v176
	v_pk_mul_f32 v[86:87], v[86:87], s[72:73] op_sel_hi:[1,0]
	v_pk_mul_f32 v[88:89], v[88:89], s[72:73] op_sel_hi:[1,0]
	v_pk_mul_f32 v[78:79], v[78:79], s[72:73] op_sel_hi:[1,0]
	v_pk_mul_f32 v[80:81], v[80:81], s[72:73] op_sel_hi:[1,0]
	v_ashrrev_i32_e32 v175, 31, v174
	v_pk_mul_f32 v[70:71], v[70:71], s[72:73] op_sel_hi:[1,0]
	v_pk_mul_f32 v[72:73], v[72:73], s[72:73] op_sel_hi:[1,0]
	s_waitcnt vmcnt(0)
	v_lshlrev_b32_e32 v124, 16, v184
	v_and_b32_e32 v125, 0xffff0000, v184
	v_mul_f32_e32 v124, v126, v124
	v_mul_f32_e32 v125, v127, v125
	v_cvt_pk_bf16_f32 v124, v124, v125
	v_lshlrev_b32_e32 v125, 16, v185
	v_and_b32_e32 v126, 0xffff0000, v185
	v_mul_f32_e32 v125, v128, v125
	v_mul_f32_e32 v126, v129, v126
	v_cvt_pk_bf16_f32 v125, v125, v126
	v_lshlrev_b32_e32 v126, 16, v186
	v_mul_f32_e32 v122, v122, v126
	v_and_b32_e32 v126, 0xffff0000, v186
	v_mul_f32_e32 v123, v123, v126
	v_cvt_pk_bf16_f32 v126, v122, v123
	v_lshlrev_b32_e32 v122, 16, v187
	v_and_b32_e32 v123, 0xffff0000, v187
	v_mul_f32_e32 v122, v190, v122
	v_mul_f32_e32 v123, v191, v123
	v_cvt_pk_bf16_f32 v127, v122, v123
	v_lshl_add_u64 v[122:123], s[74:75], 0, v[188:189]
	v_lshl_add_u64 v[122:123], v[122:123], 0, v[194:195]
	global_store_dwordx4 v[122:123], v[124:127], off
	s_nop 1
	v_pk_mul_f32 v[124:125], v[116:117], s[72:73] op_sel_hi:[1,0]
	v_pk_mul_f32 v[116:117], v[114:115], s[72:73] op_sel_hi:[1,0]
	v_lshlrev_b32_e32 v114, 16, v154
	v_and_b32_e32 v115, 0xffff0000, v154
	v_mul_f32_e32 v114, v118, v114
	v_mul_f32_e32 v115, v119, v115
	v_cvt_pk_bf16_f32 v114, v114, v115
	v_lshlrev_b32_e32 v115, 16, v155
	v_and_b32_e32 v118, 0xffff0000, v155
	v_mul_f32_e32 v115, v120, v115
	v_mul_f32_e32 v118, v121, v118
	v_cvt_pk_bf16_f32 v115, v115, v118
	v_lshlrev_b32_e32 v118, 16, v156
	v_mul_f32_e32 v116, v116, v118
	v_and_b32_e32 v118, 0xffff0000, v156
	v_mul_f32_e32 v117, v117, v118
	v_cvt_pk_bf16_f32 v116, v116, v117
	v_lshlrev_b32_e32 v117, 16, v157
	v_mul_f32_e32 v117, v124, v117
	v_and_b32_e32 v118, 0xffff0000, v157
	v_mul_f32_e32 v118, v125, v118
	v_cvt_pk_bf16_f32 v117, v117, v118
	global_store_dwordx4 v[122:123], v[114:117], off offset:256
	s_nop 1
	v_pk_mul_f32 v[116:117], v[108:109], s[72:73] op_sel_hi:[1,0]
	v_pk_mul_f32 v[108:109], v[106:107], s[72:73] op_sel_hi:[1,0]
	v_lshlrev_b32_e32 v106, 16, v150
	v_and_b32_e32 v107, 0xffff0000, v150
	v_mul_f32_e32 v106, v110, v106
	v_mul_f32_e32 v107, v111, v107
	v_cvt_pk_bf16_f32 v106, v106, v107
	v_lshlrev_b32_e32 v107, 16, v151
	v_and_b32_e32 v110, 0xffff0000, v151
	v_mul_f32_e32 v107, v112, v107
	v_mul_f32_e32 v110, v113, v110
	v_cvt_pk_bf16_f32 v107, v107, v110
	v_lshlrev_b32_e32 v110, 16, v152
	v_mul_f32_e32 v108, v108, v110
	v_and_b32_e32 v110, 0xffff0000, v152
	v_mul_f32_e32 v109, v109, v110
	v_cvt_pk_bf16_f32 v108, v108, v109
	v_lshlrev_b32_e32 v109, 16, v153
	v_and_b32_e32 v110, 0xffff0000, v153
	v_lshlrev_b64 v[114:115], 11, v[178:179]
	v_mul_f32_e32 v109, v116, v109
	v_mul_f32_e32 v110, v117, v110
	v_cvt_pk_bf16_f32 v109, v109, v110
	v_lshl_add_u64 v[110:111], s[74:75], 0, v[114:115]
	v_lshl_add_u64 v[110:111], v[110:111], 0, v[194:195]
	global_store_dwordx4 v[110:111], v[106:109], off
	s_nop 1
	v_pk_mul_f32 v[106:107], v[100:101], s[72:73] op_sel_hi:[1,0]
	v_pk_mul_f32 v[100:101], v[98:99], s[72:73] op_sel_hi:[1,0]
	v_lshlrev_b32_e32 v98, 16, v146
	v_and_b32_e32 v99, 0xffff0000, v146
	v_mul_f32_e32 v98, v102, v98
	v_mul_f32_e32 v99, v103, v99
	v_cvt_pk_bf16_f32 v98, v98, v99
	v_lshlrev_b32_e32 v99, 16, v147
	v_and_b32_e32 v102, 0xffff0000, v147
	v_mul_f32_e32 v99, v104, v99
	v_mul_f32_e32 v102, v105, v102
	v_cvt_pk_bf16_f32 v99, v99, v102
	v_lshlrev_b32_e32 v102, 16, v148
	v_mul_f32_e32 v100, v100, v102
	v_and_b32_e32 v102, 0xffff0000, v148
	v_mul_f32_e32 v101, v101, v102
	v_cvt_pk_bf16_f32 v100, v100, v101
	v_lshlrev_b32_e32 v101, 16, v149
	v_mul_f32_e32 v101, v106, v101
	v_and_b32_e32 v102, 0xffff0000, v149
	v_mul_f32_e32 v102, v107, v102
	v_cvt_pk_bf16_f32 v101, v101, v102
	global_store_dwordx4 v[110:111], v[98:101], off offset:256
	s_nop 1
	v_pk_mul_f32 v[100:101], v[92:93], s[72:73] op_sel_hi:[1,0]
	v_pk_mul_f32 v[92:93], v[90:91], s[72:73] op_sel_hi:[1,0]
	v_lshlrev_b32_e32 v90, 16, v142
	v_and_b32_e32 v91, 0xffff0000, v142
	v_mul_f32_e32 v90, v94, v90
	v_mul_f32_e32 v91, v95, v91
	v_cvt_pk_bf16_f32 v90, v90, v91
	v_lshlrev_b32_e32 v91, 16, v143
	v_and_b32_e32 v94, 0xffff0000, v143
	v_mul_f32_e32 v91, v96, v91
	v_mul_f32_e32 v94, v97, v94
	v_cvt_pk_bf16_f32 v91, v91, v94
	v_lshlrev_b32_e32 v94, 16, v144
	v_mul_f32_e32 v92, v92, v94
	v_and_b32_e32 v94, 0xffff0000, v144
	v_mul_f32_e32 v93, v93, v94
	v_cvt_pk_bf16_f32 v92, v92, v93
	v_lshlrev_b32_e32 v93, 16, v145
	v_and_b32_e32 v94, 0xffff0000, v145
	v_lshlrev_b64 v[98:99], 11, v[176:177]
	v_mul_f32_e32 v93, v100, v93
	v_mul_f32_e32 v94, v101, v94
	v_cvt_pk_bf16_f32 v93, v93, v94
	v_lshl_add_u64 v[94:95], s[74:75], 0, v[98:99]
	v_lshl_add_u64 v[94:95], v[94:95], 0, v[194:195]
	global_store_dwordx4 v[94:95], v[90:93], off
	s_nop 1
	v_pk_mul_f32 v[90:91], v[84:85], s[72:73] op_sel_hi:[1,0]
	v_pk_mul_f32 v[84:85], v[82:83], s[72:73] op_sel_hi:[1,0]
	v_lshlrev_b32_e32 v82, 16, v138
	v_and_b32_e32 v83, 0xffff0000, v138
	v_mul_f32_e32 v82, v86, v82
	v_mul_f32_e32 v83, v87, v83
	v_cvt_pk_bf16_f32 v82, v82, v83
	v_lshlrev_b32_e32 v83, 16, v139
	v_and_b32_e32 v86, 0xffff0000, v139
	v_mul_f32_e32 v83, v88, v83
	v_mul_f32_e32 v86, v89, v86
	v_cvt_pk_bf16_f32 v83, v83, v86
	v_lshlrev_b32_e32 v86, 16, v140
	v_mul_f32_e32 v84, v84, v86
	v_and_b32_e32 v86, 0xffff0000, v140
	v_mul_f32_e32 v85, v85, v86
	v_cvt_pk_bf16_f32 v84, v84, v85
	v_lshlrev_b32_e32 v85, 16, v141
	v_mul_f32_e32 v85, v90, v85
	v_and_b32_e32 v86, 0xffff0000, v141
	v_mul_f32_e32 v86, v91, v86
	v_cvt_pk_bf16_f32 v85, v85, v86
	global_store_dwordx4 v[94:95], v[82:85], off offset:256
	s_nop 1
	v_pk_mul_f32 v[84:85], v[76:77], s[72:73] op_sel_hi:[1,0]
	v_pk_mul_f32 v[76:77], v[74:75], s[72:73] op_sel_hi:[1,0]
	v_lshlrev_b32_e32 v74, 16, v134
	v_and_b32_e32 v75, 0xffff0000, v134
	v_mul_f32_e32 v74, v78, v74
	v_mul_f32_e32 v75, v79, v75
	v_cvt_pk_bf16_f32 v74, v74, v75
	v_lshlrev_b32_e32 v75, 16, v135
	v_and_b32_e32 v78, 0xffff0000, v135
	v_mul_f32_e32 v75, v80, v75
	v_mul_f32_e32 v78, v81, v78
	v_cvt_pk_bf16_f32 v75, v75, v78
	v_lshlrev_b32_e32 v78, 16, v136
	v_mul_f32_e32 v76, v76, v78
	v_and_b32_e32 v78, 0xffff0000, v136
	v_mul_f32_e32 v77, v77, v78
	v_cvt_pk_bf16_f32 v76, v76, v77
	v_lshlrev_b32_e32 v77, 16, v137
	v_and_b32_e32 v78, 0xffff0000, v137
	v_lshlrev_b64 v[82:83], 11, v[174:175]
	v_mul_f32_e32 v77, v84, v77
	v_mul_f32_e32 v78, v85, v78
	v_cvt_pk_bf16_f32 v77, v77, v78
	v_lshl_add_u64 v[78:79], s[74:75], 0, v[82:83]
	v_lshl_add_u64 v[78:79], v[78:79], 0, v[194:195]
	global_store_dwordx4 v[78:79], v[74:77], off
	s_nop 1
	v_pk_mul_f32 v[74:75], v[68:69], s[72:73] op_sel_hi:[1,0]
	v_pk_mul_f32 v[68:69], v[66:67], s[72:73] op_sel_hi:[1,0]
	v_lshlrev_b32_e32 v66, 16, v130
	v_and_b32_e32 v67, 0xffff0000, v130
	v_mul_f32_e32 v66, v70, v66
	v_mul_f32_e32 v67, v71, v67
	v_cvt_pk_bf16_f32 v66, v66, v67
	v_lshlrev_b32_e32 v67, 16, v131
	v_and_b32_e32 v70, 0xffff0000, v131
	v_mul_f32_e32 v67, v72, v67
	v_mul_f32_e32 v70, v73, v70
	v_cvt_pk_bf16_f32 v67, v67, v70
	v_lshlrev_b32_e32 v70, 16, v132
	v_mul_f32_e32 v68, v68, v70
	v_and_b32_e32 v70, 0xffff0000, v132
	v_mul_f32_e32 v69, v69, v70
	v_cvt_pk_bf16_f32 v68, v68, v69
	v_lshlrev_b32_e32 v69, 16, v133
	v_mul_f32_e32 v69, v74, v69
	v_and_b32_e32 v70, 0xffff0000, v133
	v_mul_f32_e32 v70, v75, v70
	v_cvt_pk_bf16_f32 v69, v69, v70
	global_store_dwordx4 v[78:79], v[66:69], off offset:256
	v_add_u32_e32 v78, 0x80, v172
	s_nop 0
	v_mad_i64_i32 v[66:67], s[6:7], v78, s37, v[170:171]
	v_lshl_add_u64 v[66:67], v[66:67], 0, v[194:195]
	v_add_co_u32_e32 v68, vcc, s16, v66
	v_add_u32_e32 v86, 0x90, v172
	s_nop 0
	v_addc_co_u32_e32 v69, vcc, 0, v67, vcc
	global_load_dwordx4 v[70:73], v[68:69], off offset:2048
	v_lshl_add_u64 v[66:67], v[66:67], 0, s[84:85]
	global_load_dwordx4 v[74:77], v[66:67], off offset:256
	v_pk_mul_f32 v[96:97], v[56:57], s[72:73] op_sel_hi:[1,0]
	v_mad_i64_i32 v[56:57], s[6:7], v86, s37, v[170:171]
	v_lshl_add_u64 v[56:57], v[56:57], 0, v[194:195]
	v_pk_mul_f32 v[94:95], v[58:59], s[72:73] op_sel_hi:[1,0]
	v_add_co_u32_e32 v58, vcc, s16, v56
	v_pk_mul_f32 v[92:93], v[60:61], s[72:73] op_sel_hi:[1,0]
	s_nop 0
	v_addc_co_u32_e32 v59, vcc, 0, v57, vcc
	global_load_dwordx4 v[58:61], v[58:59], off offset:2048
	v_add_u32_e32 v68, 0xa0, v172
	v_pk_mul_f32 v[102:103], v[50:51], s[72:73] op_sel_hi:[1,0]
	v_mad_i64_i32 v[50:51], s[6:7], v68, s37, v[170:171]
	v_add_u32_e32 v66, 0xb0, v172
	v_lshl_add_u64 v[50:51], v[50:51], 0, v[194:195]
	v_pk_mul_f32 v[100:101], v[52:53], s[72:73] op_sel_hi:[1,0]
	v_mad_i64_i32 v[52:53], s[6:7], v66, s37, v[170:171]
	v_lshl_add_u64 v[82:83], v[50:51], 0, s[84:85]
	v_add_co_u32_e32 v50, vcc, s16, v50
	v_lshl_add_u64 v[52:53], v[52:53], 0, v[194:195]
	s_nop 0
	v_addc_co_u32_e32 v51, vcc, 0, v51, vcc
	v_ashrrev_i32_e32 v79, 31, v78
	v_lshl_add_u64 v[104:105], v[52:53], 0, s[84:85]
	v_add_co_u32_e32 v52, vcc, s16, v52
	v_pk_mul_f32 v[98:99], v[54:55], s[72:73] op_sel_hi:[1,0]
	v_lshlrev_b64 v[54:55], 11, v[78:79]
	v_lshl_add_u64 v[56:57], v[56:57], 0, s[84:85]
	v_addc_co_u32_e32 v53, vcc, 0, v53, vcc
	v_pk_mul_f32 v[88:89], v[64:65], s[72:73] op_sel_hi:[1,0]
	v_pk_mul_f32 v[90:91], v[62:63], s[72:73] op_sel_hi:[1,0]
	v_lshl_add_u64 v[106:107], s[74:75], 0, v[54:55]
	global_load_dwordx4 v[62:65], v[56:57], off offset:256
	global_load_dwordx4 v[78:81], v[50:51], off offset:2048
	s_nop 0
	global_load_dwordx4 v[82:85], v[82:83], off offset:256
	s_nop 0
	global_load_dwordx4 v[54:57], v[52:53], off offset:2048
	s_nop 0
	global_load_dwordx4 v[50:53], v[104:105], off offset:256
	v_lshl_add_u64 v[104:105], v[106:107], 0, v[194:195]
	v_pk_mul_f32 v[46:47], v[46:47], s[72:73] op_sel_hi:[1,0]
	v_pk_mul_f32 v[48:49], v[48:49], s[72:73] op_sel_hi:[1,0]
	v_ashrrev_i32_e32 v87, 31, v86
	v_pk_mul_f32 v[38:39], v[38:39], s[72:73] op_sel_hi:[1,0]
	v_pk_mul_f32 v[40:41], v[40:41], s[72:73] op_sel_hi:[1,0]
	v_pk_mul_f32 v[30:31], v[30:31], s[72:73] op_sel_hi:[1,0]
	v_pk_mul_f32 v[32:33], v[32:33], s[72:73] op_sel_hi:[1,0]
	v_ashrrev_i32_e32 v69, 31, v68
	v_pk_mul_f32 v[22:23], v[22:23], s[72:73] op_sel_hi:[1,0]
	v_pk_mul_f32 v[24:25], v[24:25], s[72:73] op_sel_hi:[1,0]
	v_pk_mul_f32 v[14:15], v[14:15], s[72:73] op_sel_hi:[1,0]
	v_pk_mul_f32 v[16:17], v[16:17], s[72:73] op_sel_hi:[1,0]
	v_ashrrev_i32_e32 v67, 31, v66
	v_pk_mul_f32 v[6:7], v[6:7], s[72:73] op_sel_hi:[1,0]
	v_pk_mul_f32 v[8:9], v[8:9], s[72:73] op_sel_hi:[1,0]
	s_waitcnt vmcnt(0)
	v_lshlrev_b32_e32 v106, 16, v70
	v_and_b32_e32 v70, 0xffff0000, v70
	v_lshlrev_b32_e32 v107, 16, v71
	v_and_b32_e32 v71, 0xffff0000, v71
	v_lshlrev_b32_e32 v108, 16, v72
	v_and_b32_e32 v72, 0xffff0000, v72
	v_lshlrev_b32_e32 v109, 16, v73
	v_and_b32_e32 v73, 0xffff0000, v73
	v_mul_f32_e32 v70, v91, v70
	v_mul_f32_e32 v71, v89, v71
	v_mul_f32_e32 v72, v95, v72
	v_mul_f32_e32 v73, v93, v73
	v_mul_f32_e32 v90, v90, v106
	v_mul_f32_e32 v88, v88, v107
	v_mul_f32_e32 v89, v94, v108
	v_mul_f32_e32 v91, v92, v109
	v_cvt_pk_bf16_f32 v70, v90, v70
	v_cvt_pk_bf16_f32 v71, v88, v71
	v_cvt_pk_bf16_f32 v72, v89, v72
	v_cvt_pk_bf16_f32 v73, v91, v73
	v_lshlrev_b32_e32 v111, 16, v75
	v_and_b32_e32 v75, 0xffff0000, v75
	global_store_dwordx4 v[104:105], v[70:73], off
	v_lshlrev_b32_e32 v110, 16, v74
	v_and_b32_e32 v74, 0xffff0000, v74
	v_lshlrev_b32_e32 v72, 16, v76
	v_and_b32_e32 v73, 0xffff0000, v76
	v_mul_f32_e32 v71, v97, v75
	v_mul_f32_e32 v72, v102, v72
	v_mul_f32_e32 v73, v103, v73
	v_mul_f32_e32 v92, v98, v110
	v_mul_f32_e32 v74, v99, v74
	v_mul_f32_e32 v93, v96, v111
	v_cvt_pk_bf16_f32 v70, v92, v74
	v_cvt_pk_bf16_f32 v71, v93, v71
	v_cvt_pk_bf16_f32 v72, v72, v73
	v_lshlrev_b32_e32 v73, 16, v77
	v_mul_f32_e32 v73, v100, v73
	v_and_b32_e32 v74, 0xffff0000, v77
	v_mul_f32_e32 v74, v101, v74
	v_cvt_pk_bf16_f32 v73, v73, v74
	global_store_dwordx4 v[104:105], v[70:73], off offset:256
	s_nop 1
	v_pk_mul_f32 v[72:73], v[44:45], s[72:73] op_sel_hi:[1,0]
	v_pk_mul_f32 v[44:45], v[42:43], s[72:73] op_sel_hi:[1,0]
	v_lshlrev_b32_e32 v42, 16, v58
	v_and_b32_e32 v43, 0xffff0000, v58
	v_mul_f32_e32 v42, v46, v42
	v_mul_f32_e32 v43, v47, v43
	v_cvt_pk_bf16_f32 v42, v42, v43
	v_lshlrev_b32_e32 v43, 16, v59
	v_and_b32_e32 v46, 0xffff0000, v59
	v_mul_f32_e32 v43, v48, v43
	v_mul_f32_e32 v46, v49, v46
	v_cvt_pk_bf16_f32 v43, v43, v46
	v_lshlrev_b32_e32 v46, 16, v60
	v_mul_f32_e32 v44, v44, v46
	v_and_b32_e32 v46, 0xffff0000, v60
	v_mul_f32_e32 v45, v45, v46
	v_cvt_pk_bf16_f32 v44, v44, v45
	v_lshlrev_b32_e32 v45, 16, v61
	v_and_b32_e32 v46, 0xffff0000, v61
	v_lshlrev_b64 v[70:71], 11, v[86:87]
	v_mul_f32_e32 v45, v72, v45
	v_mul_f32_e32 v46, v73, v46
	v_cvt_pk_bf16_f32 v45, v45, v46
	v_lshl_add_u64 v[46:47], s[74:75], 0, v[70:71]
	v_lshl_add_u64 v[46:47], v[46:47], 0, v[194:195]
	global_store_dwordx4 v[46:47], v[42:45], off
	s_nop 1
	v_pk_mul_f32 v[42:43], v[36:37], s[72:73] op_sel_hi:[1,0]
	v_pk_mul_f32 v[36:37], v[34:35], s[72:73] op_sel_hi:[1,0]
	v_lshlrev_b32_e32 v34, 16, v62
	v_and_b32_e32 v35, 0xffff0000, v62
	v_mul_f32_e32 v34, v38, v34
	v_mul_f32_e32 v35, v39, v35
	v_cvt_pk_bf16_f32 v34, v34, v35
	v_lshlrev_b32_e32 v35, 16, v63
	v_and_b32_e32 v38, 0xffff0000, v63
	v_mul_f32_e32 v35, v40, v35
	v_mul_f32_e32 v38, v41, v38
	v_cvt_pk_bf16_f32 v35, v35, v38
	v_lshlrev_b32_e32 v38, 16, v64
	v_mul_f32_e32 v36, v36, v38
	v_and_b32_e32 v38, 0xffff0000, v64
	v_mul_f32_e32 v37, v37, v38
	v_cvt_pk_bf16_f32 v36, v36, v37
	v_lshlrev_b32_e32 v37, 16, v65
	v_mul_f32_e32 v37, v42, v37
	v_and_b32_e32 v38, 0xffff0000, v65
	v_mul_f32_e32 v38, v43, v38
	v_cvt_pk_bf16_f32 v37, v37, v38
	global_store_dwordx4 v[46:47], v[34:37], off offset:256
	s_nop 1
	v_pk_mul_f32 v[36:37], v[28:29], s[72:73] op_sel_hi:[1,0]
	v_pk_mul_f32 v[28:29], v[26:27], s[72:73] op_sel_hi:[1,0]
	v_lshlrev_b32_e32 v26, 16, v78
	v_and_b32_e32 v27, 0xffff0000, v78
	v_mul_f32_e32 v26, v30, v26
	v_mul_f32_e32 v27, v31, v27
	v_cvt_pk_bf16_f32 v26, v26, v27
	v_lshlrev_b32_e32 v27, 16, v79
	v_and_b32_e32 v30, 0xffff0000, v79
	v_mul_f32_e32 v27, v32, v27
	v_mul_f32_e32 v30, v33, v30
	v_cvt_pk_bf16_f32 v27, v27, v30
	v_lshlrev_b32_e32 v30, 16, v80
	v_mul_f32_e32 v28, v28, v30
	v_and_b32_e32 v30, 0xffff0000, v80
	v_mul_f32_e32 v29, v29, v30
	v_cvt_pk_bf16_f32 v28, v28, v29
	v_lshlrev_b32_e32 v29, 16, v81
	v_and_b32_e32 v30, 0xffff0000, v81
	v_lshlrev_b64 v[34:35], 11, v[68:69]
	v_mul_f32_e32 v29, v36, v29
	v_mul_f32_e32 v30, v37, v30
	v_cvt_pk_bf16_f32 v29, v29, v30
	v_lshl_add_u64 v[30:31], s[74:75], 0, v[34:35]
	v_lshl_add_u64 v[30:31], v[30:31], 0, v[194:195]
	global_store_dwordx4 v[30:31], v[26:29], off
	s_nop 1
	v_pk_mul_f32 v[26:27], v[20:21], s[72:73] op_sel_hi:[1,0]
	v_pk_mul_f32 v[20:21], v[18:19], s[72:73] op_sel_hi:[1,0]
	v_lshlrev_b32_e32 v18, 16, v82
	v_and_b32_e32 v19, 0xffff0000, v82
	v_mul_f32_e32 v18, v22, v18
	v_mul_f32_e32 v19, v23, v19
	v_cvt_pk_bf16_f32 v18, v18, v19
	v_lshlrev_b32_e32 v19, 16, v83
	v_and_b32_e32 v22, 0xffff0000, v83
	v_mul_f32_e32 v19, v24, v19
	v_mul_f32_e32 v22, v25, v22
	v_cvt_pk_bf16_f32 v19, v19, v22
	v_lshlrev_b32_e32 v22, 16, v84
	v_mul_f32_e32 v20, v20, v22
	v_and_b32_e32 v22, 0xffff0000, v84
	v_mul_f32_e32 v21, v21, v22
	v_cvt_pk_bf16_f32 v20, v20, v21
	v_lshlrev_b32_e32 v21, 16, v85
	v_mul_f32_e32 v21, v26, v21
	v_and_b32_e32 v22, 0xffff0000, v85
	v_mul_f32_e32 v22, v27, v22
	v_cvt_pk_bf16_f32 v21, v21, v22
	global_store_dwordx4 v[30:31], v[18:21], off offset:256
	s_nop 1
	v_pk_mul_f32 v[20:21], v[12:13], s[72:73] op_sel_hi:[1,0]
	v_pk_mul_f32 v[12:13], v[10:11], s[72:73] op_sel_hi:[1,0]
	v_lshlrev_b32_e32 v10, 16, v54
	v_and_b32_e32 v11, 0xffff0000, v54
	v_mul_f32_e32 v10, v14, v10
	v_mul_f32_e32 v11, v15, v11
	v_cvt_pk_bf16_f32 v10, v10, v11
	v_lshlrev_b32_e32 v11, 16, v55
	v_and_b32_e32 v14, 0xffff0000, v55
	v_mul_f32_e32 v11, v16, v11
	v_mul_f32_e32 v14, v17, v14
	v_cvt_pk_bf16_f32 v11, v11, v14
	v_lshlrev_b32_e32 v14, 16, v56
	v_mul_f32_e32 v12, v12, v14
	v_and_b32_e32 v14, 0xffff0000, v56
	v_mul_f32_e32 v13, v13, v14
	v_cvt_pk_bf16_f32 v12, v12, v13
	v_lshlrev_b32_e32 v13, 16, v57
	v_and_b32_e32 v14, 0xffff0000, v57
	v_lshlrev_b64 v[18:19], 11, v[66:67]
	v_mul_f32_e32 v13, v20, v13
	v_mul_f32_e32 v14, v21, v14
	v_cvt_pk_bf16_f32 v13, v13, v14
	v_lshl_add_u64 v[14:15], s[74:75], 0, v[18:19]
	v_lshl_add_u64 v[14:15], v[14:15], 0, v[194:195]
	global_store_dwordx4 v[14:15], v[10:13], off
	s_nop 1
	v_pk_mul_f32 v[10:11], v[4:5], s[72:73] op_sel_hi:[1,0]
	v_pk_mul_f32 v[4:5], v[2:3], s[72:73] op_sel_hi:[1,0]
	v_lshlrev_b32_e32 v2, 16, v50
	v_and_b32_e32 v3, 0xffff0000, v50
	v_mul_f32_e32 v2, v6, v2
	v_mul_f32_e32 v3, v7, v3
	v_cvt_pk_bf16_f32 v2, v2, v3
	v_lshlrev_b32_e32 v3, 16, v51
	v_and_b32_e32 v6, 0xffff0000, v51
	v_mul_f32_e32 v3, v8, v3
	v_mul_f32_e32 v6, v9, v6
	v_cvt_pk_bf16_f32 v3, v3, v6
	v_lshlrev_b32_e32 v6, 16, v52
	v_mul_f32_e32 v4, v4, v6
	v_and_b32_e32 v6, 0xffff0000, v52
	v_mul_f32_e32 v5, v5, v6
	v_cvt_pk_bf16_f32 v4, v4, v5
	v_lshlrev_b32_e32 v5, 16, v53
	v_mul_f32_e32 v5, v10, v5
	v_and_b32_e32 v6, 0xffff0000, v53
	v_mul_f32_e32 v6, v11, v6
	v_cvt_pk_bf16_f32 v5, v5, v6
	global_store_dwordx4 v[14:15], v[2:5], off offset:256
	s_and_b64 vcc, exec, s[62:63]
	s_mov_b32 s29, s71
	s_mov_b32 s28, s0
	s_mov_b64 s[8:9], s[60:61]
	s_mov_b64 s[6:7], s[52:53]
	s_cbranch_vccz .LBB0_252
	s_waitcnt vmcnt(0)
	v_readlane_b32 s28, v250, 12
	s_cmpk_gt_u32 s4, 0xff
	v_readlane_b32 s29, v250, 13
	s_mov_b32 s70, 0x800000
	s_cbranch_scc1 .LBB0_259
	s_barrier

.LBB0_368:
	v_add_u32_e32 v253, 0x10000, v201
	ds_read_b128 v[130:133], v253
	ds_read_b128 v[134:137], v253 offset:1024
	ds_read_b128 v[138:141], v253 offset:2048
	ds_read_b128 v[142:145], v253 offset:3072
	s_add_i32 m0, s34, 0xc000
	ds_read_b128 v[146:149], v199
	ds_read_b128 v[150:153], v199 offset:1024
	ds_read_b128 v[154:157], v199 offset:2048
	ds_read_b128 v[158:161], v199 offset:3072
	ds_read_b128 v[162:165], v199 offset:4096
	ds_read_b128 v[166:169], v199 offset:5120
	ds_read_b128 v[170:173], v199 offset:6144
	ds_read_b128 v[174:177], v199 offset:7168
	global_load_lds_dwordx4 v212, s[8:9]
	s_add_i32 m0, s34, 0xe000
	s_nop 0
	global_load_lds_dwordx4 v214, s[8:9]
	s_waitcnt lgkmcnt(8)
	s_setprio 1
	s_barrier
	s_waitcnt lgkmcnt(0)
	v_mfma_f32_16x16x32_bf16 v[126:129], v[130:133], v[146:149], v[126:129]
	v_mfma_f32_16x16x32_bf16 v[122:125], v[138:141], v[146:149], v[122:125]
	v_mfma_f32_16x16x32_bf16 v[118:121], v[130:133], v[154:157], v[118:121]
	v_mfma_f32_16x16x32_bf16 v[114:117], v[138:141], v[154:157], v[114:117]
	v_mfma_f32_16x16x32_bf16 v[110:113], v[130:133], v[162:165], v[110:113]
	v_mfma_f32_16x16x32_bf16 v[106:109], v[138:141], v[162:165], v[106:109]
	v_mfma_f32_16x16x32_bf16 v[102:105], v[130:133], v[170:173], v[102:105]
	v_mfma_f32_16x16x32_bf16 v[98:101], v[138:141], v[170:173], v[98:101]
	v_mfma_f32_16x16x32_bf16 v[126:129], v[134:137], v[150:153], v[126:129]
	v_mfma_f32_16x16x32_bf16 v[122:125], v[142:145], v[150:153], v[122:125]
	v_mfma_f32_16x16x32_bf16 v[118:121], v[134:137], v[158:161], v[118:121]
	v_mfma_f32_16x16x32_bf16 v[114:117], v[142:145], v[158:161], v[114:117]
	v_mfma_f32_16x16x32_bf16 v[110:113], v[134:137], v[166:169], v[110:113]
	v_mfma_f32_16x16x32_bf16 v[106:109], v[142:145], v[166:169], v[106:109]
	v_mfma_f32_16x16x32_bf16 v[102:105], v[134:137], v[174:177], v[102:105]
	v_mfma_f32_16x16x32_bf16 v[98:101], v[142:145], v[174:177], v[98:101]
	s_barrier
	s_setprio 0
	s_add_u32 s10, s8, 0xfffc0080
	s_addc_u32 s11, s9, -1
	s_cmp_eq_u32 s29, 12
	s_cselect_b32 s11, s81, s11
	s_cselect_b32 s10, s80, s10
	s_cselect_b32 s53, s83, s28
	s_cselect_b32 s52, s82, s7
	s_mov_b32 m0, s35
	v_lshl_add_u64 v[216:217], s[52:53], 0, v[194:195]
	ds_read_b128 v[178:181], v253 offset:16384
	ds_read_b128 v[182:185], v253 offset:17408
	ds_read_b128 v[186:189], v253 offset:18432
	ds_read_b128 v[190:193], v253 offset:19456
	global_load_lds_dwordx4 v[216:217], off
	v_lshl_add_u64 v[218:219], s[52:53], 0, v[210:211]
	s_mov_b32 m0, s42
	s_nop 0
	global_load_lds_dwordx4 v[218:219], off
	s_setprio 1
	s_barrier
	s_waitcnt lgkmcnt(0)
	v_mfma_f32_16x16x32_bf16 v[94:97], v[178:181], v[146:149], v[94:97]
	v_mfma_f32_16x16x32_bf16 v[90:93], v[186:189], v[146:149], v[90:93]
	v_mfma_f32_16x16x32_bf16 v[86:89], v[178:181], v[154:157], v[86:89]
	v_mfma_f32_16x16x32_bf16 v[82:85], v[186:189], v[154:157], v[82:85]
	v_mfma_f32_16x16x32_bf16 v[78:81], v[178:181], v[162:165], v[78:81]
	v_mfma_f32_16x16x32_bf16 v[74:77], v[186:189], v[162:165], v[74:77]
	v_mfma_f32_16x16x32_bf16 v[70:73], v[178:181], v[170:173], v[70:73]
	v_mfma_f32_16x16x32_bf16 v[66:69], v[186:189], v[170:173], v[66:69]
	v_mfma_f32_16x16x32_bf16 v[94:97], v[182:185], v[150:153], v[94:97]
	v_mfma_f32_16x16x32_bf16 v[90:93], v[190:193], v[150:153], v[90:93]
	v_mfma_f32_16x16x32_bf16 v[86:89], v[182:185], v[158:161], v[86:89]
	v_mfma_f32_16x16x32_bf16 v[82:85], v[190:193], v[158:161], v[82:85]
	v_mfma_f32_16x16x32_bf16 v[78:81], v[182:185], v[166:169], v[78:81]
	v_mfma_f32_16x16x32_bf16 v[74:77], v[190:193], v[166:169], v[74:77]
	s_mov_b32 m0, s34
	v_mfma_f32_16x16x32_bf16 v[70:73], v[182:185], v[174:177], v[70:73]
	v_lshl_add_u64 v[220:221], s[10:11], 0, v[206:207]
	v_mfma_f32_16x16x32_bf16 v[66:69], v[190:193], v[174:177], v[66:69]
	s_barrier
	s_setprio 0
	ds_read_b128 v[146:149], v199 offset:16384
	ds_read_b128 v[150:153], v199 offset:17408
	ds_read_b128 v[154:157], v199 offset:18432
	ds_read_b128 v[158:161], v199 offset:19456
	ds_read_b128 v[162:165], v199 offset:20480
	ds_read_b128 v[166:169], v199 offset:21504
	ds_read_b128 v[170:173], v199 offset:22528
	ds_read_b128 v[174:177], v199 offset:23552
	global_load_lds_dwordx4 v[220:221], off
	v_lshl_add_u64 v[222:223], s[10:11], 0, v[208:209]
	s_mov_b32 m0, s56
	s_nop 0
	global_load_lds_dwordx4 v[222:223], off
	s_setprio 1
	s_barrier
	s_waitcnt lgkmcnt(0)
	v_mfma_f32_16x16x32_bf16 v[62:65], v[130:133], v[146:149], v[62:65]
	v_mfma_f32_16x16x32_bf16 v[58:61], v[138:141], v[146:149], v[58:61]
	v_mfma_f32_16x16x32_bf16 v[54:57], v[130:133], v[154:157], v[54:57]
	v_mfma_f32_16x16x32_bf16 v[50:53], v[138:141], v[154:157], v[50:53]
	v_mfma_f32_16x16x32_bf16 v[46:49], v[130:133], v[162:165], v[46:49]
	v_mfma_f32_16x16x32_bf16 v[42:45], v[138:141], v[162:165], v[42:45]
	v_mfma_f32_16x16x32_bf16 v[38:41], v[130:133], v[170:173], v[38:41]
	v_mfma_f32_16x16x32_bf16 v[34:37], v[138:141], v[170:173], v[34:37]
	v_mfma_f32_16x16x32_bf16 v[62:65], v[134:137], v[150:153], v[62:65]
	v_mfma_f32_16x16x32_bf16 v[58:61], v[142:145], v[150:153], v[58:61]
	v_mfma_f32_16x16x32_bf16 v[54:57], v[134:137], v[158:161], v[54:57]
	v_mfma_f32_16x16x32_bf16 v[50:53], v[142:145], v[158:161], v[50:53]
	v_mfma_f32_16x16x32_bf16 v[46:49], v[134:137], v[166:169], v[46:49]
	v_mfma_f32_16x16x32_bf16 v[42:45], v[142:145], v[166:169], v[42:45]
	v_mfma_f32_16x16x32_bf16 v[38:41], v[134:137], v[174:177], v[38:41]
	v_mfma_f32_16x16x32_bf16 v[34:37], v[142:145], v[174:177], v[34:37]
	s_barrier
	s_setprio 0
	s_add_u32 s86, s52, 0x40000
	s_addc_u32 s87, s53, 0
	s_mov_b32 m0, s57
	s_nop 0
	global_load_lds_dwordx4 v194, s[86:87]
	s_mov_b32 m0, s67
	s_nop 0
	global_load_lds_dwordx4 v210, s[86:87]
	s_waitcnt vmcnt(6)
	s_setprio 1
	s_barrier
	v_mfma_f32_16x16x32_bf16 v[30:33], v[178:181], v[146:149], v[30:33]
	v_mfma_f32_16x16x32_bf16 v[26:29], v[186:189], v[146:149], v[26:29]
	v_mfma_f32_16x16x32_bf16 v[22:25], v[178:181], v[154:157], v[22:25]
	v_mfma_f32_16x16x32_bf16 v[18:21], v[186:189], v[154:157], v[18:21]
	v_mfma_f32_16x16x32_bf16 v[14:17], v[178:181], v[162:165], v[14:17]
	v_mfma_f32_16x16x32_bf16 v[10:13], v[186:189], v[162:165], v[10:13]
	v_mfma_f32_16x16x32_bf16 v[6:9], v[178:181], v[170:173], v[6:9]
	v_mfma_f32_16x16x32_bf16 v[2:5], v[186:189], v[170:173], v[2:5]
	v_mfma_f32_16x16x32_bf16 v[30:33], v[182:185], v[150:153], v[30:33]
	v_mfma_f32_16x16x32_bf16 v[26:29], v[190:193], v[150:153], v[26:29]
	v_mfma_f32_16x16x32_bf16 v[22:25], v[182:185], v[158:161], v[22:25]
	v_mfma_f32_16x16x32_bf16 v[18:21], v[190:193], v[158:161], v[18:21]
	v_mfma_f32_16x16x32_bf16 v[14:17], v[182:185], v[166:169], v[14:17]
	v_mfma_f32_16x16x32_bf16 v[10:13], v[190:193], v[166:169], v[10:13]
	v_mfma_f32_16x16x32_bf16 v[6:9], v[182:185], v[174:177], v[6:9]
	v_mfma_f32_16x16x32_bf16 v[2:5], v[190:193], v[174:177], v[2:5]
	s_barrier
	s_setprio 0
	ds_read_b128 v[130:133], v253 offset:32768
	ds_read_b128 v[134:137], v253 offset:33792
	ds_read_b128 v[138:141], v253 offset:34816
	ds_read_b128 v[142:145], v253 offset:35840
	s_add_u32 s10, s10, 0x40000
	s_addc_u32 s11, s11, 0
	s_mov_b32 m0, s70
	ds_read_b128 v[146:149], v199 offset:32768
	ds_read_b128 v[150:153], v199 offset:33792
	ds_read_b128 v[154:157], v199 offset:34816
	ds_read_b128 v[158:161], v199 offset:35840
	ds_read_b128 v[162:165], v199 offset:36864
	ds_read_b128 v[166:169], v199 offset:37888
	ds_read_b128 v[170:173], v199 offset:38912
	ds_read_b128 v[174:177], v199 offset:39936
	global_load_lds_dwordx4 v206, s[10:11]
	s_mov_b32 m0, s71
	s_nop 0
	global_load_lds_dwordx4 v208, s[10:11]
	s_waitcnt lgkmcnt(8)
	s_setprio 1
	s_barrier
	s_waitcnt lgkmcnt(0)
	v_mfma_f32_16x16x32_bf16 v[126:129], v[130:133], v[146:149], v[126:129]
	v_mfma_f32_16x16x32_bf16 v[122:125], v[138:141], v[146:149], v[122:125]
	v_mfma_f32_16x16x32_bf16 v[118:121], v[130:133], v[154:157], v[118:121]
	v_mfma_f32_16x16x32_bf16 v[114:117], v[138:141], v[154:157], v[114:117]
	v_mfma_f32_16x16x32_bf16 v[110:113], v[130:133], v[162:165], v[110:113]
	v_mfma_f32_16x16x32_bf16 v[106:109], v[138:141], v[162:165], v[106:109]
	v_mfma_f32_16x16x32_bf16 v[102:105], v[130:133], v[170:173], v[102:105]
	v_mfma_f32_16x16x32_bf16 v[98:101], v[138:141], v[170:173], v[98:101]
	v_mfma_f32_16x16x32_bf16 v[126:129], v[134:137], v[150:153], v[126:129]
	v_mfma_f32_16x16x32_bf16 v[122:125], v[142:145], v[150:153], v[122:125]
	v_mfma_f32_16x16x32_bf16 v[118:121], v[134:137], v[158:161], v[118:121]
	v_mfma_f32_16x16x32_bf16 v[114:117], v[142:145], v[158:161], v[114:117]
	v_mfma_f32_16x16x32_bf16 v[110:113], v[134:137], v[166:169], v[110:113]
	v_mfma_f32_16x16x32_bf16 v[106:109], v[142:145], v[166:169], v[106:109]
	v_mfma_f32_16x16x32_bf16 v[102:105], v[134:137], v[174:177], v[102:105]
	v_mfma_f32_16x16x32_bf16 v[98:101], v[142:145], v[174:177], v[98:101]
	s_barrier
	s_setprio 0
	s_mov_b32 m0, s78
	v_lshl_add_u64 v[216:217], v[216:217], 0, s[76:77]
	ds_read_b128 v[178:181], v253 offset:49152
	ds_read_b128 v[182:185], v253 offset:50176
	ds_read_b128 v[186:189], v253 offset:51200
	ds_read_b128 v[190:193], v253 offset:52224
	global_load_lds_dwordx4 v[216:217], off
	v_lshl_add_u64 v[216:217], v[218:219], 0, s[76:77]
	s_mov_b32 m0, s79
	s_nop 0
	global_load_lds_dwordx4 v[216:217], off
	s_setprio 1
	s_barrier
	s_waitcnt lgkmcnt(0)
	v_mfma_f32_16x16x32_bf16 v[94:97], v[178:181], v[146:149], v[94:97]
	v_mfma_f32_16x16x32_bf16 v[90:93], v[186:189], v[146:149], v[90:93]
	v_mfma_f32_16x16x32_bf16 v[86:89], v[178:181], v[154:157], v[86:89]
	v_mfma_f32_16x16x32_bf16 v[82:85], v[186:189], v[154:157], v[82:85]
	v_mfma_f32_16x16x32_bf16 v[78:81], v[178:181], v[162:165], v[78:81]
	v_mfma_f32_16x16x32_bf16 v[74:77], v[186:189], v[162:165], v[74:77]
	v_mfma_f32_16x16x32_bf16 v[70:73], v[178:181], v[170:173], v[70:73]
	v_mfma_f32_16x16x32_bf16 v[66:69], v[186:189], v[170:173], v[66:69]
	v_mfma_f32_16x16x32_bf16 v[94:97], v[182:185], v[150:153], v[94:97]
	v_mfma_f32_16x16x32_bf16 v[90:93], v[190:193], v[150:153], v[90:93]
	v_mfma_f32_16x16x32_bf16 v[86:89], v[182:185], v[158:161], v[86:89]
	v_mfma_f32_16x16x32_bf16 v[82:85], v[190:193], v[158:161], v[82:85]
	v_mfma_f32_16x16x32_bf16 v[78:81], v[182:185], v[166:169], v[78:81]
	v_mfma_f32_16x16x32_bf16 v[74:77], v[190:193], v[166:169], v[74:77]
	s_mov_b32 m0, s26
	v_mfma_f32_16x16x32_bf16 v[70:73], v[182:185], v[174:177], v[70:73]
	v_lshl_add_u64 v[216:217], v[220:221], 0, s[76:77]
	v_mfma_f32_16x16x32_bf16 v[66:69], v[190:193], v[174:177], v[66:69]
	s_barrier
	s_setprio 0
	ds_read_b128 v[146:149], v199 offset:49152
	ds_read_b128 v[150:153], v199 offset:50176
	ds_read_b128 v[154:157], v199 offset:51200
	ds_read_b128 v[158:161], v199 offset:52224
	ds_read_b128 v[162:165], v199 offset:53248
	ds_read_b128 v[166:169], v199 offset:54272
	ds_read_b128 v[170:173], v199 offset:55296
	ds_read_b128 v[174:177], v199 offset:56320
	global_load_lds_dwordx4 v[216:217], off
	v_lshl_add_u64 v[216:217], v[222:223], 0, s[76:77]
	s_mov_b32 m0, s4
	s_nop 0
	global_load_lds_dwordx4 v[216:217], off
	s_setprio 1
	s_barrier
	s_waitcnt lgkmcnt(0)
	v_mfma_f32_16x16x32_bf16 v[62:65], v[130:133], v[146:149], v[62:65]
	v_mfma_f32_16x16x32_bf16 v[58:61], v[138:141], v[146:149], v[58:61]
	v_mfma_f32_16x16x32_bf16 v[54:57], v[130:133], v[154:157], v[54:57]
	v_mfma_f32_16x16x32_bf16 v[50:53], v[138:141], v[154:157], v[50:53]
	v_mfma_f32_16x16x32_bf16 v[46:49], v[130:133], v[162:165], v[46:49]
	v_mfma_f32_16x16x32_bf16 v[42:45], v[138:141], v[162:165], v[42:45]
	v_mfma_f32_16x16x32_bf16 v[38:41], v[130:133], v[170:173], v[38:41]
	v_mfma_f32_16x16x32_bf16 v[34:37], v[138:141], v[170:173], v[34:37]
	v_mfma_f32_16x16x32_bf16 v[62:65], v[134:137], v[150:153], v[62:65]
	v_mfma_f32_16x16x32_bf16 v[58:61], v[142:145], v[150:153], v[58:61]
	v_mfma_f32_16x16x32_bf16 v[54:57], v[134:137], v[158:161], v[54:57]
	v_mfma_f32_16x16x32_bf16 v[50:53], v[142:145], v[158:161], v[50:53]
	v_mfma_f32_16x16x32_bf16 v[46:49], v[134:137], v[166:169], v[46:49]
	v_mfma_f32_16x16x32_bf16 v[42:45], v[142:145], v[166:169], v[42:45]
	v_mfma_f32_16x16x32_bf16 v[38:41], v[134:137], v[174:177], v[38:41]
	v_mfma_f32_16x16x32_bf16 v[34:37], v[142:145], v[174:177], v[34:37]
	s_barrier
	s_setprio 0
	s_add_u32 s10, s52, 0x40080
	s_addc_u32 s11, s53, 0
	s_mov_b32 m0, s5
	s_nop 0
	global_load_lds_dwordx4 v194, s[10:11]
	s_mov_b32 m0, s58
	s_nop 0
	global_load_lds_dwordx4 v210, s[10:11]
	s_waitcnt vmcnt(6)
	s_setprio 1
	s_barrier
	v_mfma_f32_16x16x32_bf16 v[30:33], v[178:181], v[146:149], v[30:33]
	v_mfma_f32_16x16x32_bf16 v[26:29], v[186:189], v[146:149], v[26:29]
	v_mfma_f32_16x16x32_bf16 v[22:25], v[178:181], v[154:157], v[22:25]
	v_mfma_f32_16x16x32_bf16 v[18:21], v[186:189], v[154:157], v[18:21]
	v_mfma_f32_16x16x32_bf16 v[14:17], v[178:181], v[162:165], v[14:17]
	v_mfma_f32_16x16x32_bf16 v[10:13], v[186:189], v[162:165], v[10:13]
	v_mfma_f32_16x16x32_bf16 v[6:9], v[178:181], v[170:173], v[6:9]
	v_mfma_f32_16x16x32_bf16 v[2:5], v[186:189], v[170:173], v[2:5]
	v_mfma_f32_16x16x32_bf16 v[30:33], v[182:185], v[150:153], v[30:33]
	v_mfma_f32_16x16x32_bf16 v[26:29], v[190:193], v[150:153], v[26:29]
	v_mfma_f32_16x16x32_bf16 v[22:25], v[182:185], v[158:161], v[22:25]
	v_mfma_f32_16x16x32_bf16 v[18:21], v[190:193], v[158:161], v[18:21]
	v_mfma_f32_16x16x32_bf16 v[14:17], v[182:185], v[166:169], v[14:17]
	v_mfma_f32_16x16x32_bf16 v[10:13], v[190:193], v[166:169], v[10:13]
	v_mfma_f32_16x16x32_bf16 v[6:9], v[182:185], v[174:177], v[6:9]
	v_mfma_f32_16x16x32_bf16 v[2:5], v[190:193], v[174:177], v[2:5]
	s_setprio 0
	s_add_i32 s29, s29, 2
	s_add_u32 s8, s8, 0x100
	s_addc_u32 s9, s9, 0
	s_add_u32 s7, s7, 0x100
	s_addc_u32 s28, s28, 0
	s_cmp_gt_u32 s29, 13
	s_barrier
	s_cbranch_scc0 .LBB0_368
	s_cmp_gt_i32 s95, 1
	s_cselect_b64 s[52:53], -1, 0
	s_mul_i32 s7, s6, 0x680000
	s_lshl_b32 s8, s95, 12
	s_lshl_b32 s9, s54, 9
	s_add_i32 s7, s7, s8
	s_add_i32 s7, s7, s9
	s_add_i32 s7, s7, 0x3800
	s_add_u32 s20, s50, s7
	s_addc_u32 s21, s51, 0
	s_lshl_b32 s7, s6, 20
	s_add_i32 s7, s7, s9
	s_add_u32 s10, s96, s7
	s_addc_u32 s11, s97, 0
	s_mov_b32 s86, 0xbfb8aa3b
	s_mov_b32 s87, 0xbfb8aa3b
	v_mul_u32_u24_e32 v253, 0x6800, v197
	v_lshlrev_b32_e32 v255, 12, v197
	v_lshl_add_u32 v253, v203, 1, v253
	v_lshl_add_u32 v255, v203, 1, v255
	v_add_u32_e32 v254, 0x1000, v253
	s_cmp_eq_u32 s95, 2
	s_cbranch_scc1 .Lem_br2
	global_load_dwordx4 v[130:133], v253, s[20:21]
	global_load_dwordx4 v[134:137], v254, s[20:21]
	global_load_dwordx4 v[138:141], v253, s[20:21] offset:256
	global_load_dwordx4 v[142:145], v254, s[20:21] offset:256
	s_add_u32 s28, s20, 0x68000
	s_addc_u32 s29, s21, 0
	global_load_dwordx4 v[146:149], v253, s[28:29]
	global_load_dwordx4 v[150:153], v254, s[28:29]
	global_load_dwordx4 v[154:157], v253, s[28:29] offset:256
	global_load_dwordx4 v[158:161], v254, s[28:29] offset:256
	s_add_u32 s28, s20, 0xd0000
	s_addc_u32 s29, s21, 0
	global_load_dwordx4 v[162:165], v253, s[28:29]
	global_load_dwordx4 v[166:169], v254, s[28:29]
	global_load_dwordx4 v[170:173], v253, s[28:29] offset:256
	global_load_dwordx4 v[174:177], v254, s[28:29] offset:256
	s_add_u32 s28, s20, 0x138000
	s_addc_u32 s29, s21, 0
	global_load_dwordx4 v[178:181], v253, s[28:29]
	global_load_dwordx4 v[182:185], v254, s[28:29]
	global_load_dwordx4 v[186:189], v253, s[28:29] offset:256
	global_load_dwordx4 v[190:193], v254, s[28:29] offset:256
	s_waitcnt vmcnt(12)
	v_lshlrev_b32_e32 v216, 16, v130
	v_and_b32_e32 v217, 0xffff0000, v130
	v_lshlrev_b32_e32 v218, 16, v131
	v_and_b32_e32 v219, 0xffff0000, v131
	v_lshlrev_b32_e32 v220, 16, v132
	v_and_b32_e32 v221, 0xffff0000, v132
	v_lshlrev_b32_e32 v222, 16, v133
	v_and_b32_e32 v223, 0xffff0000, v133
	v_pk_mul_f32 v[216:217], v[216:217], s[86:87] op_sel_hi:[1,0]
	v_pk_mul_f32 v[218:219], v[218:219], s[86:87] op_sel_hi:[1,0]
	v_pk_mul_f32 v[220:221], v[220:221], s[86:87] op_sel_hi:[1,0]
	v_pk_mul_f32 v[222:223], v[222:223], s[86:87] op_sel_hi:[1,0]
	v_exp_f32_e32 v216, v216
	v_exp_f32_e32 v217, v217
	v_exp_f32_e32 v218, v218
	v_exp_f32_e32 v219, v219
	v_exp_f32_e32 v220, v220
	v_exp_f32_e32 v221, v221
	v_exp_f32_e32 v222, v222
	v_exp_f32_e32 v223, v223
	v_pk_add_f32 v[216:217], v[216:217], 1.0 op_sel_hi:[1,0]
	v_pk_add_f32 v[218:219], v[218:219], 1.0 op_sel_hi:[1,0]
	v_pk_add_f32 v[220:221], v[220:221], 1.0 op_sel_hi:[1,0]
	v_pk_add_f32 v[222:223], v[222:223], 1.0 op_sel_hi:[1,0]
	v_rcp_f32_e32 v216, v216
	v_rcp_f32_e32 v217, v217
	v_rcp_f32_e32 v218, v218
	v_rcp_f32_e32 v219, v219
	v_rcp_f32_e32 v220, v220
	v_rcp_f32_e32 v221, v221
	v_rcp_f32_e32 v222, v222
	v_rcp_f32_e32 v223, v223
	v_lshlrev_b32_e32 v242, 16, v134
	v_and_b32_e32 v243, 0xffff0000, v134
	v_lshlrev_b32_e32 v244, 16, v135
	v_and_b32_e32 v245, 0xffff0000, v135
	v_lshlrev_b32_e32 v246, 16, v136
	v_and_b32_e32 v247, 0xffff0000, v136
	v_lshlrev_b32_e32 v248, 16, v137
	v_and_b32_e32 v249, 0xffff0000, v137
	v_pk_mul_f32 v[242:243], v[242:243], s[86:87] op_sel_hi:[1,0]
	v_pk_mul_f32 v[244:245], v[244:245], s[86:87] op_sel_hi:[1,0]
	v_pk_mul_f32 v[246:247], v[246:247], s[86:87] op_sel_hi:[1,0]
	v_pk_mul_f32 v[248:249], v[248:249], s[86:87] op_sel_hi:[1,0]
	v_exp_f32_e32 v242, v242
	v_exp_f32_e32 v243, v243
	v_exp_f32_e32 v244, v244
	v_exp_f32_e32 v245, v245
	v_exp_f32_e32 v246, v246
	v_exp_f32_e32 v247, v247
	v_exp_f32_e32 v248, v248
	v_exp_f32_e32 v249, v249
	v_pk_add_f32 v[242:243], v[242:243], 1.0 op_sel_hi:[1,0]
	v_pk_add_f32 v[244:245], v[244:245], 1.0 op_sel_hi:[1,0]
	v_pk_add_f32 v[246:247], v[246:247], 1.0 op_sel_hi:[1,0]
	v_pk_add_f32 v[248:249], v[248:249], 1.0 op_sel_hi:[1,0]
	v_pk_mul_f32 v[216:217], v[216:217], v[242:243]
	v_pk_mul_f32 v[218:219], v[218:219], v[244:245]
	v_pk_mul_f32 v[220:221], v[220:221], v[246:247]
	v_pk_mul_f32 v[222:223], v[222:223], v[248:249]
	v_pk_mul_f32 v[126:127], v[126:127], v[216:217]
	v_pk_mul_f32 v[128:129], v[128:129], v[218:219]
	v_pk_mul_f32 v[122:123], v[122:123], v[220:221]
	v_pk_mul_f32 v[124:125], v[124:125], v[222:223]
	v_lshlrev_b32_e32 v216, 16, v138
	v_and_b32_e32 v217, 0xffff0000, v138
	v_lshlrev_b32_e32 v218, 16, v139
	v_and_b32_e32 v219, 0xffff0000, v139
	v_lshlrev_b32_e32 v220, 16, v140
	v_and_b32_e32 v221, 0xffff0000, v140
	v_lshlrev_b32_e32 v222, 16, v141
	v_and_b32_e32 v223, 0xffff0000, v141
	v_pk_mul_f32 v[216:217], v[216:217], s[86:87] op_sel_hi:[1,0]
	v_pk_mul_f32 v[218:219], v[218:219], s[86:87] op_sel_hi:[1,0]
	v_pk_mul_f32 v[220:221], v[220:221], s[86:87] op_sel_hi:[1,0]
	v_pk_mul_f32 v[222:223], v[222:223], s[86:87] op_sel_hi:[1,0]
	v_exp_f32_e32 v216, v216
	v_exp_f32_e32 v217, v217
	v_exp_f32_e32 v218, v218
	v_exp_f32_e32 v219, v219
	v_exp_f32_e32 v220, v220
	v_exp_f32_e32 v221, v221
	v_exp_f32_e32 v222, v222
	v_exp_f32_e32 v223, v223
	v_pk_add_f32 v[216:217], v[216:217], 1.0 op_sel_hi:[1,0]
	v_pk_add_f32 v[218:219], v[218:219], 1.0 op_sel_hi:[1,0]
	v_pk_add_f32 v[220:221], v[220:221], 1.0 op_sel_hi:[1,0]
	v_pk_add_f32 v[222:223], v[222:223], 1.0 op_sel_hi:[1,0]
	v_rcp_f32_e32 v216, v216
	v_rcp_f32_e32 v217, v217
	v_rcp_f32_e32 v218, v218
	v_rcp_f32_e32 v219, v219
	v_rcp_f32_e32 v220, v220
	v_rcp_f32_e32 v221, v221
	v_rcp_f32_e32 v222, v222
	v_rcp_f32_e32 v223, v223
	v_lshlrev_b32_e32 v242, 16, v142
	v_and_b32_e32 v243, 0xffff0000, v142
	v_lshlrev_b32_e32 v244, 16, v143
	v_and_b32_e32 v245, 0xffff0000, v143
	v_lshlrev_b32_e32 v246, 16, v144
	v_and_b32_e32 v247, 0xffff0000, v144
	v_lshlrev_b32_e32 v248, 16, v145
	v_and_b32_e32 v249, 0xffff0000, v145
	v_pk_mul_f32 v[242:243], v[242:243], s[86:87] op_sel_hi:[1,0]
	v_pk_mul_f32 v[244:245], v[244:245], s[86:87] op_sel_hi:[1,0]
	v_pk_mul_f32 v[246:247], v[246:247], s[86:87] op_sel_hi:[1,0]
	v_pk_mul_f32 v[248:249], v[248:249], s[86:87] op_sel_hi:[1,0]
	v_exp_f32_e32 v242, v242
	v_exp_f32_e32 v243, v243
	v_exp_f32_e32 v244, v244
	v_exp_f32_e32 v245, v245
	v_exp_f32_e32 v246, v246
	v_exp_f32_e32 v247, v247
	v_exp_f32_e32 v248, v248
	v_exp_f32_e32 v249, v249
	v_pk_add_f32 v[242:243], v[242:243], 1.0 op_sel_hi:[1,0]
	v_pk_add_f32 v[244:245], v[244:245], 1.0 op_sel_hi:[1,0]
	v_pk_add_f32 v[246:247], v[246:247], 1.0 op_sel_hi:[1,0]
	v_pk_add_f32 v[248:249], v[248:249], 1.0 op_sel_hi:[1,0]
	v_pk_mul_f32 v[216:217], v[216:217], v[242:243]
	v_pk_mul_f32 v[218:219], v[218:219], v[244:245]
	v_pk_mul_f32 v[220:221], v[220:221], v[246:247]
	v_pk_mul_f32 v[222:223], v[222:223], v[248:249]
	v_pk_mul_f32 v[94:95], v[94:95], v[216:217]
	v_pk_mul_f32 v[96:97], v[96:97], v[218:219]
	v_pk_mul_f32 v[90:91], v[90:91], v[220:221]
	v_pk_mul_f32 v[92:93], v[92:93], v[222:223]
	s_add_u32 s28, s20, 0x340000
	s_addc_u32 s29, s21, 0
	global_load_dwordx4 v[130:133], v253, s[28:29]
	global_load_dwordx4 v[134:137], v254, s[28:29]
	global_load_dwordx4 v[138:141], v253, s[28:29] offset:256
	global_load_dwordx4 v[142:145], v254, s[28:29] offset:256
	s_waitcnt vmcnt(12)
	v_lshlrev_b32_e32 v216, 16, v146
	v_and_b32_e32 v217, 0xffff0000, v146
	v_lshlrev_b32_e32 v218, 16, v147
	v_and_b32_e32 v219, 0xffff0000, v147
	v_lshlrev_b32_e32 v220, 16, v148
	v_and_b32_e32 v221, 0xffff0000, v148
	v_lshlrev_b32_e32 v222, 16, v149
	v_and_b32_e32 v223, 0xffff0000, v149
	v_pk_mul_f32 v[216:217], v[216:217], s[86:87] op_sel_hi:[1,0]
	v_pk_mul_f32 v[218:219], v[218:219], s[86:87] op_sel_hi:[1,0]
	v_pk_mul_f32 v[220:221], v[220:221], s[86:87] op_sel_hi:[1,0]
	v_pk_mul_f32 v[222:223], v[222:223], s[86:87] op_sel_hi:[1,0]
	v_exp_f32_e32 v216, v216
	v_exp_f32_e32 v217, v217
	v_exp_f32_e32 v218, v218
	v_exp_f32_e32 v219, v219
	v_exp_f32_e32 v220, v220
	v_exp_f32_e32 v221, v221
	v_exp_f32_e32 v222, v222
	v_exp_f32_e32 v223, v223
	v_pk_add_f32 v[216:217], v[216:217], 1.0 op_sel_hi:[1,0]
	v_pk_add_f32 v[218:219], v[218:219], 1.0 op_sel_hi:[1,0]
	v_pk_add_f32 v[220:221], v[220:221], 1.0 op_sel_hi:[1,0]
	v_pk_add_f32 v[222:223], v[222:223], 1.0 op_sel_hi:[1,0]
	v_rcp_f32_e32 v216, v216
	v_rcp_f32_e32 v217, v217
	v_rcp_f32_e32 v218, v218
	v_rcp_f32_e32 v219, v219
	v_rcp_f32_e32 v220, v220
	v_rcp_f32_e32 v221, v221
	v_rcp_f32_e32 v222, v222
	v_rcp_f32_e32 v223, v223
	v_lshlrev_b32_e32 v242, 16, v150
	v_and_b32_e32 v243, 0xffff0000, v150
	v_lshlrev_b32_e32 v244, 16, v151
	v_and_b32_e32 v245, 0xffff0000, v151
	v_lshlrev_b32_e32 v246, 16, v152
	v_and_b32_e32 v247, 0xffff0000, v152
	v_lshlrev_b32_e32 v248, 16, v153
	v_and_b32_e32 v249, 0xffff0000, v153
	v_pk_mul_f32 v[242:243], v[242:243], s[86:87] op_sel_hi:[1,0]
	v_pk_mul_f32 v[244:245], v[244:245], s[86:87] op_sel_hi:[1,0]
	v_pk_mul_f32 v[246:247], v[246:247], s[86:87] op_sel_hi:[1,0]
	v_pk_mul_f32 v[248:249], v[248:249], s[86:87] op_sel_hi:[1,0]
	v_exp_f32_e32 v242, v242
	v_exp_f32_e32 v243, v243
	v_exp_f32_e32 v244, v244
	v_exp_f32_e32 v245, v245
	v_exp_f32_e32 v246, v246
	v_exp_f32_e32 v247, v247
	v_exp_f32_e32 v248, v248
	v_exp_f32_e32 v249, v249
	v_pk_add_f32 v[242:243], v[242:243], 1.0 op_sel_hi:[1,0]
	v_pk_add_f32 v[244:245], v[244:245], 1.0 op_sel_hi:[1,0]
	v_pk_add_f32 v[246:247], v[246:247], 1.0 op_sel_hi:[1,0]
	v_pk_add_f32 v[248:249], v[248:249], 1.0 op_sel_hi:[1,0]
	v_pk_mul_f32 v[216:217], v[216:217], v[242:243]
	v_pk_mul_f32 v[218:219], v[218:219], v[244:245]
	v_pk_mul_f32 v[220:221], v[220:221], v[246:247]
	v_pk_mul_f32 v[222:223], v[222:223], v[248:249]
	v_pk_mul_f32 v[118:119], v[118:119], v[216:217]
	v_pk_mul_f32 v[120:121], v[120:121], v[218:219]
	v_pk_mul_f32 v[114:115], v[114:115], v[220:221]
	v_pk_mul_f32 v[116:117], v[116:117], v[222:223]
	v_lshlrev_b32_e32 v216, 16, v154
	v_and_b32_e32 v217, 0xffff0000, v154
	v_lshlrev_b32_e32 v218, 16, v155
	v_and_b32_e32 v219, 0xffff0000, v155
	v_lshlrev_b32_e32 v220, 16, v156
	v_and_b32_e32 v221, 0xffff0000, v156
	v_lshlrev_b32_e32 v222, 16, v157
	v_and_b32_e32 v223, 0xffff0000, v157
	v_pk_mul_f32 v[216:217], v[216:217], s[86:87] op_sel_hi:[1,0]
	v_pk_mul_f32 v[218:219], v[218:219], s[86:87] op_sel_hi:[1,0]
	v_pk_mul_f32 v[220:221], v[220:221], s[86:87] op_sel_hi:[1,0]
	v_pk_mul_f32 v[222:223], v[222:223], s[86:87] op_sel_hi:[1,0]
	v_exp_f32_e32 v216, v216
	v_exp_f32_e32 v217, v217
	v_exp_f32_e32 v218, v218
	v_exp_f32_e32 v219, v219
	v_exp_f32_e32 v220, v220
	v_exp_f32_e32 v221, v221
	v_exp_f32_e32 v222, v222
	v_exp_f32_e32 v223, v223
	v_pk_add_f32 v[216:217], v[216:217], 1.0 op_sel_hi:[1,0]
	v_pk_add_f32 v[218:219], v[218:219], 1.0 op_sel_hi:[1,0]
	v_pk_add_f32 v[220:221], v[220:221], 1.0 op_sel_hi:[1,0]
	v_pk_add_f32 v[222:223], v[222:223], 1.0 op_sel_hi:[1,0]
	v_rcp_f32_e32 v216, v216
	v_rcp_f32_e32 v217, v217
	v_rcp_f32_e32 v218, v218
	v_rcp_f32_e32 v219, v219
	v_rcp_f32_e32 v220, v220
	v_rcp_f32_e32 v221, v221
	v_rcp_f32_e32 v222, v222
	v_rcp_f32_e32 v223, v223
	v_lshlrev_b32_e32 v242, 16, v158
	v_and_b32_e32 v243, 0xffff0000, v158
	v_lshlrev_b32_e32 v244, 16, v159
	v_and_b32_e32 v245, 0xffff0000, v159
	v_lshlrev_b32_e32 v246, 16, v160
	v_and_b32_e32 v247, 0xffff0000, v160
	v_lshlrev_b32_e32 v248, 16, v161
	v_and_b32_e32 v249, 0xffff0000, v161
	v_pk_mul_f32 v[242:243], v[242:243], s[86:87] op_sel_hi:[1,0]
	v_pk_mul_f32 v[244:245], v[244:245], s[86:87] op_sel_hi:[1,0]
	v_pk_mul_f32 v[246:247], v[246:247], s[86:87] op_sel_hi:[1,0]
	v_pk_mul_f32 v[248:249], v[248:249], s[86:87] op_sel_hi:[1,0]
	v_exp_f32_e32 v242, v242
	v_exp_f32_e32 v243, v243
	v_exp_f32_e32 v244, v244
	v_exp_f32_e32 v245, v245
	v_exp_f32_e32 v246, v246
	v_exp_f32_e32 v247, v247
	v_exp_f32_e32 v248, v248
	v_exp_f32_e32 v249, v249
	v_pk_add_f32 v[242:243], v[242:243], 1.0 op_sel_hi:[1,0]
	v_pk_add_f32 v[244:245], v[244:245], 1.0 op_sel_hi:[1,0]
	v_pk_add_f32 v[246:247], v[246:247], 1.0 op_sel_hi:[1,0]
	v_pk_add_f32 v[248:249], v[248:249], 1.0 op_sel_hi:[1,0]
	v_pk_mul_f32 v[216:217], v[216:217], v[242:243]
	v_pk_mul_f32 v[218:219], v[218:219], v[244:245]
	v_pk_mul_f32 v[220:221], v[220:221], v[246:247]
	v_pk_mul_f32 v[222:223], v[222:223], v[248:249]
	v_pk_mul_f32 v[86:87], v[86:87], v[216:217]
	v_pk_mul_f32 v[88:89], v[88:89], v[218:219]
	v_pk_mul_f32 v[82:83], v[82:83], v[220:221]
	v_pk_mul_f32 v[84:85], v[84:85], v[222:223]
	s_add_u32 s28, s20, 0x3a8000
	s_addc_u32 s29, s21, 0
	global_load_dwordx4 v[146:149], v253, s[28:29]
	global_load_dwordx4 v[150:153], v254, s[28:29]
	global_load_dwordx4 v[154:157], v253, s[28:29] offset:256
	global_load_dwordx4 v[158:161], v254, s[28:29] offset:256
	s_waitcnt vmcnt(12)
	v_lshlrev_b32_e32 v216, 16, v162
	v_and_b32_e32 v217, 0xffff0000, v162
	v_lshlrev_b32_e32 v218, 16, v163
	v_and_b32_e32 v219, 0xffff0000, v163
	v_lshlrev_b32_e32 v220, 16, v164
	v_and_b32_e32 v221, 0xffff0000, v164
	v_lshlrev_b32_e32 v222, 16, v165
	v_and_b32_e32 v223, 0xffff0000, v165
	v_pk_mul_f32 v[216:217], v[216:217], s[86:87] op_sel_hi:[1,0]
	v_pk_mul_f32 v[218:219], v[218:219], s[86:87] op_sel_hi:[1,0]
	v_pk_mul_f32 v[220:221], v[220:221], s[86:87] op_sel_hi:[1,0]
	v_pk_mul_f32 v[222:223], v[222:223], s[86:87] op_sel_hi:[1,0]
	v_exp_f32_e32 v216, v216
	v_exp_f32_e32 v217, v217
	v_exp_f32_e32 v218, v218
	v_exp_f32_e32 v219, v219
	v_exp_f32_e32 v220, v220
	v_exp_f32_e32 v221, v221
	v_exp_f32_e32 v222, v222
	v_exp_f32_e32 v223, v223
	v_pk_add_f32 v[216:217], v[216:217], 1.0 op_sel_hi:[1,0]
	v_pk_add_f32 v[218:219], v[218:219], 1.0 op_sel_hi:[1,0]
	v_pk_add_f32 v[220:221], v[220:221], 1.0 op_sel_hi:[1,0]
	v_pk_add_f32 v[222:223], v[222:223], 1.0 op_sel_hi:[1,0]
	v_rcp_f32_e32 v216, v216
	v_rcp_f32_e32 v217, v217
	v_rcp_f32_e32 v218, v218
	v_rcp_f32_e32 v219, v219
	v_rcp_f32_e32 v220, v220
	v_rcp_f32_e32 v221, v221
	v_rcp_f32_e32 v222, v222
	v_rcp_f32_e32 v223, v223
	v_lshlrev_b32_e32 v242, 16, v166
	v_and_b32_e32 v243, 0xffff0000, v166
	v_lshlrev_b32_e32 v244, 16, v167
	v_and_b32_e32 v245, 0xffff0000, v167
	v_lshlrev_b32_e32 v246, 16, v168
	v_and_b32_e32 v247, 0xffff0000, v168
	v_lshlrev_b32_e32 v248, 16, v169
	v_and_b32_e32 v249, 0xffff0000, v169
	v_pk_mul_f32 v[242:243], v[242:243], s[86:87] op_sel_hi:[1,0]
	v_pk_mul_f32 v[244:245], v[244:245], s[86:87] op_sel_hi:[1,0]
	v_pk_mul_f32 v[246:247], v[246:247], s[86:87] op_sel_hi:[1,0]
	v_pk_mul_f32 v[248:249], v[248:249], s[86:87] op_sel_hi:[1,0]
	v_exp_f32_e32 v242, v242
	v_exp_f32_e32 v243, v243
	v_exp_f32_e32 v244, v244
	v_exp_f32_e32 v245, v245
	v_exp_f32_e32 v246, v246
	v_exp_f32_e32 v247, v247
	v_exp_f32_e32 v248, v248
	v_exp_f32_e32 v249, v249
	v_pk_add_f32 v[242:243], v[242:243], 1.0 op_sel_hi:[1,0]
	v_pk_add_f32 v[244:245], v[244:245], 1.0 op_sel_hi:[1,0]
	v_pk_add_f32 v[246:247], v[246:247], 1.0 op_sel_hi:[1,0]
	v_pk_add_f32 v[248:249], v[248:249], 1.0 op_sel_hi:[1,0]
	v_pk_mul_f32 v[216:217], v[216:217], v[242:243]
	v_pk_mul_f32 v[218:219], v[218:219], v[244:245]
	v_pk_mul_f32 v[220:221], v[220:221], v[246:247]
	v_pk_mul_f32 v[222:223], v[222:223], v[248:249]
	v_pk_mul_f32 v[110:111], v[110:111], v[216:217]
	v_pk_mul_f32 v[112:113], v[112:113], v[218:219]
	v_pk_mul_f32 v[106:107], v[106:107], v[220:221]
	v_pk_mul_f32 v[108:109], v[108:109], v[222:223]
	v_lshlrev_b32_e32 v216, 16, v170
	v_and_b32_e32 v217, 0xffff0000, v170
	v_lshlrev_b32_e32 v218, 16, v171
	v_and_b32_e32 v219, 0xffff0000, v171
	v_lshlrev_b32_e32 v220, 16, v172
	v_and_b32_e32 v221, 0xffff0000, v172
	v_lshlrev_b32_e32 v222, 16, v173
	v_and_b32_e32 v223, 0xffff0000, v173
	v_pk_mul_f32 v[216:217], v[216:217], s[86:87] op_sel_hi:[1,0]
	v_pk_mul_f32 v[218:219], v[218:219], s[86:87] op_sel_hi:[1,0]
	v_pk_mul_f32 v[220:221], v[220:221], s[86:87] op_sel_hi:[1,0]
	v_pk_mul_f32 v[222:223], v[222:223], s[86:87] op_sel_hi:[1,0]
	v_exp_f32_e32 v216, v216
	v_exp_f32_e32 v217, v217
	v_exp_f32_e32 v218, v218
	v_exp_f32_e32 v219, v219
	v_exp_f32_e32 v220, v220
	v_exp_f32_e32 v221, v221
	v_exp_f32_e32 v222, v222
	v_exp_f32_e32 v223, v223
	v_pk_add_f32 v[216:217], v[216:217], 1.0 op_sel_hi:[1,0]
	v_pk_add_f32 v[218:219], v[218:219], 1.0 op_sel_hi:[1,0]
	v_pk_add_f32 v[220:221], v[220:221], 1.0 op_sel_hi:[1,0]
	v_pk_add_f32 v[222:223], v[222:223], 1.0 op_sel_hi:[1,0]
	v_rcp_f32_e32 v216, v216
	v_rcp_f32_e32 v217, v217
	v_rcp_f32_e32 v218, v218
	v_rcp_f32_e32 v219, v219
	v_rcp_f32_e32 v220, v220
	v_rcp_f32_e32 v221, v221
	v_rcp_f32_e32 v222, v222
	v_rcp_f32_e32 v223, v223
	v_lshlrev_b32_e32 v242, 16, v174
	v_and_b32_e32 v243, 0xffff0000, v174
	v_lshlrev_b32_e32 v244, 16, v175
	v_and_b32_e32 v245, 0xffff0000, v175
	v_lshlrev_b32_e32 v246, 16, v176
	v_and_b32_e32 v247, 0xffff0000, v176
	v_lshlrev_b32_e32 v248, 16, v177
	v_and_b32_e32 v249, 0xffff0000, v177
	v_pk_mul_f32 v[242:243], v[242:243], s[86:87] op_sel_hi:[1,0]
	v_pk_mul_f32 v[244:245], v[244:245], s[86:87] op_sel_hi:[1,0]
	v_pk_mul_f32 v[246:247], v[246:247], s[86:87] op_sel_hi:[1,0]
	v_pk_mul_f32 v[248:249], v[248:249], s[86:87] op_sel_hi:[1,0]
	v_exp_f32_e32 v242, v242
	v_exp_f32_e32 v243, v243
	v_exp_f32_e32 v244, v244
	v_exp_f32_e32 v245, v245
	v_exp_f32_e32 v246, v246
	v_exp_f32_e32 v247, v247
	v_exp_f32_e32 v248, v248
	v_exp_f32_e32 v249, v249
	v_pk_add_f32 v[242:243], v[242:243], 1.0 op_sel_hi:[1,0]
	v_pk_add_f32 v[244:245], v[244:245], 1.0 op_sel_hi:[1,0]
	v_pk_add_f32 v[246:247], v[246:247], 1.0 op_sel_hi:[1,0]
	v_pk_add_f32 v[248:249], v[248:249], 1.0 op_sel_hi:[1,0]
	v_pk_mul_f32 v[216:217], v[216:217], v[242:243]
	v_pk_mul_f32 v[218:219], v[218:219], v[244:245]
	v_pk_mul_f32 v[220:221], v[220:221], v[246:247]
	v_pk_mul_f32 v[222:223], v[222:223], v[248:249]
	v_pk_mul_f32 v[78:79], v[78:79], v[216:217]
	v_pk_mul_f32 v[80:81], v[80:81], v[218:219]
	v_pk_mul_f32 v[74:75], v[74:75], v[220:221]
	v_pk_mul_f32 v[76:77], v[76:77], v[222:223]
	s_add_u32 s28, s20, 0x410000
	s_addc_u32 s29, s21, 0
	global_load_dwordx4 v[162:165], v253, s[28:29]
	global_load_dwordx4 v[166:169], v254, s[28:29]
	global_load_dwordx4 v[170:173], v253, s[28:29] offset:256
	global_load_dwordx4 v[174:177], v254, s[28:29] offset:256
	s_waitcnt vmcnt(12)
	v_lshlrev_b32_e32 v216, 16, v178
	v_and_b32_e32 v217, 0xffff0000, v178
	v_lshlrev_b32_e32 v218, 16, v179
	v_and_b32_e32 v219, 0xffff0000, v179
	v_lshlrev_b32_e32 v220, 16, v180
	v_and_b32_e32 v221, 0xffff0000, v180
	v_lshlrev_b32_e32 v222, 16, v181
	v_and_b32_e32 v223, 0xffff0000, v181
	v_pk_mul_f32 v[216:217], v[216:217], s[86:87] op_sel_hi:[1,0]
	v_pk_mul_f32 v[218:219], v[218:219], s[86:87] op_sel_hi:[1,0]
	v_pk_mul_f32 v[220:221], v[220:221], s[86:87] op_sel_hi:[1,0]
	v_pk_mul_f32 v[222:223], v[222:223], s[86:87] op_sel_hi:[1,0]
	v_exp_f32_e32 v216, v216
	v_exp_f32_e32 v217, v217
	v_exp_f32_e32 v218, v218
	v_exp_f32_e32 v219, v219
	v_exp_f32_e32 v220, v220
	v_exp_f32_e32 v221, v221
	v_exp_f32_e32 v222, v222
	v_exp_f32_e32 v223, v223
	v_pk_add_f32 v[216:217], v[216:217], 1.0 op_sel_hi:[1,0]
	v_pk_add_f32 v[218:219], v[218:219], 1.0 op_sel_hi:[1,0]
	v_pk_add_f32 v[220:221], v[220:221], 1.0 op_sel_hi:[1,0]
	v_pk_add_f32 v[222:223], v[222:223], 1.0 op_sel_hi:[1,0]
	v_rcp_f32_e32 v216, v216
	v_rcp_f32_e32 v217, v217
	v_rcp_f32_e32 v218, v218
	v_rcp_f32_e32 v219, v219
	v_rcp_f32_e32 v220, v220
	v_rcp_f32_e32 v221, v221
	v_rcp_f32_e32 v222, v222
	v_rcp_f32_e32 v223, v223
	v_lshlrev_b32_e32 v242, 16, v182
	v_and_b32_e32 v243, 0xffff0000, v182
	v_lshlrev_b32_e32 v244, 16, v183
	v_and_b32_e32 v245, 0xffff0000, v183
	v_lshlrev_b32_e32 v246, 16, v184
	v_and_b32_e32 v247, 0xffff0000, v184
	v_lshlrev_b32_e32 v248, 16, v185
	v_and_b32_e32 v249, 0xffff0000, v185
	v_pk_mul_f32 v[242:243], v[242:243], s[86:87] op_sel_hi:[1,0]
	v_pk_mul_f32 v[244:245], v[244:245], s[86:87] op_sel_hi:[1,0]
	v_pk_mul_f32 v[246:247], v[246:247], s[86:87] op_sel_hi:[1,0]
	v_pk_mul_f32 v[248:249], v[248:249], s[86:87] op_sel_hi:[1,0]
	v_exp_f32_e32 v242, v242
	v_exp_f32_e32 v243, v243
	v_exp_f32_e32 v244, v244
	v_exp_f32_e32 v245, v245
	v_exp_f32_e32 v246, v246
	v_exp_f32_e32 v247, v247
	v_exp_f32_e32 v248, v248
	v_exp_f32_e32 v249, v249
	v_pk_add_f32 v[242:243], v[242:243], 1.0 op_sel_hi:[1,0]
	v_pk_add_f32 v[244:245], v[244:245], 1.0 op_sel_hi:[1,0]
	v_pk_add_f32 v[246:247], v[246:247], 1.0 op_sel_hi:[1,0]
	v_pk_add_f32 v[248:249], v[248:249], 1.0 op_sel_hi:[1,0]
	v_pk_mul_f32 v[216:217], v[216:217], v[242:243]
	v_pk_mul_f32 v[218:219], v[218:219], v[244:245]
	v_pk_mul_f32 v[220:221], v[220:221], v[246:247]
	v_pk_mul_f32 v[222:223], v[222:223], v[248:249]
	v_pk_mul_f32 v[102:103], v[102:103], v[216:217]
	v_pk_mul_f32 v[104:105], v[104:105], v[218:219]
	v_pk_mul_f32 v[98:99], v[98:99], v[220:221]
	v_pk_mul_f32 v[100:101], v[100:101], v[222:223]
	v_lshlrev_b32_e32 v216, 16, v186
	v_and_b32_e32 v217, 0xffff0000, v186
	v_lshlrev_b32_e32 v218, 16, v187
	v_and_b32_e32 v219, 0xffff0000, v187
	v_lshlrev_b32_e32 v220, 16, v188
	v_and_b32_e32 v221, 0xffff0000, v188
	v_lshlrev_b32_e32 v222, 16, v189
	v_and_b32_e32 v223, 0xffff0000, v189
	v_pk_mul_f32 v[216:217], v[216:217], s[86:87] op_sel_hi:[1,0]
	v_pk_mul_f32 v[218:219], v[218:219], s[86:87] op_sel_hi:[1,0]
	v_pk_mul_f32 v[220:221], v[220:221], s[86:87] op_sel_hi:[1,0]
	v_pk_mul_f32 v[222:223], v[222:223], s[86:87] op_sel_hi:[1,0]
	v_exp_f32_e32 v216, v216
	v_exp_f32_e32 v217, v217
	v_exp_f32_e32 v218, v218
	v_exp_f32_e32 v219, v219
	v_exp_f32_e32 v220, v220
	v_exp_f32_e32 v221, v221
	v_exp_f32_e32 v222, v222
	v_exp_f32_e32 v223, v223
	v_pk_add_f32 v[216:217], v[216:217], 1.0 op_sel_hi:[1,0]
	v_pk_add_f32 v[218:219], v[218:219], 1.0 op_sel_hi:[1,0]
	v_pk_add_f32 v[220:221], v[220:221], 1.0 op_sel_hi:[1,0]
	v_pk_add_f32 v[222:223], v[222:223], 1.0 op_sel_hi:[1,0]
	v_rcp_f32_e32 v216, v216
	v_rcp_f32_e32 v217, v217
	v_rcp_f32_e32 v218, v218
	v_rcp_f32_e32 v219, v219
	v_rcp_f32_e32 v220, v220
	v_rcp_f32_e32 v221, v221
	v_rcp_f32_e32 v222, v222
	v_rcp_f32_e32 v223, v223
	v_lshlrev_b32_e32 v242, 16, v190
	v_and_b32_e32 v243, 0xffff0000, v190
	v_lshlrev_b32_e32 v244, 16, v191
	v_and_b32_e32 v245, 0xffff0000, v191
	v_lshlrev_b32_e32 v246, 16, v192
	v_and_b32_e32 v247, 0xffff0000, v192
	v_lshlrev_b32_e32 v248, 16, v193
	v_and_b32_e32 v249, 0xffff0000, v193
	v_pk_mul_f32 v[242:243], v[242:243], s[86:87] op_sel_hi:[1,0]
	v_pk_mul_f32 v[244:245], v[244:245], s[86:87] op_sel_hi:[1,0]
	v_pk_mul_f32 v[246:247], v[246:247], s[86:87] op_sel_hi:[1,0]
	v_pk_mul_f32 v[248:249], v[248:249], s[86:87] op_sel_hi:[1,0]
	v_exp_f32_e32 v242, v242
	v_exp_f32_e32 v243, v243
	v_exp_f32_e32 v244, v244
	v_exp_f32_e32 v245, v245
	v_exp_f32_e32 v246, v246
	v_exp_f32_e32 v247, v247
	v_exp_f32_e32 v248, v248
	v_exp_f32_e32 v249, v249
	v_pk_add_f32 v[242:243], v[242:243], 1.0 op_sel_hi:[1,0]
	v_pk_add_f32 v[244:245], v[244:245], 1.0 op_sel_hi:[1,0]
	v_pk_add_f32 v[246:247], v[246:247], 1.0 op_sel_hi:[1,0]
	v_pk_add_f32 v[248:249], v[248:249], 1.0 op_sel_hi:[1,0]
	v_pk_mul_f32 v[216:217], v[216:217], v[242:243]
	v_pk_mul_f32 v[218:219], v[218:219], v[244:245]
	v_pk_mul_f32 v[220:221], v[220:221], v[246:247]
	v_pk_mul_f32 v[222:223], v[222:223], v[248:249]
	v_pk_mul_f32 v[70:71], v[70:71], v[216:217]
	v_pk_mul_f32 v[72:73], v[72:73], v[218:219]
	v_pk_mul_f32 v[66:67], v[66:67], v[220:221]
	v_pk_mul_f32 v[68:69], v[68:69], v[222:223]
	s_add_u32 s28, s20, 0x478000
	s_addc_u32 s29, s21, 0
	global_load_dwordx4 v[178:181], v253, s[28:29]
	global_load_dwordx4 v[182:185], v254, s[28:29]
	global_load_dwordx4 v[186:189], v253, s[28:29] offset:256
	global_load_dwordx4 v[190:193], v254, s[28:29] offset:256
	s_waitcnt vmcnt(12)
	v_lshlrev_b32_e32 v216, 16, v130
	v_and_b32_e32 v217, 0xffff0000, v130
	v_lshlrev_b32_e32 v218, 16, v131
	v_and_b32_e32 v219, 0xffff0000, v131
	v_lshlrev_b32_e32 v220, 16, v132
	v_and_b32_e32 v221, 0xffff0000, v132
	v_lshlrev_b32_e32 v222, 16, v133
	v_and_b32_e32 v223, 0xffff0000, v133
	v_pk_mul_f32 v[216:217], v[216:217], s[86:87] op_sel_hi:[1,0]
	v_pk_mul_f32 v[218:219], v[218:219], s[86:87] op_sel_hi:[1,0]
	v_pk_mul_f32 v[220:221], v[220:221], s[86:87] op_sel_hi:[1,0]
	v_pk_mul_f32 v[222:223], v[222:223], s[86:87] op_sel_hi:[1,0]
	v_exp_f32_e32 v216, v216
	v_exp_f32_e32 v217, v217
	v_exp_f32_e32 v218, v218
	v_exp_f32_e32 v219, v219
	v_exp_f32_e32 v220, v220
	v_exp_f32_e32 v221, v221
	v_exp_f32_e32 v222, v222
	v_exp_f32_e32 v223, v223
	v_pk_add_f32 v[216:217], v[216:217], 1.0 op_sel_hi:[1,0]
	v_pk_add_f32 v[218:219], v[218:219], 1.0 op_sel_hi:[1,0]
	v_pk_add_f32 v[220:221], v[220:221], 1.0 op_sel_hi:[1,0]
	v_pk_add_f32 v[222:223], v[222:223], 1.0 op_sel_hi:[1,0]
	v_rcp_f32_e32 v216, v216
	v_rcp_f32_e32 v217, v217
	v_rcp_f32_e32 v218, v218
	v_rcp_f32_e32 v219, v219
	v_rcp_f32_e32 v220, v220
	v_rcp_f32_e32 v221, v221
	v_rcp_f32_e32 v222, v222
	v_rcp_f32_e32 v223, v223
	v_lshlrev_b32_e32 v242, 16, v134
	v_and_b32_e32 v243, 0xffff0000, v134
	v_lshlrev_b32_e32 v244, 16, v135
	v_and_b32_e32 v245, 0xffff0000, v135
	v_lshlrev_b32_e32 v246, 16, v136
	v_and_b32_e32 v247, 0xffff0000, v136
	v_lshlrev_b32_e32 v248, 16, v137
	v_and_b32_e32 v249, 0xffff0000, v137
	v_pk_mul_f32 v[242:243], v[242:243], s[86:87] op_sel_hi:[1,0]
	v_pk_mul_f32 v[244:245], v[244:245], s[86:87] op_sel_hi:[1,0]
	v_pk_mul_f32 v[246:247], v[246:247], s[86:87] op_sel_hi:[1,0]
	v_pk_mul_f32 v[248:249], v[248:249], s[86:87] op_sel_hi:[1,0]
	v_exp_f32_e32 v242, v242
	v_exp_f32_e32 v243, v243
	v_exp_f32_e32 v244, v244
	v_exp_f32_e32 v245, v245
	v_exp_f32_e32 v246, v246
	v_exp_f32_e32 v247, v247
	v_exp_f32_e32 v248, v248
	v_exp_f32_e32 v249, v249
	v_pk_add_f32 v[242:243], v[242:243], 1.0 op_sel_hi:[1,0]
	v_pk_add_f32 v[244:245], v[244:245], 1.0 op_sel_hi:[1,0]
	v_pk_add_f32 v[246:247], v[246:247], 1.0 op_sel_hi:[1,0]
	v_pk_add_f32 v[248:249], v[248:249], 1.0 op_sel_hi:[1,0]
	v_pk_mul_f32 v[216:217], v[216:217], v[242:243]
	v_pk_mul_f32 v[218:219], v[218:219], v[244:245]
	v_pk_mul_f32 v[220:221], v[220:221], v[246:247]
	v_pk_mul_f32 v[222:223], v[222:223], v[248:249]
	v_pk_mul_f32 v[62:63], v[62:63], v[216:217]
	v_pk_mul_f32 v[64:65], v[64:65], v[218:219]
	v_pk_mul_f32 v[58:59], v[58:59], v[220:221]
	v_pk_mul_f32 v[60:61], v[60:61], v[222:223]
	v_lshlrev_b32_e32 v216, 16, v138
	v_and_b32_e32 v217, 0xffff0000, v138
	v_lshlrev_b32_e32 v218, 16, v139
	v_and_b32_e32 v219, 0xffff0000, v139
	v_lshlrev_b32_e32 v220, 16, v140
	v_and_b32_e32 v221, 0xffff0000, v140
	v_lshlrev_b32_e32 v222, 16, v141
	v_and_b32_e32 v223, 0xffff0000, v141
	v_pk_mul_f32 v[216:217], v[216:217], s[86:87] op_sel_hi:[1,0]
	v_pk_mul_f32 v[218:219], v[218:219], s[86:87] op_sel_hi:[1,0]
	v_pk_mul_f32 v[220:221], v[220:221], s[86:87] op_sel_hi:[1,0]
	v_pk_mul_f32 v[222:223], v[222:223], s[86:87] op_sel_hi:[1,0]
	v_exp_f32_e32 v216, v216
	v_exp_f32_e32 v217, v217
	v_exp_f32_e32 v218, v218
	v_exp_f32_e32 v219, v219
	v_exp_f32_e32 v220, v220
	v_exp_f32_e32 v221, v221
	v_exp_f32_e32 v222, v222
	v_exp_f32_e32 v223, v223
	v_pk_add_f32 v[216:217], v[216:217], 1.0 op_sel_hi:[1,0]
	v_pk_add_f32 v[218:219], v[218:219], 1.0 op_sel_hi:[1,0]
	v_pk_add_f32 v[220:221], v[220:221], 1.0 op_sel_hi:[1,0]
	v_pk_add_f32 v[222:223], v[222:223], 1.0 op_sel_hi:[1,0]
	v_rcp_f32_e32 v216, v216
	v_rcp_f32_e32 v217, v217
	v_rcp_f32_e32 v218, v218
	v_rcp_f32_e32 v219, v219
	v_rcp_f32_e32 v220, v220
	v_rcp_f32_e32 v221, v221
	v_rcp_f32_e32 v222, v222
	v_rcp_f32_e32 v223, v223
	v_lshlrev_b32_e32 v242, 16, v142
	v_and_b32_e32 v243, 0xffff0000, v142
	v_lshlrev_b32_e32 v244, 16, v143
	v_and_b32_e32 v245, 0xffff0000, v143
	v_lshlrev_b32_e32 v246, 16, v144
	v_and_b32_e32 v247, 0xffff0000, v144
	v_lshlrev_b32_e32 v248, 16, v145
	v_and_b32_e32 v249, 0xffff0000, v145
	v_pk_mul_f32 v[242:243], v[242:243], s[86:87] op_sel_hi:[1,0]
	v_pk_mul_f32 v[244:245], v[244:245], s[86:87] op_sel_hi:[1,0]
	v_pk_mul_f32 v[246:247], v[246:247], s[86:87] op_sel_hi:[1,0]
	v_pk_mul_f32 v[248:249], v[248:249], s[86:87] op_sel_hi:[1,0]
	v_exp_f32_e32 v242, v242
	v_exp_f32_e32 v243, v243
	v_exp_f32_e32 v244, v244
	v_exp_f32_e32 v245, v245
	v_exp_f32_e32 v246, v246
	v_exp_f32_e32 v247, v247
	v_exp_f32_e32 v248, v248
	v_exp_f32_e32 v249, v249
	v_pk_add_f32 v[242:243], v[242:243], 1.0 op_sel_hi:[1,0]
	v_pk_add_f32 v[244:245], v[244:245], 1.0 op_sel_hi:[1,0]
	v_pk_add_f32 v[246:247], v[246:247], 1.0 op_sel_hi:[1,0]
	v_pk_add_f32 v[248:249], v[248:249], 1.0 op_sel_hi:[1,0]
	v_pk_mul_f32 v[216:217], v[216:217], v[242:243]
	v_pk_mul_f32 v[218:219], v[218:219], v[244:245]
	v_pk_mul_f32 v[220:221], v[220:221], v[246:247]
	v_pk_mul_f32 v[222:223], v[222:223], v[248:249]
	v_pk_mul_f32 v[30:31], v[30:31], v[216:217]
	v_pk_mul_f32 v[32:33], v[32:33], v[218:219]
	v_pk_mul_f32 v[26:27], v[26:27], v[220:221]
	v_pk_mul_f32 v[28:29], v[28:29], v[222:223]
	s_waitcnt vmcnt(8)
	v_lshlrev_b32_e32 v216, 16, v146
	v_and_b32_e32 v217, 0xffff0000, v146
	v_lshlrev_b32_e32 v218, 16, v147
	v_and_b32_e32 v219, 0xffff0000, v147
	v_lshlrev_b32_e32 v220, 16, v148
	v_and_b32_e32 v221, 0xffff0000, v148
	v_lshlrev_b32_e32 v222, 16, v149
	v_and_b32_e32 v223, 0xffff0000, v149
	v_pk_mul_f32 v[216:217], v[216:217], s[86:87] op_sel_hi:[1,0]
	v_pk_mul_f32 v[218:219], v[218:219], s[86:87] op_sel_hi:[1,0]
	v_pk_mul_f32 v[220:221], v[220:221], s[86:87] op_sel_hi:[1,0]
	v_pk_mul_f32 v[222:223], v[222:223], s[86:87] op_sel_hi:[1,0]
	v_exp_f32_e32 v216, v216
	v_exp_f32_e32 v217, v217
	v_exp_f32_e32 v218, v218
	v_exp_f32_e32 v219, v219
	v_exp_f32_e32 v220, v220
	v_exp_f32_e32 v221, v221
	v_exp_f32_e32 v222, v222
	v_exp_f32_e32 v223, v223
	v_pk_add_f32 v[216:217], v[216:217], 1.0 op_sel_hi:[1,0]
	v_pk_add_f32 v[218:219], v[218:219], 1.0 op_sel_hi:[1,0]
	v_pk_add_f32 v[220:221], v[220:221], 1.0 op_sel_hi:[1,0]
	v_pk_add_f32 v[222:223], v[222:223], 1.0 op_sel_hi:[1,0]
	v_rcp_f32_e32 v216, v216
	v_rcp_f32_e32 v217, v217
	v_rcp_f32_e32 v218, v218
	v_rcp_f32_e32 v219, v219
	v_rcp_f32_e32 v220, v220
	v_rcp_f32_e32 v221, v221
	v_rcp_f32_e32 v222, v222
	v_rcp_f32_e32 v223, v223
	v_lshlrev_b32_e32 v242, 16, v150
	v_and_b32_e32 v243, 0xffff0000, v150
	v_lshlrev_b32_e32 v244, 16, v151
	v_and_b32_e32 v245, 0xffff0000, v151
	v_lshlrev_b32_e32 v246, 16, v152
	v_and_b32_e32 v247, 0xffff0000, v152
	v_lshlrev_b32_e32 v248, 16, v153
	v_and_b32_e32 v249, 0xffff0000, v153
	v_pk_mul_f32 v[242:243], v[242:243], s[86:87] op_sel_hi:[1,0]
	v_pk_mul_f32 v[244:245], v[244:245], s[86:87] op_sel_hi:[1,0]
	v_pk_mul_f32 v[246:247], v[246:247], s[86:87] op_sel_hi:[1,0]
	v_pk_mul_f32 v[248:249], v[248:249], s[86:87] op_sel_hi:[1,0]
	v_exp_f32_e32 v242, v242
	v_exp_f32_e32 v243, v243
	v_exp_f32_e32 v244, v244
	v_exp_f32_e32 v245, v245
	v_exp_f32_e32 v246, v246
	v_exp_f32_e32 v247, v247
	v_exp_f32_e32 v248, v248
	v_exp_f32_e32 v249, v249
	v_pk_add_f32 v[242:243], v[242:243], 1.0 op_sel_hi:[1,0]
	v_pk_add_f32 v[244:245], v[244:245], 1.0 op_sel_hi:[1,0]
	v_pk_add_f32 v[246:247], v[246:247], 1.0 op_sel_hi:[1,0]
	v_pk_add_f32 v[248:249], v[248:249], 1.0 op_sel_hi:[1,0]
	v_pk_mul_f32 v[216:217], v[216:217], v[242:243]
	v_pk_mul_f32 v[218:219], v[218:219], v[244:245]
	v_pk_mul_f32 v[220:221], v[220:221], v[246:247]
	v_pk_mul_f32 v[222:223], v[222:223], v[248:249]
	v_pk_mul_f32 v[54:55], v[54:55], v[216:217]
	v_pk_mul_f32 v[56:57], v[56:57], v[218:219]
	v_pk_mul_f32 v[50:51], v[50:51], v[220:221]
	v_pk_mul_f32 v[52:53], v[52:53], v[222:223]
	v_lshlrev_b32_e32 v216, 16, v154
	v_and_b32_e32 v217, 0xffff0000, v154
	v_lshlrev_b32_e32 v218, 16, v155
	v_and_b32_e32 v219, 0xffff0000, v155
	v_lshlrev_b32_e32 v220, 16, v156
	v_and_b32_e32 v221, 0xffff0000, v156
	v_lshlrev_b32_e32 v222, 16, v157
	v_and_b32_e32 v223, 0xffff0000, v157
	v_pk_mul_f32 v[216:217], v[216:217], s[86:87] op_sel_hi:[1,0]
	v_pk_mul_f32 v[218:219], v[218:219], s[86:87] op_sel_hi:[1,0]
	v_pk_mul_f32 v[220:221], v[220:221], s[86:87] op_sel_hi:[1,0]
	v_pk_mul_f32 v[222:223], v[222:223], s[86:87] op_sel_hi:[1,0]
	v_exp_f32_e32 v216, v216
	v_exp_f32_e32 v217, v217
	v_exp_f32_e32 v218, v218
	v_exp_f32_e32 v219, v219
	v_exp_f32_e32 v220, v220
	v_exp_f32_e32 v221, v221
	v_exp_f32_e32 v222, v222
	v_exp_f32_e32 v223, v223
	v_pk_add_f32 v[216:217], v[216:217], 1.0 op_sel_hi:[1,0]
	v_pk_add_f32 v[218:219], v[218:219], 1.0 op_sel_hi:[1,0]
	v_pk_add_f32 v[220:221], v[220:221], 1.0 op_sel_hi:[1,0]
	v_pk_add_f32 v[222:223], v[222:223], 1.0 op_sel_hi:[1,0]
	v_rcp_f32_e32 v216, v216
	v_rcp_f32_e32 v217, v217
	v_rcp_f32_e32 v218, v218
	v_rcp_f32_e32 v219, v219
	v_rcp_f32_e32 v220, v220
	v_rcp_f32_e32 v221, v221
	v_rcp_f32_e32 v222, v222
	v_rcp_f32_e32 v223, v223
	v_lshlrev_b32_e32 v242, 16, v158
	v_and_b32_e32 v243, 0xffff0000, v158
	v_lshlrev_b32_e32 v244, 16, v159
	v_and_b32_e32 v245, 0xffff0000, v159
	v_lshlrev_b32_e32 v246, 16, v160
	v_and_b32_e32 v247, 0xffff0000, v160
	v_lshlrev_b32_e32 v248, 16, v161
	v_and_b32_e32 v249, 0xffff0000, v161
	v_pk_mul_f32 v[242:243], v[242:243], s[86:87] op_sel_hi:[1,0]
	v_pk_mul_f32 v[244:245], v[244:245], s[86:87] op_sel_hi:[1,0]
	v_pk_mul_f32 v[246:247], v[246:247], s[86:87] op_sel_hi:[1,0]
	v_pk_mul_f32 v[248:249], v[248:249], s[86:87] op_sel_hi:[1,0]
	v_exp_f32_e32 v242, v242
	v_exp_f32_e32 v243, v243
	v_exp_f32_e32 v244, v244
	v_exp_f32_e32 v245, v245
	v_exp_f32_e32 v246, v246
	v_exp_f32_e32 v247, v247
	v_exp_f32_e32 v248, v248
	v_exp_f32_e32 v249, v249
	v_pk_add_f32 v[242:243], v[242:243], 1.0 op_sel_hi:[1,0]
	v_pk_add_f32 v[244:245], v[244:245], 1.0 op_sel_hi:[1,0]
	v_pk_add_f32 v[246:247], v[246:247], 1.0 op_sel_hi:[1,0]
	v_pk_add_f32 v[248:249], v[248:249], 1.0 op_sel_hi:[1,0]
	v_pk_mul_f32 v[216:217], v[216:217], v[242:243]
	v_pk_mul_f32 v[218:219], v[218:219], v[244:245]
	v_pk_mul_f32 v[220:221], v[220:221], v[246:247]
	v_pk_mul_f32 v[222:223], v[222:223], v[248:249]
	v_pk_mul_f32 v[22:23], v[22:23], v[216:217]
	v_pk_mul_f32 v[24:25], v[24:25], v[218:219]
	v_pk_mul_f32 v[18:19], v[18:19], v[220:221]
	v_pk_mul_f32 v[20:21], v[20:21], v[222:223]
	s_waitcnt vmcnt(4)
	v_lshlrev_b32_e32 v216, 16, v162
	v_and_b32_e32 v217, 0xffff0000, v162
	v_lshlrev_b32_e32 v218, 16, v163
	v_and_b32_e32 v219, 0xffff0000, v163
	v_lshlrev_b32_e32 v220, 16, v164
	v_and_b32_e32 v221, 0xffff0000, v164
	v_lshlrev_b32_e32 v222, 16, v165
	v_and_b32_e32 v223, 0xffff0000, v165
	v_pk_mul_f32 v[216:217], v[216:217], s[86:87] op_sel_hi:[1,0]
	v_pk_mul_f32 v[218:219], v[218:219], s[86:87] op_sel_hi:[1,0]
	v_pk_mul_f32 v[220:221], v[220:221], s[86:87] op_sel_hi:[1,0]
	v_pk_mul_f32 v[222:223], v[222:223], s[86:87] op_sel_hi:[1,0]
	v_exp_f32_e32 v216, v216
	v_exp_f32_e32 v217, v217
	v_exp_f32_e32 v218, v218
	v_exp_f32_e32 v219, v219
	v_exp_f32_e32 v220, v220
	v_exp_f32_e32 v221, v221
	v_exp_f32_e32 v222, v222
	v_exp_f32_e32 v223, v223
	v_pk_add_f32 v[216:217], v[216:217], 1.0 op_sel_hi:[1,0]
	v_pk_add_f32 v[218:219], v[218:219], 1.0 op_sel_hi:[1,0]
	v_pk_add_f32 v[220:221], v[220:221], 1.0 op_sel_hi:[1,0]
	v_pk_add_f32 v[222:223], v[222:223], 1.0 op_sel_hi:[1,0]
	v_rcp_f32_e32 v216, v216
	v_rcp_f32_e32 v217, v217
	v_rcp_f32_e32 v218, v218
	v_rcp_f32_e32 v219, v219
	v_rcp_f32_e32 v220, v220
	v_rcp_f32_e32 v221, v221
	v_rcp_f32_e32 v222, v222
	v_rcp_f32_e32 v223, v223
	v_lshlrev_b32_e32 v242, 16, v166
	v_and_b32_e32 v243, 0xffff0000, v166
	v_lshlrev_b32_e32 v244, 16, v167
	v_and_b32_e32 v245, 0xffff0000, v167
	v_lshlrev_b32_e32 v246, 16, v168
	v_and_b32_e32 v247, 0xffff0000, v168
	v_lshlrev_b32_e32 v248, 16, v169
	v_and_b32_e32 v249, 0xffff0000, v169
	v_pk_mul_f32 v[242:243], v[242:243], s[86:87] op_sel_hi:[1,0]
	v_pk_mul_f32 v[244:245], v[244:245], s[86:87] op_sel_hi:[1,0]
	v_pk_mul_f32 v[246:247], v[246:247], s[86:87] op_sel_hi:[1,0]
	v_pk_mul_f32 v[248:249], v[248:249], s[86:87] op_sel_hi:[1,0]
	v_exp_f32_e32 v242, v242
	v_exp_f32_e32 v243, v243
	v_exp_f32_e32 v244, v244
	v_exp_f32_e32 v245, v245
	v_exp_f32_e32 v246, v246
	v_exp_f32_e32 v247, v247
	v_exp_f32_e32 v248, v248
	v_exp_f32_e32 v249, v249
	v_pk_add_f32 v[242:243], v[242:243], 1.0 op_sel_hi:[1,0]
	v_pk_add_f32 v[244:245], v[244:245], 1.0 op_sel_hi:[1,0]
	v_pk_add_f32 v[246:247], v[246:247], 1.0 op_sel_hi:[1,0]
	v_pk_add_f32 v[248:249], v[248:249], 1.0 op_sel_hi:[1,0]
	v_pk_mul_f32 v[216:217], v[216:217], v[242:243]
	v_pk_mul_f32 v[218:219], v[218:219], v[244:245]
	v_pk_mul_f32 v[220:221], v[220:221], v[246:247]
	v_pk_mul_f32 v[222:223], v[222:223], v[248:249]
	v_pk_mul_f32 v[46:47], v[46:47], v[216:217]
	v_pk_mul_f32 v[48:49], v[48:49], v[218:219]
	v_pk_mul_f32 v[42:43], v[42:43], v[220:221]
	v_pk_mul_f32 v[44:45], v[44:45], v[222:223]
	v_lshlrev_b32_e32 v216, 16, v170
	v_and_b32_e32 v217, 0xffff0000, v170
	v_lshlrev_b32_e32 v218, 16, v171
	v_and_b32_e32 v219, 0xffff0000, v171
	v_lshlrev_b32_e32 v220, 16, v172
	v_and_b32_e32 v221, 0xffff0000, v172
	v_lshlrev_b32_e32 v222, 16, v173
	v_and_b32_e32 v223, 0xffff0000, v173
	v_pk_mul_f32 v[216:217], v[216:217], s[86:87] op_sel_hi:[1,0]
	v_pk_mul_f32 v[218:219], v[218:219], s[86:87] op_sel_hi:[1,0]
	v_pk_mul_f32 v[220:221], v[220:221], s[86:87] op_sel_hi:[1,0]
	v_pk_mul_f32 v[222:223], v[222:223], s[86:87] op_sel_hi:[1,0]
	v_exp_f32_e32 v216, v216
	v_exp_f32_e32 v217, v217
	v_exp_f32_e32 v218, v218
	v_exp_f32_e32 v219, v219
	v_exp_f32_e32 v220, v220
	v_exp_f32_e32 v221, v221
	v_exp_f32_e32 v222, v222
	v_exp_f32_e32 v223, v223
	v_pk_add_f32 v[216:217], v[216:217], 1.0 op_sel_hi:[1,0]
	v_pk_add_f32 v[218:219], v[218:219], 1.0 op_sel_hi:[1,0]
	v_pk_add_f32 v[220:221], v[220:221], 1.0 op_sel_hi:[1,0]
	v_pk_add_f32 v[222:223], v[222:223], 1.0 op_sel_hi:[1,0]
	v_rcp_f32_e32 v216, v216
	v_rcp_f32_e32 v217, v217
	v_rcp_f32_e32 v218, v218
	v_rcp_f32_e32 v219, v219
	v_rcp_f32_e32 v220, v220
	v_rcp_f32_e32 v221, v221
	v_rcp_f32_e32 v222, v222
	v_rcp_f32_e32 v223, v223
	v_lshlrev_b32_e32 v242, 16, v174
	v_and_b32_e32 v243, 0xffff0000, v174
	v_lshlrev_b32_e32 v244, 16, v175
	v_and_b32_e32 v245, 0xffff0000, v175
	v_lshlrev_b32_e32 v246, 16, v176
	v_and_b32_e32 v247, 0xffff0000, v176
	v_lshlrev_b32_e32 v248, 16, v177
	v_and_b32_e32 v249, 0xffff0000, v177
	v_pk_mul_f32 v[242:243], v[242:243], s[86:87] op_sel_hi:[1,0]
	v_pk_mul_f32 v[244:245], v[244:245], s[86:87] op_sel_hi:[1,0]
	v_pk_mul_f32 v[246:247], v[246:247], s[86:87] op_sel_hi:[1,0]
	v_pk_mul_f32 v[248:249], v[248:249], s[86:87] op_sel_hi:[1,0]
	v_exp_f32_e32 v242, v242
	v_exp_f32_e32 v243, v243
	v_exp_f32_e32 v244, v244
	v_exp_f32_e32 v245, v245
	v_exp_f32_e32 v246, v246
	v_exp_f32_e32 v247, v247
	v_exp_f32_e32 v248, v248
	v_exp_f32_e32 v249, v249
	v_pk_add_f32 v[242:243], v[242:243], 1.0 op_sel_hi:[1,0]
	v_pk_add_f32 v[244:245], v[244:245], 1.0 op_sel_hi:[1,0]
	v_pk_add_f32 v[246:247], v[246:247], 1.0 op_sel_hi:[1,0]
	v_pk_add_f32 v[248:249], v[248:249], 1.0 op_sel_hi:[1,0]
	v_pk_mul_f32 v[216:217], v[216:217], v[242:243]
	v_pk_mul_f32 v[218:219], v[218:219], v[244:245]
	v_pk_mul_f32 v[220:221], v[220:221], v[246:247]
	v_pk_mul_f32 v[222:223], v[222:223], v[248:249]
	v_pk_mul_f32 v[14:15], v[14:15], v[216:217]
	v_pk_mul_f32 v[16:17], v[16:17], v[218:219]
	v_pk_mul_f32 v[10:11], v[10:11], v[220:221]
	v_pk_mul_f32 v[12:13], v[12:13], v[222:223]
	s_waitcnt vmcnt(0)
	v_lshlrev_b32_e32 v216, 16, v178
	v_and_b32_e32 v217, 0xffff0000, v178
	v_lshlrev_b32_e32 v218, 16, v179
	v_and_b32_e32 v219, 0xffff0000, v179
	v_lshlrev_b32_e32 v220, 16, v180
	v_and_b32_e32 v221, 0xffff0000, v180
	v_lshlrev_b32_e32 v222, 16, v181
	v_and_b32_e32 v223, 0xffff0000, v181
	v_pk_mul_f32 v[216:217], v[216:217], s[86:87] op_sel_hi:[1,0]
	v_pk_mul_f32 v[218:219], v[218:219], s[86:87] op_sel_hi:[1,0]
	v_pk_mul_f32 v[220:221], v[220:221], s[86:87] op_sel_hi:[1,0]
	v_pk_mul_f32 v[222:223], v[222:223], s[86:87] op_sel_hi:[1,0]
	v_exp_f32_e32 v216, v216
	v_exp_f32_e32 v217, v217
	v_exp_f32_e32 v218, v218
	v_exp_f32_e32 v219, v219
	v_exp_f32_e32 v220, v220
	v_exp_f32_e32 v221, v221
	v_exp_f32_e32 v222, v222
	v_exp_f32_e32 v223, v223
	v_pk_add_f32 v[216:217], v[216:217], 1.0 op_sel_hi:[1,0]
	v_pk_add_f32 v[218:219], v[218:219], 1.0 op_sel_hi:[1,0]
	v_pk_add_f32 v[220:221], v[220:221], 1.0 op_sel_hi:[1,0]
	v_pk_add_f32 v[222:223], v[222:223], 1.0 op_sel_hi:[1,0]
	v_rcp_f32_e32 v216, v216
	v_rcp_f32_e32 v217, v217
	v_rcp_f32_e32 v218, v218
	v_rcp_f32_e32 v219, v219
	v_rcp_f32_e32 v220, v220
	v_rcp_f32_e32 v221, v221
	v_rcp_f32_e32 v222, v222
	v_rcp_f32_e32 v223, v223
	v_lshlrev_b32_e32 v242, 16, v182
	v_and_b32_e32 v243, 0xffff0000, v182
	v_lshlrev_b32_e32 v244, 16, v183
	v_and_b32_e32 v245, 0xffff0000, v183
	v_lshlrev_b32_e32 v246, 16, v184
	v_and_b32_e32 v247, 0xffff0000, v184
	v_lshlrev_b32_e32 v248, 16, v185
	v_and_b32_e32 v249, 0xffff0000, v185
	v_pk_mul_f32 v[242:243], v[242:243], s[86:87] op_sel_hi:[1,0]
	v_pk_mul_f32 v[244:245], v[244:245], s[86:87] op_sel_hi:[1,0]
	v_pk_mul_f32 v[246:247], v[246:247], s[86:87] op_sel_hi:[1,0]
	v_pk_mul_f32 v[248:249], v[248:249], s[86:87] op_sel_hi:[1,0]
	v_exp_f32_e32 v242, v242
	v_exp_f32_e32 v243, v243
	v_exp_f32_e32 v244, v244
	v_exp_f32_e32 v245, v245
	v_exp_f32_e32 v246, v246
	v_exp_f32_e32 v247, v247
	v_exp_f32_e32 v248, v248
	v_exp_f32_e32 v249, v249
	v_pk_add_f32 v[242:243], v[242:243], 1.0 op_sel_hi:[1,0]
	v_pk_add_f32 v[244:245], v[244:245], 1.0 op_sel_hi:[1,0]
	v_pk_add_f32 v[246:247], v[246:247], 1.0 op_sel_hi:[1,0]
	v_pk_add_f32 v[248:249], v[248:249], 1.0 op_sel_hi:[1,0]
	v_pk_mul_f32 v[216:217], v[216:217], v[242:243]
	v_pk_mul_f32 v[218:219], v[218:219], v[244:245]
	v_pk_mul_f32 v[220:221], v[220:221], v[246:247]
	v_pk_mul_f32 v[222:223], v[222:223], v[248:249]
	v_pk_mul_f32 v[38:39], v[38:39], v[216:217]
	v_pk_mul_f32 v[40:41], v[40:41], v[218:219]
	v_pk_mul_f32 v[34:35], v[34:35], v[220:221]
	v_pk_mul_f32 v[36:37], v[36:37], v[222:223]
	v_lshlrev_b32_e32 v216, 16, v186
	v_and_b32_e32 v217, 0xffff0000, v186
	v_lshlrev_b32_e32 v218, 16, v187
	v_and_b32_e32 v219, 0xffff0000, v187
	v_lshlrev_b32_e32 v220, 16, v188
	v_and_b32_e32 v221, 0xffff0000, v188
	v_lshlrev_b32_e32 v222, 16, v189
	v_and_b32_e32 v223, 0xffff0000, v189
	v_pk_mul_f32 v[216:217], v[216:217], s[86:87] op_sel_hi:[1,0]
	v_pk_mul_f32 v[218:219], v[218:219], s[86:87] op_sel_hi:[1,0]
	v_pk_mul_f32 v[220:221], v[220:221], s[86:87] op_sel_hi:[1,0]
	v_pk_mul_f32 v[222:223], v[222:223], s[86:87] op_sel_hi:[1,0]
	v_exp_f32_e32 v216, v216
	v_exp_f32_e32 v217, v217
	v_exp_f32_e32 v218, v218
	v_exp_f32_e32 v219, v219
	v_exp_f32_e32 v220, v220
	v_exp_f32_e32 v221, v221
	v_exp_f32_e32 v222, v222
	v_exp_f32_e32 v223, v223
	v_pk_add_f32 v[216:217], v[216:217], 1.0 op_sel_hi:[1,0]
	v_pk_add_f32 v[218:219], v[218:219], 1.0 op_sel_hi:[1,0]
	v_pk_add_f32 v[220:221], v[220:221], 1.0 op_sel_hi:[1,0]
	v_pk_add_f32 v[222:223], v[222:223], 1.0 op_sel_hi:[1,0]
	v_rcp_f32_e32 v216, v216
	v_rcp_f32_e32 v217, v217
	v_rcp_f32_e32 v218, v218
	v_rcp_f32_e32 v219, v219
	v_rcp_f32_e32 v220, v220
	v_rcp_f32_e32 v221, v221
	v_rcp_f32_e32 v222, v222
	v_rcp_f32_e32 v223, v223
	v_lshlrev_b32_e32 v242, 16, v190
	v_and_b32_e32 v243, 0xffff0000, v190
	v_lshlrev_b32_e32 v244, 16, v191
	v_and_b32_e32 v245, 0xffff0000, v191
	v_lshlrev_b32_e32 v246, 16, v192
	v_and_b32_e32 v247, 0xffff0000, v192
	v_lshlrev_b32_e32 v248, 16, v193
	v_and_b32_e32 v249, 0xffff0000, v193
	v_pk_mul_f32 v[242:243], v[242:243], s[86:87] op_sel_hi:[1,0]
	v_pk_mul_f32 v[244:245], v[244:245], s[86:87] op_sel_hi:[1,0]
	v_pk_mul_f32 v[246:247], v[246:247], s[86:87] op_sel_hi:[1,0]
	v_pk_mul_f32 v[248:249], v[248:249], s[86:87] op_sel_hi:[1,0]
	v_exp_f32_e32 v242, v242
	v_exp_f32_e32 v243, v243
	v_exp_f32_e32 v244, v244
	v_exp_f32_e32 v245, v245
	v_exp_f32_e32 v246, v246
	v_exp_f32_e32 v247, v247
	v_exp_f32_e32 v248, v248
	v_exp_f32_e32 v249, v249
	v_pk_add_f32 v[242:243], v[242:243], 1.0 op_sel_hi:[1,0]
	v_pk_add_f32 v[244:245], v[244:245], 1.0 op_sel_hi:[1,0]
	v_pk_add_f32 v[246:247], v[246:247], 1.0 op_sel_hi:[1,0]
	v_pk_add_f32 v[248:249], v[248:249], 1.0 op_sel_hi:[1,0]
	v_pk_mul_f32 v[216:217], v[216:217], v[242:243]
	v_pk_mul_f32 v[218:219], v[218:219], v[244:245]
	v_pk_mul_f32 v[220:221], v[220:221], v[246:247]
	v_pk_mul_f32 v[222:223], v[222:223], v[248:249]
	v_pk_mul_f32 v[6:7], v[6:7], v[216:217]
	v_pk_mul_f32 v[8:9], v[8:9], v[218:219]
	v_pk_mul_f32 v[2:3], v[2:3], v[220:221]
	v_pk_mul_f32 v[4:5], v[4:5], v[222:223]
	s_branch .Lem_done

.LBB0_504:
	v_add_u32_e32 v253, 0x10000, v163
	ds_read_b128 v[130:133], v253
	ds_read_b128 v[134:137], v253 offset:1024
	ds_read_b128 v[150:153], v253 offset:2048
	ds_read_b128 v[154:157], v253 offset:3072
	s_add_i32 m0, s42, 0xc000
	ds_read_b128 v[158:161], v162
	ds_read_b128 v[166:169], v162 offset:1024
	ds_read_b128 v[170:173], v162 offset:2048
	ds_read_b128 v[174:177], v162 offset:3072
	ds_read_b128 v[178:181], v162 offset:4096
	ds_read_b128 v[182:185], v162 offset:5120
	ds_read_b128 v[186:189], v162 offset:6144
	ds_read_b128 v[190:193], v162 offset:7168
	global_load_lds_dwordx4 v146, s[52:53]
	s_add_i32 m0, s42, 0xe000
	s_nop 0
	global_load_lds_dwordx4 v148, s[52:53]
	s_waitcnt lgkmcnt(8)
	s_setprio 1
	s_barrier
	s_waitcnt lgkmcnt(0)
	v_mfma_f32_16x16x32_bf16 v[126:129], v[130:133], v[158:161], v[126:129]
	v_mfma_f32_16x16x32_bf16 v[122:125], v[150:153], v[158:161], v[122:125]
	v_mfma_f32_16x16x32_bf16 v[118:121], v[130:133], v[170:173], v[118:121]
	v_mfma_f32_16x16x32_bf16 v[114:117], v[150:153], v[170:173], v[114:117]
	v_mfma_f32_16x16x32_bf16 v[110:113], v[130:133], v[178:181], v[110:113]
	v_mfma_f32_16x16x32_bf16 v[106:109], v[150:153], v[178:181], v[106:109]
	v_mfma_f32_16x16x32_bf16 v[102:105], v[130:133], v[186:189], v[102:105]
	v_mfma_f32_16x16x32_bf16 v[98:101], v[150:153], v[186:189], v[98:101]
	v_mfma_f32_16x16x32_bf16 v[126:129], v[134:137], v[166:169], v[126:129]
	v_mfma_f32_16x16x32_bf16 v[122:125], v[154:157], v[166:169], v[122:125]
	v_mfma_f32_16x16x32_bf16 v[118:121], v[134:137], v[174:177], v[118:121]
	v_mfma_f32_16x16x32_bf16 v[114:117], v[154:157], v[174:177], v[114:117]
	v_mfma_f32_16x16x32_bf16 v[110:113], v[134:137], v[182:185], v[110:113]
	v_mfma_f32_16x16x32_bf16 v[106:109], v[154:157], v[182:185], v[106:109]
	v_mfma_f32_16x16x32_bf16 v[102:105], v[134:137], v[190:193], v[102:105]
	v_mfma_f32_16x16x32_bf16 v[98:101], v[154:157], v[190:193], v[98:101]
	s_barrier
	s_setprio 0
	s_add_u32 s10, s52, 0xfff80080
	s_addc_u32 s11, s53, -1
	s_cmp_eq_u32 s29, 28
	s_cselect_b32 s11, s9, s11
	s_cselect_b32 s10, s8, s10
	s_cselect_b32 s55, s35, s7
	s_cselect_b32 s54, s34, s5
	s_mov_b32 m0, s41
	ds_read_b128 v[206:209], v253 offset:16384
	ds_read_b128 v[210:213], v253 offset:17408
	v_lshl_add_u64 v[222:223], s[54:55], 0, v[194:195]
	ds_read_b128 v[214:217], v253 offset:18432
	ds_read_b128 v[218:221], v253 offset:19456
	global_load_lds_dwordx4 v[222:223], off
	v_lshl_add_u64 v[224:225], s[54:55], 0, v[138:139]
	s_mov_b32 m0, s57
	s_nop 0
	global_load_lds_dwordx4 v[224:225], off
	s_setprio 1
	s_barrier
	s_waitcnt lgkmcnt(0)
	v_mfma_f32_16x16x32_bf16 v[62:65], v[206:209], v[158:161], v[62:65]
	v_mfma_f32_16x16x32_bf16 v[58:61], v[214:217], v[158:161], v[58:61]
	v_mfma_f32_16x16x32_bf16 v[54:57], v[206:209], v[170:173], v[54:57]
	v_mfma_f32_16x16x32_bf16 v[46:49], v[214:217], v[170:173], v[46:49]
	v_mfma_f32_16x16x32_bf16 v[50:53], v[206:209], v[178:181], v[50:53]
	v_mfma_f32_16x16x32_bf16 v[42:45], v[214:217], v[178:181], v[42:45]
	v_mfma_f32_16x16x32_bf16 v[38:41], v[206:209], v[186:189], v[38:41]
	v_mfma_f32_16x16x32_bf16 v[34:37], v[214:217], v[186:189], v[34:37]
	v_mfma_f32_16x16x32_bf16 v[62:65], v[210:213], v[166:169], v[62:65]
	v_mfma_f32_16x16x32_bf16 v[58:61], v[218:221], v[166:169], v[58:61]
	v_mfma_f32_16x16x32_bf16 v[54:57], v[210:213], v[174:177], v[54:57]
	v_mfma_f32_16x16x32_bf16 v[46:49], v[218:221], v[174:177], v[46:49]
	v_mfma_f32_16x16x32_bf16 v[50:53], v[210:213], v[182:185], v[50:53]
	v_mfma_f32_16x16x32_bf16 v[42:45], v[218:221], v[182:185], v[42:45]
	s_mov_b32 m0, s42
	v_mfma_f32_16x16x32_bf16 v[38:41], v[210:213], v[190:193], v[38:41]
	v_lshl_add_u64 v[226:227], s[10:11], 0, v[142:143]
	v_mfma_f32_16x16x32_bf16 v[34:37], v[218:221], v[190:193], v[34:37]
	s_barrier
	s_setprio 0
	ds_read_b128 v[158:161], v162 offset:16384
	ds_read_b128 v[166:169], v162 offset:17408
	ds_read_b128 v[170:173], v162 offset:18432
	ds_read_b128 v[174:177], v162 offset:19456
	ds_read_b128 v[178:181], v162 offset:20480
	ds_read_b128 v[182:185], v162 offset:21504
	ds_read_b128 v[186:189], v162 offset:22528
	ds_read_b128 v[190:193], v162 offset:23552
	global_load_lds_dwordx4 v[226:227], off
	v_lshl_add_u64 v[228:229], s[10:11], 0, v[140:141]
	s_mov_b32 m0, s58
	s_nop 0
	global_load_lds_dwordx4 v[228:229], off
	s_setprio 1
	s_barrier
	s_waitcnt lgkmcnt(0)
	v_mfma_f32_16x16x32_bf16 v[94:97], v[130:133], v[158:161], v[94:97]
	v_mfma_f32_16x16x32_bf16 v[90:93], v[150:153], v[158:161], v[90:93]
	v_mfma_f32_16x16x32_bf16 v[86:89], v[130:133], v[170:173], v[86:89]
	v_mfma_f32_16x16x32_bf16 v[82:85], v[150:153], v[170:173], v[82:85]
	v_mfma_f32_16x16x32_bf16 v[78:81], v[130:133], v[178:181], v[78:81]
	v_mfma_f32_16x16x32_bf16 v[74:77], v[150:153], v[178:181], v[74:77]
	v_mfma_f32_16x16x32_bf16 v[70:73], v[130:133], v[186:189], v[70:73]
	v_mfma_f32_16x16x32_bf16 v[66:69], v[150:153], v[186:189], v[66:69]
	v_mfma_f32_16x16x32_bf16 v[94:97], v[134:137], v[166:169], v[94:97]
	v_mfma_f32_16x16x32_bf16 v[90:93], v[154:157], v[166:169], v[90:93]
	v_mfma_f32_16x16x32_bf16 v[86:89], v[134:137], v[174:177], v[86:89]
	v_mfma_f32_16x16x32_bf16 v[82:85], v[154:157], v[174:177], v[82:85]
	v_mfma_f32_16x16x32_bf16 v[78:81], v[134:137], v[182:185], v[78:81]
	v_mfma_f32_16x16x32_bf16 v[74:77], v[154:157], v[182:185], v[74:77]
	v_mfma_f32_16x16x32_bf16 v[70:73], v[134:137], v[190:193], v[70:73]
	v_mfma_f32_16x16x32_bf16 v[66:69], v[154:157], v[190:193], v[66:69]
	s_barrier
	s_setprio 0
	s_add_u32 s86, s54, 0x80000
	s_addc_u32 s87, s55, 0
	s_mov_b32 m0, s59
	s_nop 0
	global_load_lds_dwordx4 v194, s[86:87]
	s_mov_b32 m0, s60
	s_nop 0
	global_load_lds_dwordx4 v138, s[86:87]
	s_waitcnt vmcnt(6)
	s_setprio 1
	s_barrier
	v_mfma_f32_16x16x32_bf16 v[30:33], v[206:209], v[158:161], v[30:33]
	v_mfma_f32_16x16x32_bf16 v[18:21], v[214:217], v[158:161], v[18:21]
	v_mfma_f32_16x16x32_bf16 v[26:29], v[206:209], v[170:173], v[26:29]
	v_mfma_f32_16x16x32_bf16 v[14:17], v[214:217], v[170:173], v[14:17]
	v_mfma_f32_16x16x32_bf16 v[22:25], v[206:209], v[178:181], v[22:25]
	v_mfma_f32_16x16x32_bf16 v[6:9], v[214:217], v[178:181], v[6:9]
	v_mfma_f32_16x16x32_bf16 v[10:13], v[206:209], v[186:189], v[10:13]
	v_mfma_f32_16x16x32_bf16 v[2:5], v[214:217], v[186:189], v[2:5]
	v_mfma_f32_16x16x32_bf16 v[30:33], v[210:213], v[166:169], v[30:33]
	v_mfma_f32_16x16x32_bf16 v[18:21], v[218:221], v[166:169], v[18:21]
	v_mfma_f32_16x16x32_bf16 v[26:29], v[210:213], v[174:177], v[26:29]
	v_mfma_f32_16x16x32_bf16 v[14:17], v[218:221], v[174:177], v[14:17]
	v_mfma_f32_16x16x32_bf16 v[22:25], v[210:213], v[182:185], v[22:25]
	v_mfma_f32_16x16x32_bf16 v[6:9], v[218:221], v[182:185], v[6:9]
	v_mfma_f32_16x16x32_bf16 v[10:13], v[210:213], v[190:193], v[10:13]
	v_mfma_f32_16x16x32_bf16 v[2:5], v[218:221], v[190:193], v[2:5]
	s_barrier
	s_setprio 0
	ds_read_b128 v[130:133], v253 offset:32768
	ds_read_b128 v[134:137], v253 offset:33792
	ds_read_b128 v[150:153], v253 offset:34816
	ds_read_b128 v[154:157], v253 offset:35840
	s_add_u32 s10, s10, 0x80000
	s_addc_u32 s11, s11, 0
	s_mov_b32 m0, s61
	ds_read_b128 v[158:161], v162 offset:32768
	ds_read_b128 v[166:169], v162 offset:33792
	ds_read_b128 v[170:173], v162 offset:34816
	ds_read_b128 v[174:177], v162 offset:35840
	ds_read_b128 v[178:181], v162 offset:36864
	ds_read_b128 v[182:185], v162 offset:37888
	ds_read_b128 v[186:189], v162 offset:38912
	ds_read_b128 v[190:193], v162 offset:39936
	global_load_lds_dwordx4 v142, s[10:11]
	s_mov_b32 m0, s62
	s_nop 0
	global_load_lds_dwordx4 v140, s[10:11]
	s_waitcnt lgkmcnt(8)
	s_setprio 1
	s_barrier
	s_waitcnt lgkmcnt(0)
	v_mfma_f32_16x16x32_bf16 v[126:129], v[130:133], v[158:161], v[126:129]
	v_mfma_f32_16x16x32_bf16 v[122:125], v[150:153], v[158:161], v[122:125]
	v_mfma_f32_16x16x32_bf16 v[118:121], v[130:133], v[170:173], v[118:121]
	v_mfma_f32_16x16x32_bf16 v[114:117], v[150:153], v[170:173], v[114:117]
	v_mfma_f32_16x16x32_bf16 v[110:113], v[130:133], v[178:181], v[110:113]
	v_mfma_f32_16x16x32_bf16 v[106:109], v[150:153], v[178:181], v[106:109]
	v_mfma_f32_16x16x32_bf16 v[102:105], v[130:133], v[186:189], v[102:105]
	v_mfma_f32_16x16x32_bf16 v[98:101], v[150:153], v[186:189], v[98:101]
	v_mfma_f32_16x16x32_bf16 v[126:129], v[134:137], v[166:169], v[126:129]
	v_mfma_f32_16x16x32_bf16 v[122:125], v[154:157], v[166:169], v[122:125]
	v_mfma_f32_16x16x32_bf16 v[118:121], v[134:137], v[174:177], v[118:121]
	v_mfma_f32_16x16x32_bf16 v[114:117], v[154:157], v[174:177], v[114:117]
	v_mfma_f32_16x16x32_bf16 v[110:113], v[134:137], v[182:185], v[110:113]
	v_mfma_f32_16x16x32_bf16 v[106:109], v[154:157], v[182:185], v[106:109]
	v_mfma_f32_16x16x32_bf16 v[102:105], v[134:137], v[190:193], v[102:105]
	v_mfma_f32_16x16x32_bf16 v[98:101], v[154:157], v[190:193], v[98:101]
	s_barrier
	s_setprio 0
	s_mov_b32 m0, s70
	ds_read_b128 v[206:209], v253 offset:49152
	ds_read_b128 v[210:213], v253 offset:50176
	v_lshl_add_u64 v[222:223], v[222:223], 0, s[76:77]
	ds_read_b128 v[214:217], v253 offset:51200
	ds_read_b128 v[218:221], v253 offset:52224
	global_load_lds_dwordx4 v[222:223], off
	v_lshl_add_u64 v[222:223], v[224:225], 0, s[76:77]
	s_mov_b32 m0, s71
	s_nop 0
	global_load_lds_dwordx4 v[222:223], off
	s_setprio 1
	s_barrier
	s_waitcnt lgkmcnt(0)
	v_mfma_f32_16x16x32_bf16 v[62:65], v[206:209], v[158:161], v[62:65]
	v_mfma_f32_16x16x32_bf16 v[58:61], v[214:217], v[158:161], v[58:61]
	v_mfma_f32_16x16x32_bf16 v[54:57], v[206:209], v[170:173], v[54:57]
	v_mfma_f32_16x16x32_bf16 v[46:49], v[214:217], v[170:173], v[46:49]
	v_mfma_f32_16x16x32_bf16 v[50:53], v[206:209], v[178:181], v[50:53]
	v_mfma_f32_16x16x32_bf16 v[42:45], v[214:217], v[178:181], v[42:45]
	v_mfma_f32_16x16x32_bf16 v[38:41], v[206:209], v[186:189], v[38:41]
	v_mfma_f32_16x16x32_bf16 v[34:37], v[214:217], v[186:189], v[34:37]
	v_mfma_f32_16x16x32_bf16 v[62:65], v[210:213], v[166:169], v[62:65]
	v_mfma_f32_16x16x32_bf16 v[58:61], v[218:221], v[166:169], v[58:61]
	v_mfma_f32_16x16x32_bf16 v[54:57], v[210:213], v[174:177], v[54:57]
	v_mfma_f32_16x16x32_bf16 v[46:49], v[218:221], v[174:177], v[46:49]
	v_mfma_f32_16x16x32_bf16 v[50:53], v[210:213], v[182:185], v[50:53]
	v_mfma_f32_16x16x32_bf16 v[42:45], v[218:221], v[182:185], v[42:45]
	s_mov_b32 m0, s78
	v_mfma_f32_16x16x32_bf16 v[38:41], v[210:213], v[190:193], v[38:41]
	v_lshl_add_u64 v[222:223], v[226:227], 0, s[76:77]
	v_mfma_f32_16x16x32_bf16 v[34:37], v[218:221], v[190:193], v[34:37]
	s_barrier
	s_setprio 0
	ds_read_b128 v[158:161], v162 offset:49152
	ds_read_b128 v[166:169], v162 offset:50176
	ds_read_b128 v[170:173], v162 offset:51200
	ds_read_b128 v[174:177], v162 offset:52224
	ds_read_b128 v[178:181], v162 offset:53248
	ds_read_b128 v[182:185], v162 offset:54272
	ds_read_b128 v[186:189], v162 offset:55296
	ds_read_b128 v[190:193], v162 offset:56320
	global_load_lds_dwordx4 v[222:223], off
	v_lshl_add_u64 v[222:223], v[228:229], 0, s[76:77]
	s_mov_b32 m0, s79
	s_nop 0
	global_load_lds_dwordx4 v[222:223], off
	s_setprio 1
	s_barrier
	s_waitcnt lgkmcnt(0)
	v_mfma_f32_16x16x32_bf16 v[94:97], v[130:133], v[158:161], v[94:97]
	v_mfma_f32_16x16x32_bf16 v[90:93], v[150:153], v[158:161], v[90:93]
	v_mfma_f32_16x16x32_bf16 v[86:89], v[130:133], v[170:173], v[86:89]
	v_mfma_f32_16x16x32_bf16 v[82:85], v[150:153], v[170:173], v[82:85]
	v_mfma_f32_16x16x32_bf16 v[78:81], v[130:133], v[178:181], v[78:81]
	v_mfma_f32_16x16x32_bf16 v[74:77], v[150:153], v[178:181], v[74:77]
	v_mfma_f32_16x16x32_bf16 v[70:73], v[130:133], v[186:189], v[70:73]
	v_mfma_f32_16x16x32_bf16 v[66:69], v[150:153], v[186:189], v[66:69]
	v_mfma_f32_16x16x32_bf16 v[94:97], v[134:137], v[166:169], v[94:97]
	v_mfma_f32_16x16x32_bf16 v[90:93], v[154:157], v[166:169], v[90:93]
	v_mfma_f32_16x16x32_bf16 v[86:89], v[134:137], v[174:177], v[86:89]
	v_mfma_f32_16x16x32_bf16 v[82:85], v[154:157], v[174:177], v[82:85]
	v_mfma_f32_16x16x32_bf16 v[78:81], v[134:137], v[182:185], v[78:81]
	v_mfma_f32_16x16x32_bf16 v[74:77], v[154:157], v[182:185], v[74:77]
	v_mfma_f32_16x16x32_bf16 v[70:73], v[134:137], v[190:193], v[70:73]
	v_mfma_f32_16x16x32_bf16 v[66:69], v[154:157], v[190:193], v[66:69]
	s_barrier
	s_setprio 0
	s_add_u32 s10, s54, 0x80080
	s_addc_u32 s11, s55, 0
	s_mov_b32 m0, s80
	s_nop 0
	global_load_lds_dwordx4 v194, s[10:11]
	s_mov_b32 m0, s81
	s_nop 0
	global_load_lds_dwordx4 v138, s[10:11]
	s_waitcnt vmcnt(6)
	s_setprio 1
	s_barrier
	v_mfma_f32_16x16x32_bf16 v[30:33], v[206:209], v[158:161], v[30:33]
	v_mfma_f32_16x16x32_bf16 v[18:21], v[214:217], v[158:161], v[18:21]
	v_mfma_f32_16x16x32_bf16 v[26:29], v[206:209], v[170:173], v[26:29]
	v_mfma_f32_16x16x32_bf16 v[14:17], v[214:217], v[170:173], v[14:17]
	v_mfma_f32_16x16x32_bf16 v[22:25], v[206:209], v[178:181], v[22:25]
	v_mfma_f32_16x16x32_bf16 v[6:9], v[214:217], v[178:181], v[6:9]
	v_mfma_f32_16x16x32_bf16 v[10:13], v[206:209], v[186:189], v[10:13]
	v_mfma_f32_16x16x32_bf16 v[2:5], v[214:217], v[186:189], v[2:5]
	v_mfma_f32_16x16x32_bf16 v[30:33], v[210:213], v[166:169], v[30:33]
	v_mfma_f32_16x16x32_bf16 v[18:21], v[218:221], v[166:169], v[18:21]
	v_mfma_f32_16x16x32_bf16 v[26:29], v[210:213], v[174:177], v[26:29]
	v_mfma_f32_16x16x32_bf16 v[14:17], v[218:221], v[174:177], v[14:17]
	v_mfma_f32_16x16x32_bf16 v[22:25], v[210:213], v[182:185], v[22:25]
	v_mfma_f32_16x16x32_bf16 v[6:9], v[218:221], v[182:185], v[6:9]
	v_mfma_f32_16x16x32_bf16 v[10:13], v[210:213], v[190:193], v[10:13]
	v_mfma_f32_16x16x32_bf16 v[2:5], v[218:221], v[190:193], v[2:5]
	s_setprio 0
	s_add_i32 s29, s29, 2
	s_add_u32 s52, s52, 0x100
	s_addc_u32 s53, s53, 0
	s_add_u32 s5, s5, 0x100
	s_addc_u32 s7, s7, 0
	s_cmp_gt_u32 s29, 29
	s_barrier
	s_cbranch_scc0 .LBB0_504
	v_readlane_b32 s10, v250, 21
	s_cmp_gt_i32 s40, 63
	v_readlane_b32 s11, v250, 22
	s_mov_b64 s[20:21], s[48:49]
	s_cselect_b32 s11, s21, s11
	s_cselect_b32 s10, s20, s10
	v_readlane_b32 s20, v252, 0
	v_readlane_b32 s26, v252, 6
	v_readlane_b32 s27, v252, 7
	s_cselect_b32 s53, s3, s27
	s_cselect_b32 s52, s2, s26
	s_sub_i32 s5, s40, 64
	s_cmp_gt_i32 s40, 63
	s_cselect_b32 s54, s5, s40
	s_lshr_b32 s5, s40, 3
	s_cmp_gt_i32 s40, 63
	s_mulk_i32 s5, 0x1800
	v_lshl_or_b32 v130, s28, 8, v164
	s_cselect_b32 s28, 0xc000, s5
	s_ashr_i32 s29, s28, 31
	s_lshl_b64 s[28:29], s[28:29], 2
	s_add_u32 s28, s63, s28
	v_ashrrev_i32_e32 v131, 31, v130
	s_addc_u32 s29, s67, s29
	v_lshlrev_b64 v[130:131], 2, v[130:131]
	v_lshl_add_u64 v[132:133], s[28:29], 0, v[130:131]
	s_mov_b64 s[28:29], 0x6484000
	s_ashr_i32 s55, s54, 31
	v_lshl_add_u64 v[154:155], v[132:133], 0, s[28:29]
	s_lshl_b64 s[28:29], s[54:55], 19
	v_lshl_add_u64 v[134:135], s[28:29], 0, v[144:145]
	v_lshlrev_b64 v[134:135], 2, v[134:135]
	v_lshl_add_u64 v[136:137], s[10:11], 0, v[134:135]
	v_lshl_add_u64 v[134:135], s[52:53], 0, v[134:135]
	s_mov_b32 s5, 0x6484000
	v_lshl_add_u64 v[150:151], v[136:137], 0, v[130:131]
	v_lshl_add_u64 v[152:153], v[134:135], 0, v[130:131]
	v_add_co_u32_e32 v130, vcc, s5, v132
	s_mov_b64 s[10:11], 0x20000
	s_nop 0
	v_addc_co_u32_e32 v131, vcc, 0, v133, vcc
	v_add_co_u32_e32 v156, vcc, s13, v150
	global_load_dwordx4 v[134:137], v[130:131], off
	s_nop 0
	global_load_dwordx4 v[130:133], v[154:155], off offset:16
	global_load_dwordx4 v[166:169], v[150:151], off offset:16
	global_load_dwordx4 v[170:173], v[150:151], off
	v_lshl_add_u64 v[158:159], v[150:151], 0, s[10:11]
	v_addc_co_u32_e32 v157, vcc, 0, v151, vcc
	s_mov_b32 s5, 0x40000
	global_load_dwordx4 v[174:177], v[156:157], off
	global_load_dwordx4 v[178:181], v[158:159], off offset:16
	s_mov_b64 s[10:11], 0x40000
	v_add_co_u32_e32 v158, vcc, s5, v150
	v_lshl_add_u64 v[160:161], v[150:151], 0, s[10:11]
	s_nop 0
	v_addc_co_u32_e32 v159, vcc, 0, v151, vcc
	s_mov_b32 s7, 0x60000
	global_load_dwordx4 v[182:185], v[158:159], off
	global_load_dwordx4 v[186:189], v[160:161], off offset:16
	s_mov_b64 s[10:11], 0x60000
	v_add_co_u32_e32 v160, vcc, s7, v150
	v_lshl_add_u64 v[206:207], v[150:151], 0, s[10:11]
	s_nop 0
	v_addc_co_u32_e32 v161, vcc, 0, v151, vcc
	global_load_dwordx4 v[190:193], v[160:161], off
	s_nop 0
	global_load_dwordx4 v[206:209], v[206:207], off offset:16
	v_readlane_b32 s21, v252, 1
	v_readlane_b32 s22, v252, 2
	v_readlane_b32 s23, v252, 3
	v_readlane_b32 s24, v252, 4
	v_readlane_b32 s25, v252, 5
	s_waitcnt vmcnt(0)
	v_pk_fma_f32 v[124:125], v[124:125], v[132:133], v[168:169]
	v_pk_fma_f32 v[122:123], v[122:123], v[130:131], v[166:167]
	global_store_dwordx4 v[152:153], v[122:125], off offset:16
	v_pk_fma_f32 v[128:129], v[128:129], v[136:137], v[172:173]
	v_pk_fma_f32 v[126:127], v[126:127], v[134:135], v[170:171]
	v_pk_fma_f32 v[122:123], v[120:121], v[136:137], v[176:177]
	v_pk_fma_f32 v[120:121], v[118:119], v[134:135], v[174:175]
	v_add_co_u32_e32 v118, vcc, s13, v152
	v_pk_fma_f32 v[116:117], v[116:117], v[132:133], v[180:181]
	s_nop 0
	v_addc_co_u32_e32 v119, vcc, 0, v153, vcc
	v_pk_fma_f32 v[114:115], v[114:115], v[130:131], v[178:179]
	global_store_dwordx4 v[118:119], v[114:117], off offset:16
	v_pk_fma_f32 v[108:109], v[108:109], v[132:133], v[188:189]
	v_pk_fma_f32 v[106:107], v[106:107], v[130:131], v[186:187]
	v_pk_fma_f32 v[114:115], v[112:113], v[136:137], v[184:185]
	v_pk_fma_f32 v[112:113], v[110:111], v[134:135], v[182:183]
	v_add_co_u32_e32 v110, vcc, s5, v152
	global_store_dwordx4 v[152:153], v[126:129], off
	s_nop 0
	v_addc_co_u32_e32 v111, vcc, 0, v153, vcc
	global_store_dwordx4 v[110:111], v[106:109], off offset:16
	v_pk_fma_f32 v[100:101], v[100:101], v[132:133], v[208:209]
	v_pk_fma_f32 v[98:99], v[98:99], v[130:131], v[206:207]
	v_pk_fma_f32 v[106:107], v[104:105], v[136:137], v[192:193]
	v_pk_fma_f32 v[104:105], v[102:103], v[134:135], v[190:191]
	v_add_co_u32_e32 v102, vcc, s7, v152
	global_store_dwordx4 v[118:119], v[120:123], off
	s_nop 0
	v_addc_co_u32_e32 v103, vcc, 0, v153, vcc
	global_store_dwordx4 v[110:111], v[112:115], off
	global_store_dwordx4 v[102:103], v[104:107], off
	global_store_dwordx4 v[102:103], v[98:101], off offset:16
	s_mov_b32 s5, 0x100000
	s_mov_b64 s[10:11], 0x100000
	v_add_co_u32_e32 v98, vcc, s5, v150
	v_lshl_add_u64 v[100:101], v[150:151], 0, s[10:11]
	s_nop 0
	v_addc_co_u32_e32 v99, vcc, 0, v151, vcc
	global_load_dwordx4 v[112:115], v[98:99], off
	global_load_dwordx4 v[120:123], v[100:101], off offset:16
	s_mov_b64 s[10:11], 0x120000
	v_add_co_u32_e32 v100, vcc, s45, v150
	v_lshl_add_u64 v[104:105], v[150:151], 0, s[10:11]
	s_nop 0
	v_addc_co_u32_e32 v101, vcc, 0, v151, vcc
	s_mov_b64 s[10:11], 0x140000
	s_mov_b32 s7, 0x140000
	global_load_dwordx4 v[124:127], v[100:101], off
	global_load_dwordx4 v[166:169], v[104:105], off offset:16
	v_lshl_add_u64 v[106:107], v[150:151], 0, s[10:11]
	v_add_co_u32_e32 v104, vcc, s7, v150
	s_mov_b64 s[10:11], 0x160000
	s_nop 0
	v_addc_co_u32_e32 v105, vcc, 0, v151, vcc
	v_lshl_add_u64 v[108:109], v[150:151], 0, s[10:11]
	s_mov_b32 s10, 0x160000
	global_load_dwordx4 v[170:173], v[104:105], off
	global_load_dwordx4 v[174:177], v[106:107], off offset:16
	v_add_co_u32_e32 v106, vcc, s10, v150
	s_waitcnt vmcnt(0)
	v_pk_fma_f32 v[112:113], v[94:95], v[134:135], v[112:113]
	v_addc_co_u32_e32 v107, vcc, 0, v151, vcc
	global_load_dwordx4 v[178:181], v[106:107], off
	global_load_dwordx4 v[182:185], v[108:109], off offset:16
	v_add_co_u32_e32 v94, vcc, s5, v152
	v_pk_fma_f32 v[92:93], v[92:93], v[132:133], v[122:123]
	s_nop 0
	v_addc_co_u32_e32 v95, vcc, 0, v153, vcc
	v_pk_fma_f32 v[90:91], v[90:91], v[130:131], v[120:121]
	global_store_dwordx4 v[94:95], v[90:93], off offset:16
	v_pk_fma_f32 v[84:85], v[84:85], v[132:133], v[168:169]
	v_pk_fma_f32 v[82:83], v[82:83], v[130:131], v[166:167]
	v_pk_fma_f32 v[90:91], v[88:89], v[136:137], v[126:127]
	v_pk_fma_f32 v[88:89], v[86:87], v[134:135], v[124:125]
	v_add_co_u32_e32 v86, vcc, s45, v152
	v_pk_fma_f32 v[114:115], v[96:97], v[136:137], v[114:115]
	s_nop 0
	v_addc_co_u32_e32 v87, vcc, 0, v153, vcc
	global_store_dwordx4 v[86:87], v[82:85], off offset:16
	v_pk_fma_f32 v[76:77], v[76:77], v[132:133], v[176:177]
	v_pk_fma_f32 v[74:75], v[74:75], v[130:131], v[174:175]
	v_pk_fma_f32 v[82:83], v[80:81], v[136:137], v[172:173]
	v_pk_fma_f32 v[80:81], v[78:79], v[134:135], v[170:171]
	v_add_co_u32_e32 v78, vcc, s7, v152
	global_store_dwordx4 v[94:95], v[112:115], off
	s_nop 0
	v_addc_co_u32_e32 v79, vcc, 0, v153, vcc
	global_store_dwordx4 v[78:79], v[74:77], off offset:16
	global_store_dwordx4 v[86:87], v[88:91], off
	global_store_dwordx4 v[78:79], v[80:83], off
	v_add_co_u32_e32 v74, vcc, s10, v152
	s_waitcnt vmcnt(0)
	v_pk_fma_f32 v[72:73], v[72:73], v[136:137], v[180:181]
	v_pk_fma_f32 v[70:71], v[70:71], v[134:135], v[178:179]
	v_addc_co_u32_e32 v75, vcc, 0, v153, vcc
	v_pk_fma_f32 v[68:69], v[68:69], v[132:133], v[184:185]
	v_pk_fma_f32 v[66:67], v[66:67], v[130:131], v[182:183]
	global_store_dwordx4 v[74:75], v[70:73], off
	global_store_dwordx4 v[74:75], v[66:69], off offset:16
	s_mov_b64 s[10:11], 0x20200
	v_lshl_add_u64 v[76:77], v[150:151], 0, s[10:11]
	s_mov_b64 s[10:11], 0x40200
	global_load_dwordx4 v[80:83], v[150:151], off offset:512
	global_load_dwordx4 v[70:73], v[154:155], off offset:512
	global_load_dwordx4 v[66:69], v[154:155], off offset:528
	global_load_dwordx4 v[88:91], v[150:151], off offset:528
	global_load_dwordx4 v[112:115], v[156:157], off offset:512
	global_load_dwordx4 v[120:123], v[158:159], off offset:512
	global_load_dwordx4 v[124:127], v[76:77], off offset:16
	v_lshl_add_u64 v[76:77], v[150:151], 0, s[10:11]
	s_mov_b64 s[10:11], 0x60200
	global_load_dwordx4 v[128:131], v[76:77], off offset:16
	global_load_dwordx4 v[132:135], v[160:161], off offset:512
	v_lshl_add_u64 v[76:77], v[150:151], 0, s[10:11]
	global_load_dwordx4 v[154:157], v[76:77], off offset:16
	s_waitcnt vmcnt(0)
	v_pk_fma_f32 v[64:65], v[64:65], v[72:73], v[82:83]
	v_pk_fma_f32 v[62:63], v[62:63], v[70:71], v[80:81]
	v_pk_fma_f32 v[60:61], v[60:61], v[68:69], v[90:91]
	v_pk_fma_f32 v[58:59], v[58:59], v[66:67], v[88:89]
	v_pk_fma_f32 v[52:53], v[52:53], v[72:73], v[122:123]
	v_pk_fma_f32 v[50:51], v[50:51], v[70:71], v[120:121]
	v_pk_fma_f32 v[48:49], v[48:49], v[68:69], v[126:127]
	v_pk_fma_f32 v[46:47], v[46:47], v[66:67], v[124:125]
	v_pk_fma_f32 v[56:57], v[56:57], v[72:73], v[114:115]
	v_pk_fma_f32 v[54:55], v[54:55], v[70:71], v[112:113]
	global_store_dwordx4 v[152:153], v[62:65], off offset:512
	global_store_dwordx4 v[152:153], v[58:61], off offset:528
	global_store_dwordx4 v[118:119], v[54:57], off offset:512
	global_store_dwordx4 v[110:111], v[50:53], off offset:512
	v_pk_fma_f32 v[44:45], v[44:45], v[68:69], v[130:131]
	v_pk_fma_f32 v[42:43], v[42:43], v[66:67], v[128:129]
	v_pk_fma_f32 v[40:41], v[40:41], v[72:73], v[134:135]
	v_pk_fma_f32 v[38:39], v[38:39], v[70:71], v[132:133]
	v_pk_fma_f32 v[36:37], v[36:37], v[68:69], v[156:157]
	v_pk_fma_f32 v[34:35], v[34:35], v[66:67], v[154:155]
	global_store_dwordx4 v[118:119], v[46:49], off offset:528
	global_store_dwordx4 v[110:111], v[42:45], off offset:528
	global_store_dwordx4 v[102:103], v[38:41], off offset:512
	global_store_dwordx4 v[102:103], v[34:37], off offset:528
	s_mov_b64 s[10:11], 0x100200
	v_lshl_add_u64 v[50:51], v[150:151], 0, s[10:11]
	s_mov_b64 s[10:11], 0x120200
	v_lshl_add_u64 v[54:55], v[150:151], 0, s[10:11]
	s_mov_b64 s[10:11], 0x140200
	v_lshl_add_u64 v[58:59], v[150:151], 0, s[10:11]
	s_mov_b64 s[10:11], 0x160200
	global_load_dwordx4 v[34:37], v[98:99], off offset:512
	global_load_dwordx4 v[38:41], v[100:101], off offset:512
	global_load_dwordx4 v[42:45], v[104:105], off offset:512
	global_load_dwordx4 v[46:49], v[106:107], off offset:512
	v_lshl_add_u64 v[62:63], v[150:151], 0, s[10:11]
	global_load_dwordx4 v[50:53], v[50:51], off offset:16
	s_waitcnt vmcnt(0)
	v_pk_fma_f32 v[32:33], v[32:33], v[72:73], v[36:37]
	global_load_dwordx4 v[54:57], v[54:55], off offset:16
	v_pk_fma_f32 v[30:31], v[30:31], v[70:71], v[34:35]
	global_load_dwordx4 v[58:61], v[58:59], off offset:16
	v_pk_fma_f32 v[28:29], v[28:29], v[72:73], v[40:41]
	global_load_dwordx4 v[62:65], v[62:63], off offset:16
	v_pk_fma_f32 v[26:27], v[26:27], v[70:71], v[38:39]
	v_pk_fma_f32 v[24:25], v[24:25], v[72:73], v[44:45]
	v_pk_fma_f32 v[22:23], v[22:23], v[70:71], v[42:43]
	v_pk_fma_f32 v[12:13], v[12:13], v[72:73], v[48:49]
	v_pk_fma_f32 v[10:11], v[10:11], v[70:71], v[46:47]
	v_pk_fma_f32 v[20:21], v[20:21], v[68:69], v[52:53]
	v_pk_fma_f32 v[18:19], v[18:19], v[66:67], v[50:51]
	global_store_dwordx4 v[94:95], v[30:33], off offset:512
	global_store_dwordx4 v[86:87], v[26:29], off offset:512
	global_store_dwordx4 v[78:79], v[22:25], off offset:512
	global_store_dwordx4 v[74:75], v[10:13], off offset:512
	s_waitcnt vmcnt(0)
	v_pk_fma_f32 v[16:17], v[16:17], v[68:69], v[56:57]
	v_pk_fma_f32 v[14:15], v[14:15], v[66:67], v[54:55]
	v_pk_fma_f32 v[8:9], v[8:9], v[68:69], v[60:61]
	v_pk_fma_f32 v[6:7], v[6:7], v[66:67], v[58:59]
	v_pk_fma_f32 v[4:5], v[4:5], v[68:69], v[64:65]
	v_pk_fma_f32 v[2:3], v[2:3], v[66:67], v[62:63]
	global_store_dwordx4 v[94:95], v[18:21], off offset:528
	global_store_dwordx4 v[86:87], v[14:17], off offset:528
	global_store_dwordx4 v[78:79], v[6:9], off offset:528
	global_store_dwordx4 v[74:75], v[2:5], off offset:528
	s_and_b64 vcc, exec, s[0:1]
	s_mov_b32 s40, s6
	s_mov_b32 s28, s4
	s_mov_b64 s[54:55], s[34:35]
	s_mov_b64 s[52:53], s[8:9]
	s_cbranch_vccz .LBB0_501
	s_waitcnt vmcnt(0)
	v_readlane_b32 s28, v250, 12
	v_readlane_b32 s26, v250, 15
	s_cmpk_gt_u32 s12, 0xff
	v_readlane_b32 s29, v250, 13
	v_readlane_b32 s27, v250, 16
	s_mov_b32 s70, 0x800000
	v_readlane_b32 s79, v250, 18
	s_cbranch_scc1 .LBB0_508
	s_barrier
